# GEMM K-loops: third LDS slot for A half-tile 0 (static LDS +16KB) balances LDS-DMA 4/4 per super-phase; pre-MMA barrier moved after 4 MFMAs
# speedup vs baseline: 1.0055x; 1.0055x over previous
;     __device__ bool next(int i, pg8::Unit& u) const { const int t = (i >> 2) * G + c; if (t >= ntile) return false; const int br = i & 3; u.pm = br * 65 + (t >> 3); u.pn = br * 8 + (t & 7); return true; }
; template <class Epi, class Sched, bool ALIGN_EPI = false, bool SP2 = false>
; __device__ __forceinline__ void gemm_phase(PG8_LAS unsigned char* lds, const Gemm g, const Sched& S, const Epi& E) {
;     ...
;     Unit cur, nxt; int ui = 0;
;     if (!S.next(0, cur)) return;
;     f32x4 acc[2][2][4][2];
; #pragma unroll
;     for (int a = 0; a < 2; ++a)
; #pragma unroll
;         for (int b = 0; b < 2; ++b)
; #pragma unroll
;             for (int m = 0; m < 4; ++m)
; #pragma unroll
;                 for (int n = 0; n < 2; ++n) { float zr_ = 0.f; asm volatile("" : "+v"(zr_)); acc[a][b][m][n] = (f32x4){zr_, zr_, zr_, zr_}; }
;     bf16x8 At[4][2], B0[2][2], B1[2][2];
;     const char* cA = (const char*)g.A + (size_t)cur.pm * tstep; const char* cB = (const char*)g.Bt + (size_t)cur.pn * tstep;
;     S.a_ready(cur);
.LBB0_157:
	s_andn2_b64 vcc, exec, s[4:5]
	s_cbranch_vccnz .LBB0_262
	s_mov_b32 s100, 0
	s_mov_b32 s101, 0x8000
	v_readlane_b32 s8, v253, 51
	v_readlane_b32 s9, v253, 52
	v_mov_b32_e32 v0, v197
	v_readlane_b32 s0, v252, 60
	v_readlane_b32 s1, v252, 61
	v_mov_b32_e32 v145, v197
	s_andn2_b64 vcc, exec, s[0:1]
	v_cndmask_b32_e64 v0, 0, 1, s[0:1]
	v_cmp_ne_u32_e64 s[4:5], 1, v0
	v_readfirstlane_b32 s14, v145
	s_cbranch_vccnz .LBB0_161
	v_readlane_b32 s0, v253, 47
	s_mov_b32 s6, s0
	v_readlane_b32 s0, v253, 31
	s_mov_b32 s24, s0
	s_and_b64 vcc, exec, s[4:5]
	s_cbranch_vccz .LBB0_162

; #define PG8_STAGE(bufoff, gbase, voff) do { _Pragma("unroll") for (int _i = 0; _i < 2; ++_i) \
;         __builtin_amdgcn_global_load_lds((const unsigned*)((const char*)(gbase) + (voff)[_i]), (PG8_LAS unsigned*)(lds + (bufoff) + ldsw + _i * 8192), 16, 0, 0); } while (0)
; #define PG8_LDA(dst, b, h) do { _Pragma("unroll") for (int m = 0; m < 4; ++m) _Pragma("unroll") for (int k = 0; k < 2; ++k) dst[m][k] = *(const PG8_LAS bf16x8*)(lds + PG8_SA(b, h) + aoff + m * 2048 + k * 1024); } while (0)
; #define PG8_LDB(dst, b, h) do { _Pragma("unroll") for (int n = 0; n < 2; ++n) _Pragma("unroll") for (int k = 0; k < 2; ++k) dst[n][k] = *(const PG8_LAS bf16x8*)(lds + PG8_SB(b, h) + boff + n * 2048 + k * 1024); } while (0)
; #define PG8_MMA(ai, bj, At, Bt) do { __builtin_amdgcn_s_setprio(1); _Pragma("unroll") for (int m = 0; m < 4; ++m) _Pragma("unroll") for (int n = 0; n < 2; ++n) _Pragma("unroll") for (int k = 0; k < 2; ++k) \
;         acc[ai][bj][m][n] = __builtin_amdgcn_mfma_f32_16x16x32_bf16(Bt[n][k], At[m][k], acc[ai][bj][m][n], 0, 0, 0); __builtin_amdgcn_s_setprio(0); } while (0)
; #define PG8_WAIT_V(n) asm volatile("s_waitcnt vmcnt(" #n ")" ::: "memory")
; #define PG8_BAR __builtin_amdgcn_s_barrier()
; template <class Epi, class Sched, bool ALIGN_EPI = false, bool SP2 = false>
; __device__ __forceinline__ void gemm_phase(PG8_LAS unsigned char* lds, const Gemm g, const Sched& S, const Epi& E) {
;     ...
;         for (int t = 0; t < nt; t += 2) {
;             const bool last = (t == nt - 2);
;             const char* a1 = cA + (size_t)(t + 1) * kstep;
;             const char* a2 = last ? nA : cA + (size_t)(t + 2) * kstep; const char* b2 = last ? nB : cB + (size_t)(t + 2) * kstep;
;             const char* a3 = a2 + kstep; const char* b3 = b2 + kstep;
;             if (last && has_next) S.a_ready(nxt);
;             if constexpr (SP2) {
;             PG8_LDB(B0, 0, 0); PG8_LDB(B1, 0, 1); PG8_SCHED; PG8_LDA(At, 0, 0); PG8_STAGE(PG8_SA(1, 1), a1 + hstep, voffA);
;             PG8_WAIT_V(8); PG8_WAIT_L(0); PG8_BAR; PG8_MMA(0, 0, At, B0); PG8_MMA(0, 1, At, B1); PG8_BAR; PG8_SCHED;
;             PG8_LDA(At, 0, 1); PG8_STAGE(PG8_SB(0, 0), b2, voffB); PG8_STAGE(PG8_SB(0, 1), b2 + hstep, voffB); PG8_STAGE(PG8_SA(0, 0), a2, voffA);
;             PG8_WAIT_V(8); PG8_WAIT_L(0); PG8_BAR; PG8_MMA(1, 0, At, B0); PG8_MMA(1, 1, At, B1); PG8_BAR; PG8_SCHED;
.LBB0_170:
	s_sub_i32 vcc_hi, 0x29000, s100
	s_sub_i32 vcc_hi, vcc_hi, s101
	s_add_u32 s26, s38, 0xfff80080
	s_addc_u32 s27, s39, -1
	s_add_i32 s50, 0, 0x10000
	s_cmp_eq_u32 s49, 28
	s_cselect_b32 s41, s7, s27
	s_cselect_b32 s40, s19, s26
	s_cselect_b32 s27, s17, s48
	s_cselect_b32 s26, s46, s47
	s_add_i32 s52, 0, 0x14000
	v_add_u32_e32 v156, s50, v145
	v_add_u32_e32 v172, s52, v145
	ds_read_b128 v[140:143], v156
	ds_read_b128 v[148:151], v156 offset:1024
	ds_read_b128 v[152:155], v156 offset:2048
	ds_read_b128 v[156:159], v156 offset:3072
	ds_read_b128 v[160:163], v172
	ds_read_b128 v[164:167], v172 offset:1024
	ds_read_b128 v[168:171], v172 offset:2048
	ds_read_b128 v[172:175], v172 offset:3072
	v_lshl_add_u64 v[214:215], s[38:39], 0, v[136:137]
	s_add_i32 m0, s25, 0xc000
	v_add_u32_e32 v250, s100, v147
	ds_read_b128 v[176:179], v250
	ds_read_b128 v[180:183], v250 offset:1024
	ds_read_b128 v[184:187], v250 offset:2048
	ds_read_b128 v[188:191], v250 offset:3072
	ds_read_b128 v[192:195], v250 offset:4096
	ds_read_b128 v[202:205], v250 offset:5120
	ds_read_b128 v[206:209], v250 offset:6144
	ds_read_b128 v[210:213], v250 offset:7168
	global_load_lds_dwordx4 v[214:215], off
	v_lshl_add_u64 v[214:215], s[38:39], 0, v[138:139]
	s_add_i32 m0, s25, 0xe000
	s_nop 0
	global_load_lds_dwordx4 v[214:215], off
	v_lshl_add_u64 v[238:239], s[40:41], 0, v[130:131]
	v_lshl_add_u64 v[240:241], s[40:41], 0, v[132:133]
	s_add_i32 m0, vcc_hi, s25
	s_nop 0
	global_load_lds_dwordx4 v[238:239], off
	s_add_i32 m0, m0, 0x2000
	s_nop 0
	global_load_lds_dwordx4 v[240:241], off
	s_waitcnt vmcnt(10)
	s_waitcnt lgkmcnt(0)
	s_setprio 1
	s_waitcnt lgkmcnt(0)
	v_mfma_f32_16x16x32_bf16 v[122:125], v[140:143], v[176:179], v[122:125]
	v_mfma_f32_16x16x32_bf16 v[126:129], v[152:155], v[176:179], v[126:129]
	v_mfma_f32_16x16x32_bf16 v[106:109], v[140:143], v[184:187], v[106:109]
	v_mfma_f32_16x16x32_bf16 v[110:113], v[152:155], v[184:187], v[110:113]
	s_barrier
	v_mfma_f32_16x16x32_bf16 v[90:93], v[140:143], v[192:195], v[90:93]
	v_mfma_f32_16x16x32_bf16 v[94:97], v[152:155], v[192:195], v[94:97]
	v_mfma_f32_16x16x32_bf16 v[74:77], v[140:143], v[206:209], v[74:77]
	v_mfma_f32_16x16x32_bf16 v[78:81], v[152:155], v[206:209], v[78:81]
	v_mfma_f32_16x16x32_bf16 v[122:125], v[148:151], v[180:183], v[122:125]
	v_mfma_f32_16x16x32_bf16 v[126:129], v[156:159], v[180:183], v[126:129]
	v_mfma_f32_16x16x32_bf16 v[106:109], v[148:151], v[188:191], v[106:109]
	v_mfma_f32_16x16x32_bf16 v[110:113], v[156:159], v[188:191], v[110:113]
	v_mfma_f32_16x16x32_bf16 v[90:93], v[148:151], v[202:205], v[90:93]
	v_mfma_f32_16x16x32_bf16 v[94:97], v[156:159], v[202:205], v[94:97]
	v_mfma_f32_16x16x32_bf16 v[74:77], v[148:151], v[210:213], v[74:77]
	v_mfma_f32_16x16x32_bf16 v[78:81], v[156:159], v[210:213], v[78:81]
	s_setprio 0
	s_setprio 1
	v_mfma_f32_16x16x32_bf16 v[114:117], v[160:163], v[176:179], v[114:117]
	v_mfma_f32_16x16x32_bf16 v[118:121], v[168:171], v[176:179], v[118:121]
	v_mfma_f32_16x16x32_bf16 v[98:101], v[160:163], v[184:187], v[98:101]
	v_mfma_f32_16x16x32_bf16 v[102:105], v[168:171], v[184:187], v[102:105]
	v_mfma_f32_16x16x32_bf16 v[82:85], v[160:163], v[192:195], v[82:85]
	v_mfma_f32_16x16x32_bf16 v[86:89], v[168:171], v[192:195], v[86:89]
	v_mfma_f32_16x16x32_bf16 v[66:69], v[160:163], v[206:209], v[66:69]
	v_mfma_f32_16x16x32_bf16 v[70:73], v[168:171], v[206:209], v[70:73]
	v_mfma_f32_16x16x32_bf16 v[114:117], v[164:167], v[180:183], v[114:117]
	v_mfma_f32_16x16x32_bf16 v[118:121], v[172:175], v[180:183], v[118:121]
	v_mfma_f32_16x16x32_bf16 v[98:101], v[164:167], v[188:191], v[98:101]
	v_mfma_f32_16x16x32_bf16 v[102:105], v[172:175], v[188:191], v[102:105]
	v_mfma_f32_16x16x32_bf16 v[82:85], v[164:167], v[202:205], v[82:85]
	v_mfma_f32_16x16x32_bf16 v[86:89], v[172:175], v[202:205], v[86:89]
	v_mfma_f32_16x16x32_bf16 v[66:69], v[164:167], v[210:213], v[66:69]
	v_mfma_f32_16x16x32_bf16 v[70:73], v[172:175], v[210:213], v[70:73]
	s_setprio 0
	s_barrier
	s_add_i32 s50, s50, s29
	v_lshl_add_u64 v[214:215], s[26:27], 0, v[0:1]
	s_mov_b32 m0, s50
	ds_read_b128 v[176:179], v147 offset:16384
	ds_read_b128 v[180:183], v147 offset:17408
	ds_read_b128 v[184:187], v147 offset:18432
	ds_read_b128 v[188:191], v147 offset:19456
	ds_read_b128 v[192:195], v147 offset:20480
	ds_read_b128 v[202:205], v147 offset:21504
	ds_read_b128 v[206:209], v147 offset:22528
	ds_read_b128 v[210:213], v147 offset:23552
	global_load_lds_dwordx4 v[214:215], off
	s_add_i32 m0, s50, 0x2000
	s_add_u32 s50, s26, 0x80000
	v_lshl_add_u64 v[216:217], s[26:27], 0, v[134:135]
	s_addc_u32 s51, s27, 0
	s_add_i32 s52, s52, s29
	global_load_lds_dwordx4 v[216:217], off
	v_lshl_add_u64 v[218:219], s[50:51], 0, v[0:1]
	s_mov_b32 m0, s52
	global_load_lds_dwordx4 v[218:219], off
	v_lshl_add_u64 v[218:219], s[50:51], 0, v[134:135]
	s_add_i32 m0, s52, 0x2000
	s_nop 0
	global_load_lds_dwordx4 v[218:219], off
	s_waitcnt vmcnt(8)
	s_waitcnt lgkmcnt(0)
	s_setprio 1
	s_waitcnt lgkmcnt(0)
	v_mfma_f32_16x16x32_bf16 v[58:61], v[140:143], v[176:179], v[58:61]
	v_mfma_f32_16x16x32_bf16 v[62:65], v[152:155], v[176:179], v[62:65]
	v_mfma_f32_16x16x32_bf16 v[42:45], v[140:143], v[184:187], v[42:45]
	v_mfma_f32_16x16x32_bf16 v[46:49], v[152:155], v[184:187], v[46:49]
	s_barrier
; #define PG8_STAGE(bufoff, gbase, voff) do { _Pragma("unroll") for (int _i = 0; _i < 2; ++_i) \
;         __builtin_amdgcn_global_load_lds((const unsigned*)((const char*)(gbase) + (voff)[_i]), (PG8_LAS unsigned*)(lds + (bufoff) + ldsw + _i * 8192), 16, 0, 0); } while (0)
; #define PG8_LDA(dst, b, h) do { _Pragma("unroll") for (int m = 0; m < 4; ++m) _Pragma("unroll") for (int k = 0; k < 2; ++k) dst[m][k] = *(const PG8_LAS bf16x8*)(lds + PG8_SA(b, h) + aoff + m * 2048 + k * 1024); } while (0)
; #define PG8_LDB(dst, b, h) do { _Pragma("unroll") for (int n = 0; n < 2; ++n) _Pragma("unroll") for (int k = 0; k < 2; ++k) dst[n][k] = *(const PG8_LAS bf16x8*)(lds + PG8_SB(b, h) + boff + n * 2048 + k * 1024); } while (0)
; #define PG8_MMA(ai, bj, At, Bt) do { __builtin_amdgcn_s_setprio(1); _Pragma("unroll") for (int m = 0; m < 4; ++m) _Pragma("unroll") for (int n = 0; n < 2; ++n) _Pragma("unroll") for (int k = 0; k < 2; ++k) \
;         acc[ai][bj][m][n] = __builtin_amdgcn_mfma_f32_16x16x32_bf16(Bt[n][k], At[m][k], acc[ai][bj][m][n], 0, 0, 0); __builtin_amdgcn_s_setprio(0); } while (0)
; #define PG8_WAIT_V(n) asm volatile("s_waitcnt vmcnt(" #n ")" ::: "memory")
; #define PG8_WAIT_L(n) asm volatile("s_waitcnt lgkmcnt(" #n ")" ::: "memory")
; #define PG8_BAR __builtin_amdgcn_s_barrier()
; #define PG8_SCHED __builtin_amdgcn_sched_barrier(0)
; template <class Epi, class Sched, bool ALIGN_EPI = false, bool SP2 = false>
; __device__ __forceinline__ void gemm_phase(PG8_LAS unsigned char* lds, const Gemm g, const Sched& S, const Epi& E) {
;     ...
;             PG8_WAIT_V(8); PG8_WAIT_L(0); PG8_BAR; PG8_MMA(0, 0, At, B0); PG8_MMA(0, 1, At, B1); PG8_BAR; PG8_SCHED;
;             PG8_LDA(At, 0, 1); PG8_STAGE(PG8_SB(0, 0), b2, voffB); PG8_STAGE(PG8_SB(0, 1), b2 + hstep, voffB); PG8_STAGE(PG8_SA(0, 0), a2, voffA);
;             PG8_WAIT_V(8); PG8_WAIT_L(0); PG8_BAR; PG8_MMA(1, 0, At, B0); PG8_MMA(1, 1, At, B1); PG8_BAR; PG8_SCHED;
;             PG8_LDB(B0, 1, 0); PG8_LDB(B1, 1, 1); PG8_SCHED; PG8_LDA(At, 1, 0); PG8_STAGE(PG8_SA(0, 1), a2 + hstep, voffA);
;             PG8_WAIT_V(8); PG8_WAIT_L(0); PG8_BAR; PG8_MMA(0, 0, At, B0); PG8_MMA(0, 1, At, B1); PG8_BAR; PG8_SCHED;
	v_mfma_f32_16x16x32_bf16 v[26:29], v[140:143], v[192:195], v[26:29]
	v_mfma_f32_16x16x32_bf16 v[30:33], v[152:155], v[192:195], v[30:33]
	v_mfma_f32_16x16x32_bf16 v[10:13], v[140:143], v[206:209], v[10:13]
	v_mfma_f32_16x16x32_bf16 v[14:17], v[152:155], v[206:209], v[14:17]
	v_mfma_f32_16x16x32_bf16 v[58:61], v[148:151], v[180:183], v[58:61]
	v_mfma_f32_16x16x32_bf16 v[62:65], v[156:159], v[180:183], v[62:65]
	v_mfma_f32_16x16x32_bf16 v[42:45], v[148:151], v[188:191], v[42:45]
	v_mfma_f32_16x16x32_bf16 v[46:49], v[156:159], v[188:191], v[46:49]
	v_mfma_f32_16x16x32_bf16 v[26:29], v[148:151], v[202:205], v[26:29]
	v_mfma_f32_16x16x32_bf16 v[30:33], v[156:159], v[202:205], v[30:33]
	v_mfma_f32_16x16x32_bf16 v[10:13], v[148:151], v[210:213], v[10:13]
	v_mfma_f32_16x16x32_bf16 v[14:17], v[156:159], v[210:213], v[14:17]
	s_setprio 0
	s_setprio 1
	v_mfma_f32_16x16x32_bf16 v[50:53], v[160:163], v[176:179], v[50:53]
	v_mfma_f32_16x16x32_bf16 v[54:57], v[168:171], v[176:179], v[54:57]
	v_mfma_f32_16x16x32_bf16 v[34:37], v[160:163], v[184:187], v[34:37]
	v_mfma_f32_16x16x32_bf16 v[38:41], v[168:171], v[184:187], v[38:41]
	v_mfma_f32_16x16x32_bf16 v[18:21], v[160:163], v[192:195], v[18:21]
	v_mfma_f32_16x16x32_bf16 v[22:25], v[168:171], v[192:195], v[22:25]
	v_mfma_f32_16x16x32_bf16 v[2:5], v[160:163], v[206:209], v[2:5]
	v_mfma_f32_16x16x32_bf16 v[6:9], v[168:171], v[206:209], v[6:9]
	v_mfma_f32_16x16x32_bf16 v[50:53], v[164:167], v[180:183], v[50:53]
	v_mfma_f32_16x16x32_bf16 v[54:57], v[172:175], v[180:183], v[54:57]
	v_mfma_f32_16x16x32_bf16 v[34:37], v[164:167], v[188:191], v[34:37]
	v_mfma_f32_16x16x32_bf16 v[38:41], v[172:175], v[188:191], v[38:41]
	v_mfma_f32_16x16x32_bf16 v[18:21], v[164:167], v[202:205], v[18:21]
	v_mfma_f32_16x16x32_bf16 v[22:25], v[172:175], v[202:205], v[22:25]
	v_mfma_f32_16x16x32_bf16 v[2:5], v[164:167], v[210:213], v[2:5]
	v_mfma_f32_16x16x32_bf16 v[6:9], v[172:175], v[210:213], v[6:9]
	s_setprio 0
	s_barrier
	s_add_i32 s50, 0, 0x18000
	s_add_i32 s51, 0, 0x1c000
	v_add_u32_e32 v156, s50, v145
	v_add_u32_e32 v172, s51, v145
	ds_read_b128 v[140:143], v156
	ds_read_b128 v[148:151], v156 offset:1024
	ds_read_b128 v[152:155], v156 offset:2048
	ds_read_b128 v[156:159], v156 offset:3072
	ds_read_b128 v[160:163], v172
	ds_read_b128 v[164:167], v172 offset:1024
	ds_read_b128 v[168:171], v172 offset:2048
	ds_read_b128 v[172:175], v172 offset:3072
	s_add_u32 s40, s40, 0x80000
	s_addc_u32 s41, s41, 0
	s_mov_b32 m0, s31
	v_lshl_add_u64 v[230:231], s[40:41], 0, v[130:131]
	v_add_u32_e32 v250, s101, v147
	ds_read_b128 v[176:179], v250
	ds_read_b128 v[180:183], v250 offset:1024
	ds_read_b128 v[184:187], v250 offset:2048
	ds_read_b128 v[188:191], v250 offset:3072
	ds_read_b128 v[192:195], v250 offset:4096
	ds_read_b128 v[202:205], v250 offset:5120
	ds_read_b128 v[206:209], v250 offset:6144
	ds_read_b128 v[210:213], v250 offset:7168
	global_load_lds_dwordx4 v[230:231], off
	v_lshl_add_u64 v[230:231], s[40:41], 0, v[132:133]
	s_mov_b32 m0, s42
	s_nop 0
	global_load_lds_dwordx4 v[230:231], off
	v_lshl_add_u64 v[242:243], v[238:239], 0, s[54:55]
	v_lshl_add_u64 v[244:245], v[240:241], 0, s[54:55]
	s_add_i32 m0, s100, s25
	s_nop 0
	global_load_lds_dwordx4 v[242:243], off
	s_add_i32 m0, m0, 0x2000
	s_nop 0
	global_load_lds_dwordx4 v[244:245], off
	s_waitcnt vmcnt(10)
	s_waitcnt lgkmcnt(0)
	s_setprio 1
	s_waitcnt lgkmcnt(0)
	v_mfma_f32_16x16x32_bf16 v[122:125], v[140:143], v[176:179], v[122:125]
	v_mfma_f32_16x16x32_bf16 v[126:129], v[152:155], v[176:179], v[126:129]
	v_mfma_f32_16x16x32_bf16 v[106:109], v[140:143], v[184:187], v[106:109]
	v_mfma_f32_16x16x32_bf16 v[110:113], v[152:155], v[184:187], v[110:113]
	s_barrier
; #define PG8_STAGE(bufoff, gbase, voff) do { _Pragma("unroll") for (int _i = 0; _i < 2; ++_i) \
;         __builtin_amdgcn_global_load_lds((const unsigned*)((const char*)(gbase) + (voff)[_i]), (PG8_LAS unsigned*)(lds + (bufoff) + ldsw + _i * 8192), 16, 0, 0); } while (0)
; #define PG8_LDA(dst, b, h) do { _Pragma("unroll") for (int m = 0; m < 4; ++m) _Pragma("unroll") for (int k = 0; k < 2; ++k) dst[m][k] = *(const PG8_LAS bf16x8*)(lds + PG8_SA(b, h) + aoff + m * 2048 + k * 1024); } while (0)
; #define PG8_LDB(dst, b, h) do { _Pragma("unroll") for (int n = 0; n < 2; ++n) _Pragma("unroll") for (int k = 0; k < 2; ++k) dst[n][k] = *(const PG8_LAS bf16x8*)(lds + PG8_SB(b, h) + boff + n * 2048 + k * 1024); } while (0)
; #define PG8_MMA(ai, bj, At, Bt) do { __builtin_amdgcn_s_setprio(1); _Pragma("unroll") for (int m = 0; m < 4; ++m) _Pragma("unroll") for (int n = 0; n < 2; ++n) _Pragma("unroll") for (int k = 0; k < 2; ++k) \
;         acc[ai][bj][m][n] = __builtin_amdgcn_mfma_f32_16x16x32_bf16(Bt[n][k], At[m][k], acc[ai][bj][m][n], 0, 0, 0); __builtin_amdgcn_s_setprio(0); } while (0)
; #define PG8_WAIT_V(n) asm volatile("s_waitcnt vmcnt(" #n ")" ::: "memory")
; #define PG8_WAIT_L(n) asm volatile("s_waitcnt lgkmcnt(" #n ")" ::: "memory")
; template <class Epi, class Sched, bool ALIGN_EPI = false, bool SP2 = false>
; __device__ __forceinline__ void gemm_phase(PG8_LAS unsigned char* lds, const Gemm g, const Sched& S, const Epi& E) {
;     ...
;         for (int t = 0; t < nt; t += 2) {
;             const bool last = (t == nt - 2);
;             const char* a1 = cA + (size_t)(t + 1) * kstep;
;             const char* a2 = last ? nA : cA + (size_t)(t + 2) * kstep; const char* b2 = last ? nB : cB + (size_t)(t + 2) * kstep;
;             const char* a3 = a2 + kstep; const char* b3 = b2 + kstep;
;             if (last && has_next) S.a_ready(nxt);
;     ...
;             PG8_LDB(B0, 1, 0); PG8_LDB(B1, 1, 1); PG8_SCHED; PG8_LDA(At, 1, 0); PG8_STAGE(PG8_SA(0, 1), a2 + hstep, voffA);
;             PG8_WAIT_V(8); PG8_WAIT_L(0); PG8_BAR; PG8_MMA(0, 0, At, B0); PG8_MMA(0, 1, At, B1); PG8_BAR; PG8_SCHED;
;             PG8_LDA(At, 1, 1); PG8_STAGE(PG8_SB(1, 0), b3, voffB); PG8_STAGE(PG8_SB(1, 1), b3 + hstep, voffB); PG8_STAGE(PG8_SA(1, 0), a3, voffA);
;             PG8_WAIT_V(8); PG8_WAIT_L(0); PG8_BAR; PG8_MMA(1, 0, At, B0); PG8_MMA(1, 1, At, B1); PG8_BAR; PG8_SCHED;
	v_mfma_f32_16x16x32_bf16 v[90:93], v[140:143], v[192:195], v[90:93]
	v_mfma_f32_16x16x32_bf16 v[94:97], v[152:155], v[192:195], v[94:97]
	v_mfma_f32_16x16x32_bf16 v[74:77], v[140:143], v[206:209], v[74:77]
	v_mfma_f32_16x16x32_bf16 v[78:81], v[152:155], v[206:209], v[78:81]
	v_mfma_f32_16x16x32_bf16 v[122:125], v[148:151], v[180:183], v[122:125]
	v_mfma_f32_16x16x32_bf16 v[126:129], v[156:159], v[180:183], v[126:129]
	v_mfma_f32_16x16x32_bf16 v[106:109], v[148:151], v[188:191], v[106:109]
	v_mfma_f32_16x16x32_bf16 v[110:113], v[156:159], v[188:191], v[110:113]
	v_mfma_f32_16x16x32_bf16 v[90:93], v[148:151], v[202:205], v[90:93]
	v_mfma_f32_16x16x32_bf16 v[94:97], v[156:159], v[202:205], v[94:97]
	v_mfma_f32_16x16x32_bf16 v[74:77], v[148:151], v[210:213], v[74:77]
	v_mfma_f32_16x16x32_bf16 v[78:81], v[156:159], v[210:213], v[78:81]
	s_setprio 0
	s_setprio 1
	v_mfma_f32_16x16x32_bf16 v[114:117], v[160:163], v[176:179], v[114:117]
	v_mfma_f32_16x16x32_bf16 v[118:121], v[168:171], v[176:179], v[118:121]
	v_mfma_f32_16x16x32_bf16 v[98:101], v[160:163], v[184:187], v[98:101]
	v_mfma_f32_16x16x32_bf16 v[102:105], v[168:171], v[184:187], v[102:105]
	v_mfma_f32_16x16x32_bf16 v[82:85], v[160:163], v[192:195], v[82:85]
	v_mfma_f32_16x16x32_bf16 v[86:89], v[168:171], v[192:195], v[86:89]
	v_mfma_f32_16x16x32_bf16 v[66:69], v[160:163], v[206:209], v[66:69]
	v_mfma_f32_16x16x32_bf16 v[70:73], v[168:171], v[206:209], v[70:73]
	v_mfma_f32_16x16x32_bf16 v[114:117], v[164:167], v[180:183], v[114:117]
	v_mfma_f32_16x16x32_bf16 v[118:121], v[172:175], v[180:183], v[118:121]
	v_mfma_f32_16x16x32_bf16 v[98:101], v[164:167], v[188:191], v[98:101]
	v_mfma_f32_16x16x32_bf16 v[102:105], v[172:175], v[188:191], v[102:105]
	v_mfma_f32_16x16x32_bf16 v[82:85], v[164:167], v[202:205], v[82:85]
	v_mfma_f32_16x16x32_bf16 v[86:89], v[172:175], v[202:205], v[86:89]
	v_mfma_f32_16x16x32_bf16 v[66:69], v[164:167], v[210:213], v[66:69]
	v_mfma_f32_16x16x32_bf16 v[70:73], v[172:175], v[210:213], v[70:73]
	s_setprio 0
	s_barrier
	s_add_i32 s40, s50, s29
	v_lshl_add_u64 v[214:215], v[214:215], 0, s[54:55]
	s_mov_b32 m0, s40
	ds_read_b128 v[176:179], v147 offset:49152
	ds_read_b128 v[180:183], v147 offset:50176
	ds_read_b128 v[184:187], v147 offset:51200
	ds_read_b128 v[188:191], v147 offset:52224
	ds_read_b128 v[192:195], v147 offset:53248
	ds_read_b128 v[202:205], v147 offset:54272
	ds_read_b128 v[206:209], v147 offset:55296
	ds_read_b128 v[210:213], v147 offset:56320
	global_load_lds_dwordx4 v[214:215], off
	s_add_i32 m0, s40, 0x2000
	s_add_u32 s26, s26, 0x80080
	v_lshl_add_u64 v[214:215], v[216:217], 0, s[54:55]
	s_addc_u32 s27, s27, 0
	s_add_i32 s40, s51, s29
	global_load_lds_dwordx4 v[214:215], off
	v_lshl_add_u64 v[214:215], s[26:27], 0, v[0:1]
	s_mov_b32 m0, s40
	s_nop 0
	global_load_lds_dwordx4 v[214:215], off
	v_lshl_add_u64 v[214:215], s[26:27], 0, v[134:135]
	s_add_i32 m0, s40, 0x2000
	s_nop 0
	global_load_lds_dwordx4 v[214:215], off
	s_waitcnt vmcnt(8)
	s_waitcnt lgkmcnt(0)
	s_setprio 1
	s_waitcnt lgkmcnt(0)
	v_mfma_f32_16x16x32_bf16 v[58:61], v[140:143], v[176:179], v[58:61]
	v_mfma_f32_16x16x32_bf16 v[62:65], v[152:155], v[176:179], v[62:65]
	v_mfma_f32_16x16x32_bf16 v[42:45], v[140:143], v[184:187], v[42:45]
	v_mfma_f32_16x16x32_bf16 v[46:49], v[152:155], v[184:187], v[46:49]
	s_barrier
	v_mfma_f32_16x16x32_bf16 v[26:29], v[140:143], v[192:195], v[26:29]
	v_mfma_f32_16x16x32_bf16 v[30:33], v[152:155], v[192:195], v[30:33]
	v_mfma_f32_16x16x32_bf16 v[10:13], v[140:143], v[206:209], v[10:13]
	v_mfma_f32_16x16x32_bf16 v[14:17], v[152:155], v[206:209], v[14:17]
	v_mfma_f32_16x16x32_bf16 v[58:61], v[148:151], v[180:183], v[58:61]
	v_mfma_f32_16x16x32_bf16 v[62:65], v[156:159], v[180:183], v[62:65]
	v_mfma_f32_16x16x32_bf16 v[42:45], v[148:151], v[188:191], v[42:45]
	v_mfma_f32_16x16x32_bf16 v[46:49], v[156:159], v[188:191], v[46:49]
	v_mfma_f32_16x16x32_bf16 v[26:29], v[148:151], v[202:205], v[26:29]
	v_mfma_f32_16x16x32_bf16 v[30:33], v[156:159], v[202:205], v[30:33]
	v_mfma_f32_16x16x32_bf16 v[10:13], v[148:151], v[210:213], v[10:13]
	v_mfma_f32_16x16x32_bf16 v[14:17], v[156:159], v[210:213], v[14:17]
	s_setprio 0
	s_setprio 1
	v_mfma_f32_16x16x32_bf16 v[50:53], v[160:163], v[176:179], v[50:53]
	v_mfma_f32_16x16x32_bf16 v[54:57], v[168:171], v[176:179], v[54:57]
	v_mfma_f32_16x16x32_bf16 v[34:37], v[160:163], v[184:187], v[34:37]
	v_mfma_f32_16x16x32_bf16 v[38:41], v[168:171], v[184:187], v[38:41]
	v_mfma_f32_16x16x32_bf16 v[18:21], v[160:163], v[192:195], v[18:21]
	v_mfma_f32_16x16x32_bf16 v[22:25], v[168:171], v[192:195], v[22:25]
	v_mfma_f32_16x16x32_bf16 v[2:5], v[160:163], v[206:209], v[2:5]
	v_mfma_f32_16x16x32_bf16 v[6:9], v[168:171], v[206:209], v[6:9]
	v_mfma_f32_16x16x32_bf16 v[50:53], v[164:167], v[180:183], v[50:53]
	v_mfma_f32_16x16x32_bf16 v[54:57], v[172:175], v[180:183], v[54:57]
	v_mfma_f32_16x16x32_bf16 v[34:37], v[164:167], v[188:191], v[34:37]
	v_mfma_f32_16x16x32_bf16 v[38:41], v[172:175], v[188:191], v[38:41]
	v_mfma_f32_16x16x32_bf16 v[18:21], v[164:167], v[202:205], v[18:21]
	v_mfma_f32_16x16x32_bf16 v[22:25], v[172:175], v[202:205], v[22:25]
	v_mfma_f32_16x16x32_bf16 v[2:5], v[164:167], v[210:213], v[2:5]
	v_mfma_f32_16x16x32_bf16 v[6:9], v[172:175], v[210:213], v[6:9]
	s_setprio 0
	s_barrier
	s_add_i32 s49, s49, 2
	s_mov_b32 s101, s100
	s_mov_b32 s100, vcc_hi
	s_add_u32 s38, s38, 0x100
	s_addc_u32 s39, s39, 0
	s_add_u32 s47, s47, 0x100
	s_addc_u32 s48, s48, 0
	s_cmp_gt_u32 s49, 29
	s_cbranch_scc0 .LBB0_170
	s_and_b64 vcc, exec, s[14:15]
	s_cbranch_vccz .LBB0_173
	s_barrier

; __device__ __forceinline__ int ltid() { int t = threadIdx.x; asm volatile("" : "+v"(t)); return t; }
; #define PG8_STAGE(bufoff, gbase, voff) do { _Pragma("unroll") for (int _i = 0; _i < 2; ++_i) \
;         __builtin_amdgcn_global_load_lds((const unsigned*)((const char*)(gbase) + (voff)[_i]), (PG8_LAS unsigned*)(lds + (bufoff) + ldsw + _i * 8192), 16, 0, 0); } while (0)
; template <class Epi, class Sched, bool ALIGN_EPI = false, bool SP2 = false>
; __device__ __forceinline__ void gemm_phase(PG8_LAS unsigned char* lds, const Gemm g, const Sched& S, const Epi& E) {
;     const int tid = ltid(), wid = __builtin_amdgcn_readfirstlane(tid >> 6), lane = tid & 63, wr = wid >> 2, wc = wid & 3, fr = lane & 15, fq = lane >> 4;
;     const int K = g.K, nt = K / BK;
;     unsigned voffA[2], voffB[2];
; #pragma unroll
;     for (int i = 0; i < 2; ++i) { int R, C; stage_rc(tid * 16 + i * 8192, R, C); const int Rb = Epi::PERM ? ((R & ~31) + perm32(R & 31)) : R;
;         voffA[i] = (unsigned)(R * K + C) * 2u; voffB[i] = (unsigned)(Rb * K + C) * 2u; }
;     const size_t kstep = (size_t)(BK * 2);
;     const size_t hstep = (size_t)HALF * K * 2;
;     const size_t tstep = 2 * hstep;
;     const unsigned ldsw = (unsigned)wid * 1024u;
;     const int aoff = lds_byte(wr * 64 + fr, fq * 8), boff = lds_byte(wc * 32 + fr, fq * 8);
;     ...
;     Unit cur, nxt; int ui = 0;
;     if (!S.next(0, cur)) return;
;     f32x4 acc[2][2][4][2];
; #pragma unroll
;     for (int a = 0; a < 2; ++a)
; #pragma unroll
;         for (int b = 0; b < 2; ++b)
; #pragma unroll
;             for (int m = 0; m < 4; ++m)
; #pragma unroll
;                 for (int n = 0; n < 2; ++n) { float zr_ = 0.f; asm volatile("" : "+v"(zr_)); acc[a][b][m][n] = (f32x4){zr_, zr_, zr_, zr_}; }
;     bf16x8 At[4][2], B0[2][2], B1[2][2];
;     const char* cA = (const char*)g.A + (size_t)cur.pm * tstep; const char* cB = (const char*)g.Bt + (size_t)cur.pn * tstep;
;     S.a_ready(cur);
;     if constexpr (SP2) {
;         PG8_STAGE(PG8_SB(0, 0), cB, voffB); PG8_STAGE(PG8_SB(0, 1), cB + hstep, voffB); PG8_STAGE(PG8_SA(0, 0), cA, voffA); PG8_STAGE(PG8_SA(0, 1), cA + hstep, voffA);
;         if (wr == 1) PG8_BAR;
;         PG8_WAIT_V(2); PG8_BAR;
;         PG8_STAGE(PG8_SB(1, 0), cB + kstep, voffB); PG8_STAGE(PG8_SA(1, 0), cA + kstep, voffA); PG8_STAGE(PG8_SB(1, 1), cB + hstep + kstep, voffB);
;         PG8_WAIT_V(6); PG8_BAR;
.LBB0_948:
	s_andn2_b64 vcc, exec, s[4:5]
	s_cbranch_vccnz .LBB0_1243
	s_mov_b32 s100, 0
	s_mov_b32 s101, 0x8000
	v_readlane_b32 s0, v253, 51
	v_readlane_b32 s1, v253, 52
	v_mov_b32_e32 v0, v197
	s_waitcnt lgkmcnt(0)
	s_load_dwordx16 s[40:55], s[0:1], 0x88
	s_load_dwordx2 s[8:9], s[0:1], 0x110
	s_lshr_b32 s0, s30, 5
	v_mov_b32_e32 v0, v197
	s_cmp_ge_i32 s94, s0
	s_nop 0
	v_readfirstlane_b32 s14, v0
	s_cbranch_scc1 .LBB0_997
	v_lshlrev_b32_e32 v2, 4, v0
	v_add_u32_e32 v3, 0x2000, v2
	v_ashrrev_i32_e32 v4, 31, v3
	v_lshrrev_b32_e32 v4, 22, v4
	v_add_u32_e32 v4, v3, v4
	v_ashrrev_i32_e32 v130, 10, v4
	v_mul_i32_i24_e32 v4, 0x400, v130
	v_sub_u32_e32 v3, v3, v4
	v_lshrrev_b32_e32 v4, 4, v3
	v_bitop3_b32 v3, v4, v3, 32 bitop3:0x6c
	v_ashrrev_i32_e32 v4, 31, v3
	v_lshrrev_b32_e32 v4, 26, v4
	v_add_u32_e32 v4, v3, v4
	v_lshlrev_b32_e32 v5, 3, v130
	v_ashrrev_i32_e32 v131, 6, v4
	v_and_b32_e32 v5, -16, v5
	v_add_u32_e32 v5, v131, v5
	v_and_b32_e32 v6, 3, v131
	s_mov_b32 s17, 0x3fffe0
	v_lshrrev_b32_e32 v7, 2, v5
	v_lshlrev_b32_e32 v8, 1, v5
	v_and_or_b32 v6, v5, s17, v6
	v_and_b32_e32 v7, 4, v7
	v_and_b32_e32 v8, 24, v8
	v_and_b32_e32 v4, 0xc0, v4
	v_or3_b32 v6, v6, v7, v8
	v_sub_u32_e32 v3, v3, v4
	v_mov_b32_e32 v8, 1
	v_lshlrev_b32_e32 v7, 5, v130
	v_ashrrev_i16_sdwa v3, v8, sext(v3) dst_sel:DWORD dst_unused:UNUSED_PAD src0_sel:DWORD src1_sel:BYTE_0
	v_and_b32_e32 v7, 32, v7
	v_bfe_i32 v132, v3, 0, 16
	v_add_lshl_u32 v3, v7, v132, 1
	v_lshl_add_u32 v194, v6, 10, v3
	v_lshl_add_u32 v202, v5, 10, v3
	v_bfe_i32 v3, v0, 27, 1
	v_lshrrev_b32_e32 v3, 22, v3
	v_add_u32_e32 v3, v2, v3
	v_and_b32_e32 v3, 0xfffffc00, v3
	v_sub_u32_e32 v2, v2, v3
	v_lshrrev_b32_e32 v3, 4, v2
	v_bitop3_b32 v3, v3, v2, 32 bitop3:0x6c
	v_ashrrev_i32_e32 v2, 31, v2
	v_lshrrev_b32_e32 v2, 26, v2
	v_add_u32_e32 v2, v3, v2
	v_ashrrev_i32_e32 v133, 6, v2
	v_ashrrev_i32_e32 v2, 31, v0
	s_waitcnt lgkmcnt(0)
	s_add_u32 s1, s8, 0x2d4a6000
	v_lshrrev_b32_e32 v2, 26, v2
	s_addc_u32 s12, s9, 0
	v_add_u32_e32 v2, v0, v2
	s_add_u32 s31, s8, 0x82c6000
	v_ashrrev_i32_e32 v134, 6, v2
	s_addc_u32 s56, s9, 0
	v_readlane_b32 s4, v253, 10
	v_lshlrev_b32_e32 v2, 3, v134
	s_add_u32 s4, s31, s4
	v_and_b32_e32 v2, -16, v2
	s_addc_u32 s5, s56, 0
	v_readlane_b32 s6, v253, 13
	v_add_u32_e32 v2, v133, v2
	v_readlane_b32 s7, v253, 14
	s_add_u32 s26, s1, s6
	v_and_b32_e32 v4, 3, v133
	v_lshrrev_b32_e32 v5, 2, v2
	v_lshlrev_b32_e32 v6, 1, v2
	s_addc_u32 s27, s12, s7
	s_ashr_i32 s15, s14, 6
	v_and_or_b32 v4, v2, s17, v4
	v_and_b32_e32 v5, 4, v5
	v_and_b32_e32 v6, 24, v6
	s_ashr_i32 s16, s14, 8
	s_lshl_b32 s57, s15, 10
	v_or3_b32 v4, v4, v5, v6
	v_mul_i32_i24_e32 v6, 64, v133
	s_add_u32 s6, s26, 0x20000
	v_sub_u32_e32 v3, v3, v6
	s_addc_u32 s7, s27, 0
	v_lshlrev_b32_e32 v5, 5, v134
	v_ashrrev_i16_sdwa v3, v8, sext(v3) dst_sel:DWORD dst_unused:UNUSED_PAD src0_sel:DWORD src1_sel:BYTE_0
	s_add_u32 s10, s4, 0x20000
	v_and_b32_e32 v5, 32, v5
	v_bfe_i32 v135, v3, 0, 16
	s_addc_u32 s11, s5, 0
	v_add_lshl_u32 v3, v5, v135, 1
	s_add_i32 s58, s57, 0
	v_lshl_add_u32 v204, v4, 10, v3
	v_lshl_add_u32 v206, v2, 10, v3
	v_mov_b32_e32 v126, v1
	v_mov_b32_e32 v118, v1
	v_mov_b32_e32 v110, v1
	v_mov_b32_e32 v102, v1
	v_mov_b32_e32 v94, v1
	v_mov_b32_e32 v86, v1
	v_mov_b32_e32 v78, v1
	v_mov_b32_e32 v70, v1
	v_mov_b32_e32 v122, v1
	v_mov_b32_e32 v114, v1
	v_mov_b32_e32 v106, v1
	v_mov_b32_e32 v98, v1
	v_mov_b32_e32 v90, v1
	v_mov_b32_e32 v82, v1
	v_mov_b32_e32 v74, v1
	v_mov_b32_e32 v66, v1
	v_mov_b32_e32 v62, v1
	v_mov_b32_e32 v54, v1
	v_mov_b32_e32 v46, v1
	v_mov_b32_e32 v38, v1
	v_mov_b32_e32 v30, v1
	v_mov_b32_e32 v22, v1
	v_mov_b32_e32 v14, v1
	v_mov_b32_e32 v6, v1
	v_mov_b32_e32 v58, v1
	v_mov_b32_e32 v50, v1
	v_mov_b32_e32 v42, v1
	v_mov_b32_e32 v34, v1
	v_mov_b32_e32 v26, v1
	v_mov_b32_e32 v18, v1
	v_mov_b32_e32 v10, v1
	v_mov_b32_e32 v2, v1
	s_add_i32 m0, s58, 0x10000
	s_nop 0
	global_load_lds_dwordx4 v204, s[4:5]
	s_add_i32 m0, s58, 0x12000
	s_add_i32 s59, s58, 0x2000
	global_load_lds_dwordx4 v194, s[4:5]
	s_add_i32 m0, s58, 0x14000
	s_add_i32 s60, s58, 0x4000
	global_load_lds_dwordx4 v204, s[10:11]
	s_add_i32 m0, s58, 0x16000
	s_add_i32 s61, s58, 0x6000
	global_load_lds_dwordx4 v194, s[10:11]
	s_mov_b32 m0, s58
	v_mov_b32_e32 v205, v1
	global_load_lds_dwordx4 v206, s[26:27]
	s_mov_b32 m0, s59
	v_mov_b32_e32 v195, v1
	global_load_lds_dwordx4 v202, s[26:27]
	s_mov_b32 m0, s60
	v_mov_b32_e32 v207, v1
	global_load_lds_dwordx4 v206, s[6:7]
	s_mov_b32 m0, s61
	v_mov_b32_e32 v203, v1
	global_load_lds_dwordx4 v202, s[6:7]
	s_cmp_eq_u32 s16, 1
	v_lshl_add_u64 v[16:17], s[4:5], 0, v[204:205]
	v_lshl_add_u64 v[12:13], s[4:5], 0, v[194:195]
	v_lshl_add_u64 v[4:5], s[26:27], 0, v[206:207]
	s_cselect_b64 s[6:7], -1, 0
	s_cmp_lg_u32 s16, 1
	v_lshl_add_u64 v[8:9], s[26:27], 0, v[202:203]
	s_cbranch_scc1 .LBB0_952
	s_barrier

; #define PG8_STAGE(bufoff, gbase, voff) do { _Pragma("unroll") for (int _i = 0; _i < 2; ++_i) \
;         __builtin_amdgcn_global_load_lds((const unsigned*)((const char*)(gbase) + (voff)[_i]), (PG8_LAS unsigned*)(lds + (bufoff) + ldsw + _i * 8192), 16, 0, 0); } while (0)
; #define PG8_LDA(dst, b, h) do { _Pragma("unroll") for (int m = 0; m < 4; ++m) _Pragma("unroll") for (int k = 0; k < 2; ++k) dst[m][k] = *(const PG8_LAS bf16x8*)(lds + PG8_SA(b, h) + aoff + m * 2048 + k * 1024); } while (0)
; #define PG8_LDB(dst, b, h) do { _Pragma("unroll") for (int n = 0; n < 2; ++n) _Pragma("unroll") for (int k = 0; k < 2; ++k) dst[n][k] = *(const PG8_LAS bf16x8*)(lds + PG8_SB(b, h) + boff + n * 2048 + k * 1024); } while (0)
; #define PG8_MMA(ai, bj, At, Bt) do { __builtin_amdgcn_s_setprio(1); _Pragma("unroll") for (int m = 0; m < 4; ++m) _Pragma("unroll") for (int n = 0; n < 2; ++n) _Pragma("unroll") for (int k = 0; k < 2; ++k) \
;         acc[ai][bj][m][n] = __builtin_amdgcn_mfma_f32_16x16x32_bf16(Bt[n][k], At[m][k], acc[ai][bj][m][n], 0, 0, 0); __builtin_amdgcn_s_setprio(0); } while (0)
; #define PG8_WAIT_V(n) asm volatile("s_waitcnt vmcnt(" #n ")" ::: "memory")
; #define PG8_BAR __builtin_amdgcn_s_barrier()
; template <class Epi, class Sched, bool ALIGN_EPI = false, bool SP2 = false>
; __device__ __forceinline__ void gemm_phase(PG8_LAS unsigned char* lds, const Gemm g, const Sched& S, const Epi& E) {
;     ...
;         for (int t = 0; t < nt; t += 2) {
;             const bool last = (t == nt - 2);
;             const char* a1 = cA + (size_t)(t + 1) * kstep;
;             const char* a2 = last ? nA : cA + (size_t)(t + 2) * kstep; const char* b2 = last ? nB : cB + (size_t)(t + 2) * kstep;
;             const char* a3 = a2 + kstep; const char* b3 = b2 + kstep;
;             if (last && has_next) S.a_ready(nxt);
;             if constexpr (SP2) {
;             PG8_LDB(B0, 0, 0); PG8_LDB(B1, 0, 1); PG8_SCHED; PG8_LDA(At, 0, 0); PG8_STAGE(PG8_SA(1, 1), a1 + hstep, voffA);
;             PG8_WAIT_V(8); PG8_WAIT_L(0); PG8_BAR; PG8_MMA(0, 0, At, B0); PG8_MMA(0, 1, At, B1); PG8_BAR; PG8_SCHED;
;             PG8_LDA(At, 0, 1); PG8_STAGE(PG8_SB(0, 0), b2, voffB); PG8_STAGE(PG8_SB(0, 1), b2 + hstep, voffB); PG8_STAGE(PG8_SA(0, 0), a2, voffA);
;             PG8_WAIT_V(8); PG8_WAIT_L(0); PG8_BAR; PG8_MMA(1, 0, At, B0); PG8_MMA(1, 1, At, B1); PG8_BAR; PG8_SCHED;
.LBB0_958:
	s_sub_i32 vcc_hi, 0x29000, s100
	s_sub_i32 vcc_hi, vcc_hi, s101
	s_add_u32 s4, s26, 0xfffe0080
	s_addc_u32 s5, s27, -1
	s_add_i32 s72, 0, 0x10000
	s_cmp_eq_u32 s71, 4
	s_cselect_b32 s39, s17, s5
	s_cselect_b32 s38, s29, s4
	v_add_u32_e32 v0, s72, v242
	s_cselect_b32 s5, s19, s70
	s_cselect_b32 s4, s68, s69
	s_add_i32 s74, 0, 0x14000
	ds_read_b128 v[130:133], v0
	ds_read_b128 v[134:137], v0 offset:1024
	ds_read_b128 v[138:141], v0 offset:2048
	ds_read_b128 v[142:145], v0 offset:3072
	v_add_u32_e32 v0, s74, v242
	ds_read_b128 v[146:149], v0
	ds_read_b128 v[150:153], v0 offset:1024
	ds_read_b128 v[154:157], v0 offset:2048
	ds_read_b128 v[158:161], v0 offset:3072
	v_lshl_add_u64 v[212:213], s[26:27], 0, v[208:209]
	s_add_i32 m0, s58, 0xc000
	v_add_u32_e32 v250, s100, v244
	ds_read_b128 v[162:165], v250
	ds_read_b128 v[166:169], v250 offset:1024
	ds_read_b128 v[170:173], v250 offset:2048
	ds_read_b128 v[174:177], v250 offset:3072
	ds_read_b128 v[178:181], v250 offset:4096
	ds_read_b128 v[182:185], v250 offset:5120
	ds_read_b128 v[186:189], v250 offset:6144
	ds_read_b128 v[190:193], v250 offset:7168
	global_load_lds_dwordx4 v[212:213], off
	v_lshl_add_u64 v[212:213], s[26:27], 0, v[210:211]
	s_add_i32 m0, s58, 0xe000
	s_nop 0
	global_load_lds_dwordx4 v[212:213], off
	v_lshl_add_u64 v[238:239], s[38:39], 0, v[206:207]
	v_lshl_add_u64 v[240:241], s[38:39], 0, v[202:203]
	s_add_i32 m0, vcc_hi, s58
	s_nop 0
	global_load_lds_dwordx4 v[238:239], off
	s_add_i32 m0, m0, 0x2000
	s_nop 0
	global_load_lds_dwordx4 v[240:241], off
	s_waitcnt vmcnt(10)
	s_waitcnt lgkmcnt(0)
	s_setprio 1
	s_waitcnt lgkmcnt(0)
	v_mfma_f32_16x16x32_bf16 v[126:129], v[130:133], v[162:165], v[126:129]
	v_mfma_f32_16x16x32_bf16 v[118:121], v[138:141], v[162:165], v[118:121]
	v_mfma_f32_16x16x32_bf16 v[110:113], v[130:133], v[170:173], v[110:113]
	v_mfma_f32_16x16x32_bf16 v[102:105], v[138:141], v[170:173], v[102:105]
	s_barrier
	v_mfma_f32_16x16x32_bf16 v[94:97], v[130:133], v[178:181], v[94:97]
	v_mfma_f32_16x16x32_bf16 v[86:89], v[138:141], v[178:181], v[86:89]
	v_mfma_f32_16x16x32_bf16 v[78:81], v[130:133], v[186:189], v[78:81]
	v_mfma_f32_16x16x32_bf16 v[70:73], v[138:141], v[186:189], v[70:73]
	v_mfma_f32_16x16x32_bf16 v[126:129], v[134:137], v[166:169], v[126:129]
	v_mfma_f32_16x16x32_bf16 v[118:121], v[142:145], v[166:169], v[118:121]
	v_mfma_f32_16x16x32_bf16 v[110:113], v[134:137], v[174:177], v[110:113]
	v_mfma_f32_16x16x32_bf16 v[102:105], v[142:145], v[174:177], v[102:105]
	v_mfma_f32_16x16x32_bf16 v[94:97], v[134:137], v[182:185], v[94:97]
	v_mfma_f32_16x16x32_bf16 v[86:89], v[142:145], v[182:185], v[86:89]
	v_mfma_f32_16x16x32_bf16 v[78:81], v[134:137], v[190:193], v[78:81]
	v_mfma_f32_16x16x32_bf16 v[70:73], v[142:145], v[190:193], v[70:73]
	s_setprio 0
	s_setprio 1
	v_mfma_f32_16x16x32_bf16 v[122:125], v[146:149], v[162:165], v[122:125]
	v_mfma_f32_16x16x32_bf16 v[114:117], v[154:157], v[162:165], v[114:117]
	v_mfma_f32_16x16x32_bf16 v[106:109], v[146:149], v[170:173], v[106:109]
	v_mfma_f32_16x16x32_bf16 v[98:101], v[154:157], v[170:173], v[98:101]
	v_mfma_f32_16x16x32_bf16 v[90:93], v[146:149], v[178:181], v[90:93]
	v_mfma_f32_16x16x32_bf16 v[82:85], v[154:157], v[178:181], v[82:85]
	v_mfma_f32_16x16x32_bf16 v[74:77], v[146:149], v[186:189], v[74:77]
	v_mfma_f32_16x16x32_bf16 v[66:69], v[154:157], v[186:189], v[66:69]
	v_mfma_f32_16x16x32_bf16 v[122:125], v[150:153], v[166:169], v[122:125]
	v_mfma_f32_16x16x32_bf16 v[114:117], v[158:161], v[166:169], v[114:117]
	v_mfma_f32_16x16x32_bf16 v[106:109], v[150:153], v[174:177], v[106:109]
	v_mfma_f32_16x16x32_bf16 v[98:101], v[158:161], v[174:177], v[98:101]
	v_mfma_f32_16x16x32_bf16 v[90:93], v[150:153], v[182:185], v[90:93]
	v_mfma_f32_16x16x32_bf16 v[82:85], v[158:161], v[182:185], v[82:85]
	v_mfma_f32_16x16x32_bf16 v[74:77], v[150:153], v[190:193], v[74:77]
	v_mfma_f32_16x16x32_bf16 v[66:69], v[158:161], v[190:193], v[66:69]
	s_setprio 0
	s_barrier
	s_add_i32 s72, s72, s57
	v_lshl_add_u64 v[212:213], s[4:5], 0, v[204:205]
	s_mov_b32 m0, s72
	ds_read_b128 v[162:165], v244 offset:16384
	ds_read_b128 v[166:169], v244 offset:17408
	ds_read_b128 v[170:173], v244 offset:18432
	ds_read_b128 v[174:177], v244 offset:19456
	ds_read_b128 v[178:181], v244 offset:20480
	ds_read_b128 v[182:185], v244 offset:21504
	ds_read_b128 v[186:189], v244 offset:22528
	ds_read_b128 v[190:193], v244 offset:23552
	global_load_lds_dwordx4 v[212:213], off
	s_add_i32 m0, s72, 0x2000
	s_add_u32 s72, s4, 0x20000
	v_lshl_add_u64 v[214:215], s[4:5], 0, v[194:195]
	s_addc_u32 s73, s5, 0
	s_add_i32 s74, s74, s57
	global_load_lds_dwordx4 v[214:215], off
	v_lshl_add_u64 v[216:217], s[72:73], 0, v[204:205]
	s_mov_b32 m0, s74
	global_load_lds_dwordx4 v[216:217], off
	v_lshl_add_u64 v[216:217], s[72:73], 0, v[194:195]
	s_add_i32 m0, s74, 0x2000
	s_nop 0
	global_load_lds_dwordx4 v[216:217], off
	s_waitcnt vmcnt(8)
	s_waitcnt lgkmcnt(0)
	s_setprio 1
	s_waitcnt lgkmcnt(0)
	v_mfma_f32_16x16x32_bf16 v[62:65], v[130:133], v[162:165], v[62:65]
	v_mfma_f32_16x16x32_bf16 v[54:57], v[138:141], v[162:165], v[54:57]
	v_mfma_f32_16x16x32_bf16 v[46:49], v[130:133], v[170:173], v[46:49]
	v_mfma_f32_16x16x32_bf16 v[38:41], v[138:141], v[170:173], v[38:41]
	s_barrier
; #define PG8_STAGE(bufoff, gbase, voff) do { _Pragma("unroll") for (int _i = 0; _i < 2; ++_i) \
;         __builtin_amdgcn_global_load_lds((const unsigned*)((const char*)(gbase) + (voff)[_i]), (PG8_LAS unsigned*)(lds + (bufoff) + ldsw + _i * 8192), 16, 0, 0); } while (0)
; #define PG8_LDA(dst, b, h) do { _Pragma("unroll") for (int m = 0; m < 4; ++m) _Pragma("unroll") for (int k = 0; k < 2; ++k) dst[m][k] = *(const PG8_LAS bf16x8*)(lds + PG8_SA(b, h) + aoff + m * 2048 + k * 1024); } while (0)
; #define PG8_LDB(dst, b, h) do { _Pragma("unroll") for (int n = 0; n < 2; ++n) _Pragma("unroll") for (int k = 0; k < 2; ++k) dst[n][k] = *(const PG8_LAS bf16x8*)(lds + PG8_SB(b, h) + boff + n * 2048 + k * 1024); } while (0)
; #define PG8_MMA(ai, bj, At, Bt) do { __builtin_amdgcn_s_setprio(1); _Pragma("unroll") for (int m = 0; m < 4; ++m) _Pragma("unroll") for (int n = 0; n < 2; ++n) _Pragma("unroll") for (int k = 0; k < 2; ++k) \
;         acc[ai][bj][m][n] = __builtin_amdgcn_mfma_f32_16x16x32_bf16(Bt[n][k], At[m][k], acc[ai][bj][m][n], 0, 0, 0); __builtin_amdgcn_s_setprio(0); } while (0)
; #define PG8_WAIT_V(n) asm volatile("s_waitcnt vmcnt(" #n ")" ::: "memory")
; #define PG8_WAIT_L(n) asm volatile("s_waitcnt lgkmcnt(" #n ")" ::: "memory")
; #define PG8_BAR __builtin_amdgcn_s_barrier()
; #define PG8_SCHED __builtin_amdgcn_sched_barrier(0)
; template <class Epi, class Sched, bool ALIGN_EPI = false, bool SP2 = false>
; __device__ __forceinline__ void gemm_phase(PG8_LAS unsigned char* lds, const Gemm g, const Sched& S, const Epi& E) {
;     ...
;             PG8_WAIT_V(8); PG8_WAIT_L(0); PG8_BAR; PG8_MMA(0, 0, At, B0); PG8_MMA(0, 1, At, B1); PG8_BAR; PG8_SCHED;
;             PG8_LDA(At, 0, 1); PG8_STAGE(PG8_SB(0, 0), b2, voffB); PG8_STAGE(PG8_SB(0, 1), b2 + hstep, voffB); PG8_STAGE(PG8_SA(0, 0), a2, voffA);
;             PG8_WAIT_V(8); PG8_WAIT_L(0); PG8_BAR; PG8_MMA(1, 0, At, B0); PG8_MMA(1, 1, At, B1); PG8_BAR; PG8_SCHED;
;             PG8_LDB(B0, 1, 0); PG8_LDB(B1, 1, 1); PG8_SCHED; PG8_LDA(At, 1, 0); PG8_STAGE(PG8_SA(0, 1), a2 + hstep, voffA);
;             PG8_WAIT_V(8); PG8_WAIT_L(0); PG8_BAR; PG8_MMA(0, 0, At, B0); PG8_MMA(0, 1, At, B1); PG8_BAR; PG8_SCHED;
	v_mfma_f32_16x16x32_bf16 v[30:33], v[130:133], v[178:181], v[30:33]
	v_mfma_f32_16x16x32_bf16 v[22:25], v[138:141], v[178:181], v[22:25]
	v_mfma_f32_16x16x32_bf16 v[14:17], v[130:133], v[186:189], v[14:17]
	v_mfma_f32_16x16x32_bf16 v[6:9], v[138:141], v[186:189], v[6:9]
	v_mfma_f32_16x16x32_bf16 v[62:65], v[134:137], v[166:169], v[62:65]
	v_mfma_f32_16x16x32_bf16 v[54:57], v[142:145], v[166:169], v[54:57]
	v_mfma_f32_16x16x32_bf16 v[46:49], v[134:137], v[174:177], v[46:49]
	v_mfma_f32_16x16x32_bf16 v[38:41], v[142:145], v[174:177], v[38:41]
	v_mfma_f32_16x16x32_bf16 v[30:33], v[134:137], v[182:185], v[30:33]
	v_mfma_f32_16x16x32_bf16 v[22:25], v[142:145], v[182:185], v[22:25]
	v_mfma_f32_16x16x32_bf16 v[14:17], v[134:137], v[190:193], v[14:17]
	v_mfma_f32_16x16x32_bf16 v[6:9], v[142:145], v[190:193], v[6:9]
	s_setprio 0
	s_setprio 1
	v_mfma_f32_16x16x32_bf16 v[58:61], v[146:149], v[162:165], v[58:61]
	v_mfma_f32_16x16x32_bf16 v[50:53], v[154:157], v[162:165], v[50:53]
	v_mfma_f32_16x16x32_bf16 v[42:45], v[146:149], v[170:173], v[42:45]
	v_mfma_f32_16x16x32_bf16 v[34:37], v[154:157], v[170:173], v[34:37]
	v_mfma_f32_16x16x32_bf16 v[26:29], v[146:149], v[178:181], v[26:29]
	v_mfma_f32_16x16x32_bf16 v[18:21], v[154:157], v[178:181], v[18:21]
	v_mfma_f32_16x16x32_bf16 v[10:13], v[146:149], v[186:189], v[10:13]
	v_mfma_f32_16x16x32_bf16 v[2:5], v[154:157], v[186:189], v[2:5]
	v_mfma_f32_16x16x32_bf16 v[58:61], v[150:153], v[166:169], v[58:61]
	v_mfma_f32_16x16x32_bf16 v[50:53], v[158:161], v[166:169], v[50:53]
	v_mfma_f32_16x16x32_bf16 v[42:45], v[150:153], v[174:177], v[42:45]
	v_mfma_f32_16x16x32_bf16 v[34:37], v[158:161], v[174:177], v[34:37]
	v_mfma_f32_16x16x32_bf16 v[26:29], v[150:153], v[182:185], v[26:29]
	v_mfma_f32_16x16x32_bf16 v[18:21], v[158:161], v[182:185], v[18:21]
	v_mfma_f32_16x16x32_bf16 v[10:13], v[150:153], v[190:193], v[10:13]
	v_mfma_f32_16x16x32_bf16 v[2:5], v[158:161], v[190:193], v[2:5]
	s_setprio 0
	s_barrier
	s_add_i32 s72, 0, 0x18000
	v_add_u32_e32 v0, s72, v242
	s_add_i32 s73, 0, 0x1c000
	ds_read_b128 v[130:133], v0
	ds_read_b128 v[134:137], v0 offset:1024
	ds_read_b128 v[138:141], v0 offset:2048
	ds_read_b128 v[142:145], v0 offset:3072
	v_add_u32_e32 v0, s73, v242
	ds_read_b128 v[146:149], v0
	ds_read_b128 v[150:153], v0 offset:1024
	ds_read_b128 v[154:157], v0 offset:2048
	ds_read_b128 v[158:161], v0 offset:3072
	s_add_u32 s38, s38, 0x20000
	s_addc_u32 s39, s39, 0
	s_mov_b32 m0, s60
	v_lshl_add_u64 v[220:221], s[38:39], 0, v[206:207]
	v_add_u32_e32 v250, s101, v244
	ds_read_b128 v[162:165], v250
	ds_read_b128 v[166:169], v250 offset:1024
	ds_read_b128 v[170:173], v250 offset:2048
	ds_read_b128 v[174:177], v250 offset:3072
	ds_read_b128 v[178:181], v250 offset:4096
	ds_read_b128 v[182:185], v250 offset:5120
	ds_read_b128 v[186:189], v250 offset:6144
	ds_read_b128 v[190:193], v250 offset:7168
	global_load_lds_dwordx4 v[220:221], off
	v_lshl_add_u64 v[220:221], s[38:39], 0, v[202:203]
	s_mov_b32 m0, s61
	s_nop 0
	global_load_lds_dwordx4 v[220:221], off
	v_lshl_add_u64 v[246:247], v[238:239], 0, s[96:97]
	v_lshl_add_u64 v[248:249], v[240:241], 0, s[96:97]
	s_add_i32 m0, s100, s58
	s_nop 0
	global_load_lds_dwordx4 v[246:247], off
	s_add_i32 m0, m0, 0x2000
	s_nop 0
	global_load_lds_dwordx4 v[248:249], off
	s_waitcnt vmcnt(10)
	s_waitcnt lgkmcnt(0)
	s_setprio 1
	s_waitcnt lgkmcnt(0)
	v_mfma_f32_16x16x32_bf16 v[126:129], v[130:133], v[162:165], v[126:129]
	v_mfma_f32_16x16x32_bf16 v[118:121], v[138:141], v[162:165], v[118:121]
	v_mfma_f32_16x16x32_bf16 v[110:113], v[130:133], v[170:173], v[110:113]
	v_mfma_f32_16x16x32_bf16 v[102:105], v[138:141], v[170:173], v[102:105]
	s_barrier
; #define PG8_STAGE(bufoff, gbase, voff) do { _Pragma("unroll") for (int _i = 0; _i < 2; ++_i) \
;         __builtin_amdgcn_global_load_lds((const unsigned*)((const char*)(gbase) + (voff)[_i]), (PG8_LAS unsigned*)(lds + (bufoff) + ldsw + _i * 8192), 16, 0, 0); } while (0)
; #define PG8_LDA(dst, b, h) do { _Pragma("unroll") for (int m = 0; m < 4; ++m) _Pragma("unroll") for (int k = 0; k < 2; ++k) dst[m][k] = *(const PG8_LAS bf16x8*)(lds + PG8_SA(b, h) + aoff + m * 2048 + k * 1024); } while (0)
; #define PG8_LDB(dst, b, h) do { _Pragma("unroll") for (int n = 0; n < 2; ++n) _Pragma("unroll") for (int k = 0; k < 2; ++k) dst[n][k] = *(const PG8_LAS bf16x8*)(lds + PG8_SB(b, h) + boff + n * 2048 + k * 1024); } while (0)
; #define PG8_MMA(ai, bj, At, Bt) do { __builtin_amdgcn_s_setprio(1); _Pragma("unroll") for (int m = 0; m < 4; ++m) _Pragma("unroll") for (int n = 0; n < 2; ++n) _Pragma("unroll") for (int k = 0; k < 2; ++k) \
;         acc[ai][bj][m][n] = __builtin_amdgcn_mfma_f32_16x16x32_bf16(Bt[n][k], At[m][k], acc[ai][bj][m][n], 0, 0, 0); __builtin_amdgcn_s_setprio(0); } while (0)
; #define PG8_WAIT_V(n) asm volatile("s_waitcnt vmcnt(" #n ")" ::: "memory")
; #define PG8_WAIT_L(n) asm volatile("s_waitcnt lgkmcnt(" #n ")" ::: "memory")
; template <class Epi, class Sched, bool ALIGN_EPI = false, bool SP2 = false>
; __device__ __forceinline__ void gemm_phase(PG8_LAS unsigned char* lds, const Gemm g, const Sched& S, const Epi& E) {
;     ...
;         for (int t = 0; t < nt; t += 2) {
;             const bool last = (t == nt - 2);
;             const char* a1 = cA + (size_t)(t + 1) * kstep;
;             const char* a2 = last ? nA : cA + (size_t)(t + 2) * kstep; const char* b2 = last ? nB : cB + (size_t)(t + 2) * kstep;
;             const char* a3 = a2 + kstep; const char* b3 = b2 + kstep;
;             if (last && has_next) S.a_ready(nxt);
;     ...
;             PG8_LDB(B0, 1, 0); PG8_LDB(B1, 1, 1); PG8_SCHED; PG8_LDA(At, 1, 0); PG8_STAGE(PG8_SA(0, 1), a2 + hstep, voffA);
;             PG8_WAIT_V(8); PG8_WAIT_L(0); PG8_BAR; PG8_MMA(0, 0, At, B0); PG8_MMA(0, 1, At, B1); PG8_BAR; PG8_SCHED;
;             PG8_LDA(At, 1, 1); PG8_STAGE(PG8_SB(1, 0), b3, voffB); PG8_STAGE(PG8_SB(1, 1), b3 + hstep, voffB); PG8_STAGE(PG8_SA(1, 0), a3, voffA);
;             PG8_WAIT_V(8); PG8_WAIT_L(0); PG8_BAR; PG8_MMA(1, 0, At, B0); PG8_MMA(1, 1, At, B1); PG8_BAR; PG8_SCHED;
	v_mfma_f32_16x16x32_bf16 v[94:97], v[130:133], v[178:181], v[94:97]
	v_mfma_f32_16x16x32_bf16 v[86:89], v[138:141], v[178:181], v[86:89]
	v_mfma_f32_16x16x32_bf16 v[78:81], v[130:133], v[186:189], v[78:81]
	v_mfma_f32_16x16x32_bf16 v[70:73], v[138:141], v[186:189], v[70:73]
	v_mfma_f32_16x16x32_bf16 v[126:129], v[134:137], v[166:169], v[126:129]
	v_mfma_f32_16x16x32_bf16 v[118:121], v[142:145], v[166:169], v[118:121]
	v_mfma_f32_16x16x32_bf16 v[110:113], v[134:137], v[174:177], v[110:113]
	v_mfma_f32_16x16x32_bf16 v[102:105], v[142:145], v[174:177], v[102:105]
	v_mfma_f32_16x16x32_bf16 v[94:97], v[134:137], v[182:185], v[94:97]
	v_mfma_f32_16x16x32_bf16 v[86:89], v[142:145], v[182:185], v[86:89]
	v_mfma_f32_16x16x32_bf16 v[78:81], v[134:137], v[190:193], v[78:81]
	v_mfma_f32_16x16x32_bf16 v[70:73], v[142:145], v[190:193], v[70:73]
	s_setprio 0
	s_setprio 1
	v_mfma_f32_16x16x32_bf16 v[122:125], v[146:149], v[162:165], v[122:125]
	v_mfma_f32_16x16x32_bf16 v[114:117], v[154:157], v[162:165], v[114:117]
	v_mfma_f32_16x16x32_bf16 v[106:109], v[146:149], v[170:173], v[106:109]
	v_mfma_f32_16x16x32_bf16 v[98:101], v[154:157], v[170:173], v[98:101]
	v_mfma_f32_16x16x32_bf16 v[90:93], v[146:149], v[178:181], v[90:93]
	v_mfma_f32_16x16x32_bf16 v[82:85], v[154:157], v[178:181], v[82:85]
	v_mfma_f32_16x16x32_bf16 v[74:77], v[146:149], v[186:189], v[74:77]
	v_mfma_f32_16x16x32_bf16 v[66:69], v[154:157], v[186:189], v[66:69]
	v_mfma_f32_16x16x32_bf16 v[122:125], v[150:153], v[166:169], v[122:125]
	v_mfma_f32_16x16x32_bf16 v[114:117], v[158:161], v[166:169], v[114:117]
	v_mfma_f32_16x16x32_bf16 v[106:109], v[150:153], v[174:177], v[106:109]
	v_mfma_f32_16x16x32_bf16 v[98:101], v[158:161], v[174:177], v[98:101]
	v_mfma_f32_16x16x32_bf16 v[90:93], v[150:153], v[182:185], v[90:93]
	v_mfma_f32_16x16x32_bf16 v[82:85], v[158:161], v[182:185], v[82:85]
	v_mfma_f32_16x16x32_bf16 v[74:77], v[150:153], v[190:193], v[74:77]
	v_mfma_f32_16x16x32_bf16 v[66:69], v[158:161], v[190:193], v[66:69]
	s_setprio 0
	s_barrier
	s_add_i32 s38, s72, s57
	v_lshl_add_u64 v[212:213], v[212:213], 0, s[96:97]
	s_mov_b32 m0, s38
	ds_read_b128 v[162:165], v244 offset:49152
	ds_read_b128 v[166:169], v244 offset:50176
	ds_read_b128 v[170:173], v244 offset:51200
	ds_read_b128 v[174:177], v244 offset:52224
	ds_read_b128 v[178:181], v244 offset:53248
	ds_read_b128 v[182:185], v244 offset:54272
	ds_read_b128 v[186:189], v244 offset:55296
	ds_read_b128 v[190:193], v244 offset:56320
	global_load_lds_dwordx4 v[212:213], off
	s_add_i32 m0, s38, 0x2000
	s_add_u32 s4, s4, 0x20080
	v_lshl_add_u64 v[212:213], v[214:215], 0, s[96:97]
	s_addc_u32 s5, s5, 0
	s_add_i32 s38, s73, s57
	global_load_lds_dwordx4 v[212:213], off
	v_lshl_add_u64 v[212:213], s[4:5], 0, v[204:205]
	s_mov_b32 m0, s38
	s_nop 0
	global_load_lds_dwordx4 v[212:213], off
	v_lshl_add_u64 v[212:213], s[4:5], 0, v[194:195]
	s_add_i32 m0, s38, 0x2000
	s_nop 0
	global_load_lds_dwordx4 v[212:213], off
	s_waitcnt vmcnt(8)
	s_waitcnt lgkmcnt(0)
	s_setprio 1
	s_waitcnt lgkmcnt(0)
	v_mfma_f32_16x16x32_bf16 v[62:65], v[130:133], v[162:165], v[62:65]
	v_mfma_f32_16x16x32_bf16 v[54:57], v[138:141], v[162:165], v[54:57]
	v_mfma_f32_16x16x32_bf16 v[46:49], v[130:133], v[170:173], v[46:49]
	v_mfma_f32_16x16x32_bf16 v[38:41], v[138:141], v[170:173], v[38:41]
	s_barrier
	v_mfma_f32_16x16x32_bf16 v[30:33], v[130:133], v[178:181], v[30:33]
	v_mfma_f32_16x16x32_bf16 v[22:25], v[138:141], v[178:181], v[22:25]
	v_mfma_f32_16x16x32_bf16 v[14:17], v[130:133], v[186:189], v[14:17]
	v_mfma_f32_16x16x32_bf16 v[6:9], v[138:141], v[186:189], v[6:9]
	v_mfma_f32_16x16x32_bf16 v[62:65], v[134:137], v[166:169], v[62:65]
	v_mfma_f32_16x16x32_bf16 v[54:57], v[142:145], v[166:169], v[54:57]
	v_mfma_f32_16x16x32_bf16 v[46:49], v[134:137], v[174:177], v[46:49]
	v_mfma_f32_16x16x32_bf16 v[38:41], v[142:145], v[174:177], v[38:41]
	v_mfma_f32_16x16x32_bf16 v[30:33], v[134:137], v[182:185], v[30:33]
	v_mfma_f32_16x16x32_bf16 v[22:25], v[142:145], v[182:185], v[22:25]
	v_mfma_f32_16x16x32_bf16 v[14:17], v[134:137], v[190:193], v[14:17]
	v_mfma_f32_16x16x32_bf16 v[6:9], v[142:145], v[190:193], v[6:9]
	s_setprio 0
	s_setprio 1
	v_mfma_f32_16x16x32_bf16 v[58:61], v[146:149], v[162:165], v[58:61]
	v_mfma_f32_16x16x32_bf16 v[50:53], v[154:157], v[162:165], v[50:53]
	v_mfma_f32_16x16x32_bf16 v[42:45], v[146:149], v[170:173], v[42:45]
	v_mfma_f32_16x16x32_bf16 v[34:37], v[154:157], v[170:173], v[34:37]
	v_mfma_f32_16x16x32_bf16 v[26:29], v[146:149], v[178:181], v[26:29]
	v_mfma_f32_16x16x32_bf16 v[18:21], v[154:157], v[178:181], v[18:21]
	v_mfma_f32_16x16x32_bf16 v[10:13], v[146:149], v[186:189], v[10:13]
	v_mfma_f32_16x16x32_bf16 v[2:5], v[154:157], v[186:189], v[2:5]
	v_mfma_f32_16x16x32_bf16 v[58:61], v[150:153], v[166:169], v[58:61]
	v_mfma_f32_16x16x32_bf16 v[50:53], v[158:161], v[166:169], v[50:53]
	v_mfma_f32_16x16x32_bf16 v[42:45], v[150:153], v[174:177], v[42:45]
	v_mfma_f32_16x16x32_bf16 v[34:37], v[158:161], v[174:177], v[34:37]
	v_mfma_f32_16x16x32_bf16 v[26:29], v[150:153], v[182:185], v[26:29]
	v_mfma_f32_16x16x32_bf16 v[18:21], v[158:161], v[182:185], v[18:21]
	v_mfma_f32_16x16x32_bf16 v[10:13], v[150:153], v[190:193], v[10:13]
	v_mfma_f32_16x16x32_bf16 v[2:5], v[158:161], v[190:193], v[2:5]
	s_setprio 0
	s_barrier
	s_add_i32 s71, s71, 2
	s_mov_b32 s101, s100
	s_mov_b32 s100, vcc_hi
	s_add_u32 s26, s26, 0x100
	s_addc_u32 s27, s27, 0
	s_add_u32 s69, s69, 0x100
	s_addc_u32 s70, s70, 0
	s_cmp_gt_u32 s71, 5
	s_cbranch_scc0 .LBB0_958
	s_and_b64 vcc, exec, s[14:15]
	s_cbranch_vccz .LBB0_961
	s_barrier

; #define PG8_BAR __builtin_amdgcn_s_barrier()
;     __host__ __device__ bool next(int i, Unit& u) const {
;         const long L = (long)i * G + c; if (L >= nwg) return false;
;         int wgid = (int)L; { const int q = nwg / NXCD, r = nwg % NXCD, xcd = wgid % NXCD, off = wgid / NXCD; wgid = (xcd < r ? xcd * (q + 1) : r * (q + 1) + (xcd - r) * q) + off; }
; template <class Epi, class Sched, bool ALIGN_EPI = false, bool SP2 = false>
; __device__ __forceinline__ void gemm_phase(PG8_LAS unsigned char* lds, const Gemm g, const Sched& S, const Epi& E) {
;     const int tid = ltid(), wid = __builtin_amdgcn_readfirstlane(tid >> 6), lane = tid & 63, wr = wid >> 2, wc = wid & 3, fr = lane & 15, fq = lane >> 4;
;     const int K = g.K, nt = K / BK;
;     unsigned voffA[2], voffB[2];
; #pragma unroll
;     for (int i = 0; i < 2; ++i) { int R, C; stage_rc(tid * 16 + i * 8192, R, C); const int Rb = Epi::PERM ? ((R & ~31) + perm32(R & 31)) : R;
;         voffA[i] = (unsigned)(R * K + C) * 2u; voffB[i] = (unsigned)(Rb * K + C) * 2u; }
;     const size_t kstep = (size_t)(BK * 2);
;     const size_t hstep = (size_t)HALF * K * 2;
;     const size_t tstep = 2 * hstep;
;     const unsigned ldsw = (unsigned)wid * 1024u;
;     const int aoff = lds_byte(wr * 64 + fr, fq * 8), boff = lds_byte(wc * 32 + fr, fq * 8);
;     ...
;     Unit cur, nxt; int ui = 0;
;     if (!S.next(0, cur)) return;
;     f32x4 acc[2][2][4][2];
; #pragma unroll
;     for (int a = 0; a < 2; ++a)
; #pragma unroll
;         for (int b = 0; b < 2; ++b)
; #pragma unroll
;             for (int m = 0; m < 4; ++m)
; #pragma unroll
;                 for (int n = 0; n < 2; ++n) { float zr_ = 0.f; asm volatile("" : "+v"(zr_)); acc[a][b][m][n] = (f32x4){zr_, zr_, zr_, zr_}; }
;     bf16x8 At[4][2], B0[2][2], B1[2][2];
;     const char* cA = (const char*)g.A + (size_t)cur.pm * tstep; const char* cB = (const char*)g.Bt + (size_t)cur.pn * tstep;
;     S.a_ready(cur);
;     if constexpr (SP2) {
;         PG8_STAGE(PG8_SB(0, 0), cB, voffB); PG8_STAGE(PG8_SB(0, 1), cB + hstep, voffB); PG8_STAGE(PG8_SA(0, 0), cA, voffA); PG8_STAGE(PG8_SA(0, 1), cA + hstep, voffA);
;         if (wr == 1) PG8_BAR;
;         PG8_WAIT_V(2); PG8_BAR;
;         PG8_STAGE(PG8_SB(1, 0), cB + kstep, voffB); PG8_STAGE(PG8_SA(1, 0), cA + kstep, voffA); PG8_STAGE(PG8_SB(1, 1), cB + hstep + kstep, voffB);
;         PG8_WAIT_V(6); PG8_BAR;
.LBB0_1245:
	s_andn2_b64 vcc, exec, s[4:5]
	s_cbranch_vccnz .LBB0_1316
	s_mov_b32 s100, 0
	s_mov_b32 s101, 0x8000
	v_readlane_b32 s4, v253, 51
	v_readlane_b32 s5, v253, 52
	v_mov_b32_e32 v0, v197
	s_lshr_b32 s12, s30, 5
	v_mov_b32_e32 v132, v197
	s_cmp_ge_i32 s94, s12
	s_waitcnt lgkmcnt(0)
	v_readfirstlane_b32 s10, v132
	s_cbranch_scc1 .LBB0_1262
	v_lshlrev_b32_e32 v0, 4, v132
	v_add_u32_e32 v2, 0x2000, v0
	v_ashrrev_i32_e32 v3, 31, v2
	v_lshrrev_b32_e32 v3, 22, v3
	v_add_u32_e32 v3, v2, v3
	v_ashrrev_i32_e32 v134, 10, v3
	v_mul_i32_i24_e32 v3, 0x400, v134
	v_sub_u32_e32 v2, v2, v3
	v_lshrrev_b32_e32 v3, 4, v2
	v_bitop3_b32 v2, v3, v2, 32 bitop3:0x6c
	v_ashrrev_i32_e32 v3, 31, v2
	s_load_dwordx4 s[16:19], s[4:5], 0x108
	s_load_dwordx2 s[8:9], s[4:5], 0x0
	s_nop 0
	s_load_dwordx2 s[4:5], s[4:5], 0x10
	v_lshrrev_b32_e32 v3, 26, v3
	v_add_u32_e32 v3, v2, v3
	s_lshr_b32 s0, s30, 8
	v_ashrrev_i32_e32 v135, 6, v3
	v_lshlrev_b32_e32 v5, 5, v134
	v_and_b32_e32 v3, 0xc0, v3
	s_waitcnt lgkmcnt(0)
	s_add_u32 s1, s18, 0x315a6000
	v_and_b32_e32 v136, 32, v5
	v_sub_u32_e32 v2, v2, v3
	v_mov_b32_e32 v5, 1
	s_addc_u32 s28, s19, 0
	v_ashrrev_i16_sdwa v2, v5, sext(v2) dst_sel:DWORD dst_unused:UNUSED_PAD src0_sel:DWORD src1_sel:BYTE_0
	s_add_u32 s29, s18, 0x8ac6000
	v_bfe_i32 v137, v2, 0, 16
	v_bfe_i32 v2, v132, 27, 1
	s_addc_u32 s31, s19, 0
	s_ashr_i32 s14, s10, 6
	v_lshrrev_b32_e32 v2, 22, v2
	v_readlane_b32 s6, v253, 22
	s_ashr_i32 s11, s10, 8
	s_lshl_b32 s44, s14, 10
	v_add_u32_e32 v2, v0, v2
	s_add_i32 s45, s0, 1
	v_readlane_b32 s7, v253, 23
	v_and_b32_e32 v2, 0xfffffc00, v2
	s_and_b64 s[6:7], s[6:7], exec
	v_sub_u32_e32 v0, v0, v2
	s_cselect_b32 s6, s45, s0
	v_readlane_b32 s7, v253, 21
	v_lshrrev_b32_e32 v2, 4, v0
	s_mul_i32 s6, s6, s7
	v_readlane_b32 s7, v252, 62
	v_bitop3_b32 v2, v2, v0, 32 bitop3:0x6c
	v_ashrrev_i32_e32 v0, 31, v0
	s_add_i32 s6, s6, s7
	v_lshrrev_b32_e32 v0, 26, v0
	s_ashr_i32 s7, s6, 31
	v_add_u32_e32 v0, v2, v0
	s_lshr_b32 s7, s7, 26
	v_ashrrev_i32_e32 v133, 6, v0
	v_ashrrev_i32_e32 v0, 31, v132
	s_add_i32 s7, s6, s7
	v_lshrrev_b32_e32 v0, 26, v0
	s_ashr_i32 s15, s7, 6
	v_add_u32_e32 v0, v132, v0
	s_lshl_b32 s15, s15, 3
	v_ashrrev_i32_e32 v138, 6, v0
	s_sub_i32 s20, s0, s15
	v_lshlrev_b32_e32 v3, 5, v138
	s_min_i32 s20, s20, 8
	v_and_b32_e32 v139, 32, v3
	v_mul_i32_i24_e32 v3, 64, v133
	s_abs_i32 s21, s20
	v_sub_u32_e32 v2, v2, v3
	v_cvt_f32_u32_e32 v3, s21
	v_ashrrev_i16_sdwa v2, v5, sext(v2) dst_sel:DWORD dst_unused:UNUSED_PAD src0_sel:DWORD src1_sel:BYTE_0
	v_bfe_i32 v140, v2, 0, 16
	s_sub_i32 s23, 0, s21
	v_rcp_iflag_f32_e32 v2, v3
	s_andn2_b32 s7, s7, 63
	s_sub_i32 s6, s6, s7
	s_abs_i32 s22, s6
	v_mul_f32_e32 v2, 0x4f7ffffe, v2
	v_cvt_u32_f32_e32 v2, v2
	s_xor_b32 s7, s6, s20
	s_ashr_i32 s7, s7, 31
	v_lshlrev_b32_e32 v0, 3, v138
	v_readfirstlane_b32 s24, v2
	s_mul_i32 s23, s23, s24
	s_mul_hi_u32 s23, s24, s23
	s_add_i32 s24, s24, s23
	s_mul_hi_u32 s23, s22, s24
	s_mul_i32 s24, s23, s21
	s_sub_i32 s22, s22, s24
	s_add_i32 s24, s23, 1
	s_sub_i32 s25, s22, s21
	s_cmp_ge_u32 s22, s21
	s_cselect_b32 s23, s24, s23
	s_cselect_b32 s22, s25, s22
	s_add_i32 s24, s23, 1
	s_cmp_ge_u32 s22, s21
	s_cselect_b32 s21, s24, s23
	s_xor_b32 s21, s21, s7
	s_sub_i32 s22, s21, s7
	s_mul_i32 s7, s22, s20
	s_sub_i32 s6, s6, s7
	s_add_i32 s24, s15, s6
	s_ashr_i32 s25, s24, 31
	s_ashr_i32 s23, s22, 31
	v_and_b32_e32 v0, 0xffff0, v0
	s_lshl_b64 s[6:7], s[24:25], 20
	s_lshl_b64 s[20:21], s[22:23], 20
	v_lshlrev_b32_e32 v4, 3, v134
	v_add_u32_e32 v0, v133, v0
	s_add_u32 s38, s29, s20
	v_and_b32_e32 v4, 0xffff0, v4
	v_lshl_or_b32 v0, v0, 11, v139
	s_addc_u32 s39, s31, s21
	s_add_i32 s23, s44, 0
	v_add_u32_e32 v4, v135, v4
	v_add_lshl_u32 v0, v0, v140, 1
	v_mov_b32_e32 v98, v1
	v_mov_b32_e32 v78, v1
	v_mov_b32_e32 v102, v1
	v_mov_b32_e32 v74, v1
	v_mov_b32_e32 v106, v1
	v_mov_b32_e32 v70, v1
	v_mov_b32_e32 v110, v1
	v_mov_b32_e32 v66, v1
	v_mov_b32_e32 v46, v1
	v_mov_b32_e32 v2, v1
	v_mov_b32_e32 v42, v1
	v_mov_b32_e32 v6, v1
	v_mov_b32_e32 v38, v1
	v_mov_b32_e32 v10, v1
	v_mov_b32_e32 v34, v1
	v_mov_b32_e32 v14, v1
	v_mov_b32_e32 v114, v1
	v_mov_b32_e32 v94, v1
	v_mov_b32_e32 v118, v1
	v_mov_b32_e32 v90, v1
	v_mov_b32_e32 v122, v1
	v_mov_b32_e32 v86, v1
	v_mov_b32_e32 v126, v1
	v_mov_b32_e32 v82, v1
	v_mov_b32_e32 v62, v1
	v_mov_b32_e32 v18, v1
	v_mov_b32_e32 v58, v1
	v_mov_b32_e32 v22, v1
	v_mov_b32_e32 v54, v1
	v_mov_b32_e32 v26, v1
	v_mov_b32_e32 v50, v1
	v_mov_b32_e32 v30, v1
	s_add_i32 m0, s23, 0x10000
	v_lshl_or_b32 v4, v4, 11, v136
	global_load_lds_dwordx4 v0, s[38:39]
	s_add_i32 m0, s23, 0x12000
	v_add_lshl_u32 v130, v4, v137, 1
	s_add_u32 s20, s38, 0x80000
	global_load_lds_dwordx4 v130, s[38:39]
	s_addc_u32 s21, s39, 0
	s_add_i32 m0, s23, 0x14000
	v_mov_b32_e32 v131, v1
	global_load_lds_dwordx4 v0, s[20:21]
	s_add_i32 m0, s23, 0x16000
	s_add_u32 s26, s1, s6
	s_addc_u32 s27, s28, s7
	s_add_i32 s25, s23, 0x2000
	global_load_lds_dwordx4 v130, s[20:21]
	s_mov_b32 m0, s23
	s_add_u32 s6, s26, 0x80000
	global_load_lds_dwordx4 v0, s[26:27]
	s_mov_b32 m0, s25
	s_addc_u32 s7, s27, 0
	s_add_i32 s46, s23, 0x4000
	global_load_lds_dwordx4 v130, s[26:27]
	s_mov_b32 m0, s46
	s_add_i32 s47, s23, 0x6000
	global_load_lds_dwordx4 v0, s[6:7]
	s_mov_b32 m0, s47
	s_cmp_eq_u32 s11, 1
	global_load_lds_dwordx4 v130, s[6:7]
	v_lshl_add_u64 v[32:33], s[38:39], 0, v[0:1]
	v_lshl_add_u64 v[28:29], s[38:39], 0, v[130:131]
	v_lshl_add_u64 v[24:25], s[26:27], 0, v[0:1]
	s_cselect_b64 s[6:7], -1, 0
	s_cmp_lg_u32 s11, 1
	v_lshl_add_u64 v[20:21], s[26:27], 0, v[130:131]
	s_cbranch_scc1 .LBB0_1249
	s_barrier

; #define PG8_STAGE(bufoff, gbase, voff) do { _Pragma("unroll") for (int _i = 0; _i < 2; ++_i) \
;         __builtin_amdgcn_global_load_lds((const unsigned*)((const char*)(gbase) + (voff)[_i]), (PG8_LAS unsigned*)(lds + (bufoff) + ldsw + _i * 8192), 16, 0, 0); } while (0)
; #define PG8_LDA(dst, b, h) do { _Pragma("unroll") for (int m = 0; m < 4; ++m) _Pragma("unroll") for (int k = 0; k < 2; ++k) dst[m][k] = *(const PG8_LAS bf16x8*)(lds + PG8_SA(b, h) + aoff + m * 2048 + k * 1024); } while (0)
; #define PG8_LDB(dst, b, h) do { _Pragma("unroll") for (int n = 0; n < 2; ++n) _Pragma("unroll") for (int k = 0; k < 2; ++k) dst[n][k] = *(const PG8_LAS bf16x8*)(lds + PG8_SB(b, h) + boff + n * 2048 + k * 1024); } while (0)
; #define PG8_MMA(ai, bj, At, Bt) do { __builtin_amdgcn_s_setprio(1); _Pragma("unroll") for (int m = 0; m < 4; ++m) _Pragma("unroll") for (int n = 0; n < 2; ++n) _Pragma("unroll") for (int k = 0; k < 2; ++k) \
;         acc[ai][bj][m][n] = __builtin_amdgcn_mfma_f32_16x16x32_bf16(Bt[n][k], At[m][k], acc[ai][bj][m][n], 0, 0, 0); __builtin_amdgcn_s_setprio(0); } while (0)
; #define PG8_WAIT_V(n) asm volatile("s_waitcnt vmcnt(" #n ")" ::: "memory")
; #define PG8_BAR __builtin_amdgcn_s_barrier()
; template <class Epi, class Sched, bool ALIGN_EPI = false, bool SP2 = false>
; __device__ __forceinline__ void gemm_phase(PG8_LAS unsigned char* lds, const Gemm g, const Sched& S, const Epi& E) {
;     ...
;         for (int t = 0; t < nt; t += 2) {
;             const bool last = (t == nt - 2);
;             const char* a1 = cA + (size_t)(t + 1) * kstep;
;             const char* a2 = last ? nA : cA + (size_t)(t + 2) * kstep; const char* b2 = last ? nB : cB + (size_t)(t + 2) * kstep;
;             const char* a3 = a2 + kstep; const char* b3 = b2 + kstep;
;             if (last && has_next) S.a_ready(nxt);
;             if constexpr (SP2) {
;             PG8_LDB(B0, 0, 0); PG8_LDB(B1, 0, 1); PG8_SCHED; PG8_LDA(At, 0, 0); PG8_STAGE(PG8_SA(1, 1), a1 + hstep, voffA);
;             PG8_WAIT_V(8); PG8_WAIT_L(0); PG8_BAR; PG8_MMA(0, 0, At, B0); PG8_MMA(0, 1, At, B1); PG8_BAR; PG8_SCHED;
;             PG8_LDA(At, 0, 1); PG8_STAGE(PG8_SB(0, 0), b2, voffB); PG8_STAGE(PG8_SB(0, 1), b2 + hstep, voffB); PG8_STAGE(PG8_SA(0, 0), a2, voffA);
;             PG8_WAIT_V(8); PG8_WAIT_L(0); PG8_BAR; PG8_MMA(1, 0, At, B0); PG8_MMA(1, 1, At, B1); PG8_BAR; PG8_SCHED;
.LBB0_1255:
	s_sub_i32 vcc_hi, 0x29000, s100
	s_sub_i32 vcc_hi, vcc_hi, s101
	s_add_u32 s38, s26, 0x100
	s_addc_u32 s39, s27, 0
	s_add_i32 s64, 0, 0x10000
	s_cmp_eq_u32 s63, 28
	s_cselect_b32 s43, s15, s39
	s_cselect_b32 s42, s59, s38
	s_cselect_b32 s41, s11, s62
	s_cselect_b32 s40, s60, s61
	s_add_i32 s65, 0, 0x14000
	v_add_u32_e32 v148, s64, v171
	v_add_u32_e32 v164, s65, v171
	ds_read_b128 v[136:139], v148
	ds_read_b128 v[140:143], v148 offset:1024
	ds_read_b128 v[144:147], v148 offset:2048
	ds_read_b128 v[148:151], v148 offset:3072
	ds_read_b128 v[152:155], v164
	ds_read_b128 v[156:159], v164 offset:1024
	ds_read_b128 v[160:163], v164 offset:2048
	ds_read_b128 v[164:167], v164 offset:3072
	v_lshl_add_u64 v[168:169], s[26:27], 0, v[132:133]
	s_add_i32 m0, s23, 0xc000
	v_add_u32_e32 v250, s100, v173
	ds_read_b128 v[174:177], v250
	ds_read_b128 v[178:181], v250 offset:1024
	ds_read_b128 v[182:185], v250 offset:2048
	ds_read_b128 v[186:189], v250 offset:3072
	ds_read_b128 v[190:193], v250 offset:4096
	ds_read_b128 v[202:205], v250 offset:5120
	ds_read_b128 v[206:209], v250 offset:6144
	ds_read_b128 v[210:213], v250 offset:7168
	global_load_lds_dwordx4 v[168:169], off
	v_lshl_add_u64 v[168:169], s[26:27], 0, v[134:135]
	s_add_i32 m0, s23, 0xe000
	s_nop 0
	global_load_lds_dwordx4 v[168:169], off
	v_lshl_add_u64 v[238:239], s[42:43], 0, v[0:1]
	v_lshl_add_u64 v[240:241], s[42:43], 0, v[130:131]
	s_add_i32 m0, vcc_hi, s23
	s_nop 0
	global_load_lds_dwordx4 v[238:239], off
	s_add_i32 m0, m0, 0x2000
	s_nop 0
	global_load_lds_dwordx4 v[240:241], off
	s_waitcnt vmcnt(10)
	s_waitcnt lgkmcnt(0)
	s_setprio 1
	s_waitcnt lgkmcnt(0)
	v_mfma_f32_16x16x32_bf16 v[98:101], v[136:139], v[174:177], v[98:101]
	v_mfma_f32_16x16x32_bf16 v[78:81], v[144:147], v[174:177], v[78:81]
	v_mfma_f32_16x16x32_bf16 v[102:105], v[136:139], v[182:185], v[102:105]
	v_mfma_f32_16x16x32_bf16 v[74:77], v[144:147], v[182:185], v[74:77]
	s_barrier
	v_mfma_f32_16x16x32_bf16 v[106:109], v[136:139], v[190:193], v[106:109]
	v_mfma_f32_16x16x32_bf16 v[70:73], v[144:147], v[190:193], v[70:73]
	v_mfma_f32_16x16x32_bf16 v[110:113], v[136:139], v[206:209], v[110:113]
	v_mfma_f32_16x16x32_bf16 v[66:69], v[144:147], v[206:209], v[66:69]
	v_mfma_f32_16x16x32_bf16 v[98:101], v[140:143], v[178:181], v[98:101]
	v_mfma_f32_16x16x32_bf16 v[78:81], v[148:151], v[178:181], v[78:81]
	v_mfma_f32_16x16x32_bf16 v[102:105], v[140:143], v[186:189], v[102:105]
	v_mfma_f32_16x16x32_bf16 v[74:77], v[148:151], v[186:189], v[74:77]
	v_mfma_f32_16x16x32_bf16 v[106:109], v[140:143], v[202:205], v[106:109]
	v_mfma_f32_16x16x32_bf16 v[70:73], v[148:151], v[202:205], v[70:73]
	v_mfma_f32_16x16x32_bf16 v[110:113], v[140:143], v[210:213], v[110:113]
	v_mfma_f32_16x16x32_bf16 v[66:69], v[148:151], v[210:213], v[66:69]
	s_setprio 0
	s_setprio 1
	v_mfma_f32_16x16x32_bf16 v[46:49], v[152:155], v[174:177], v[46:49]
	v_mfma_f32_16x16x32_bf16 v[2:5], v[160:163], v[174:177], v[2:5]
	v_mfma_f32_16x16x32_bf16 v[42:45], v[152:155], v[182:185], v[42:45]
	v_mfma_f32_16x16x32_bf16 v[6:9], v[160:163], v[182:185], v[6:9]
	v_mfma_f32_16x16x32_bf16 v[38:41], v[152:155], v[190:193], v[38:41]
	v_mfma_f32_16x16x32_bf16 v[10:13], v[160:163], v[190:193], v[10:13]
	v_mfma_f32_16x16x32_bf16 v[34:37], v[152:155], v[206:209], v[34:37]
	v_mfma_f32_16x16x32_bf16 v[14:17], v[160:163], v[206:209], v[14:17]
	v_mfma_f32_16x16x32_bf16 v[46:49], v[156:159], v[178:181], v[46:49]
	v_mfma_f32_16x16x32_bf16 v[2:5], v[164:167], v[178:181], v[2:5]
	v_mfma_f32_16x16x32_bf16 v[42:45], v[156:159], v[186:189], v[42:45]
	v_mfma_f32_16x16x32_bf16 v[6:9], v[164:167], v[186:189], v[6:9]
	v_mfma_f32_16x16x32_bf16 v[38:41], v[156:159], v[202:205], v[38:41]
	v_mfma_f32_16x16x32_bf16 v[10:13], v[164:167], v[202:205], v[10:13]
	v_mfma_f32_16x16x32_bf16 v[34:37], v[156:159], v[210:213], v[34:37]
	v_mfma_f32_16x16x32_bf16 v[14:17], v[164:167], v[210:213], v[14:17]
	s_setprio 0
	s_barrier
	s_add_i32 s26, s64, s44
	v_lshl_add_u64 v[168:169], s[40:41], 0, v[0:1]
	s_mov_b32 m0, s26
	ds_read_b128 v[174:177], v173 offset:16384
	ds_read_b128 v[178:181], v173 offset:17408
	ds_read_b128 v[182:185], v173 offset:18432
	ds_read_b128 v[186:189], v173 offset:19456
	ds_read_b128 v[190:193], v173 offset:20480
	ds_read_b128 v[202:205], v173 offset:21504
	ds_read_b128 v[206:209], v173 offset:22528
	ds_read_b128 v[210:213], v173 offset:23552
	global_load_lds_dwordx4 v[168:169], off
	s_add_i32 m0, s26, 0x2000
	s_add_u32 s26, s40, 0x80000
	v_lshl_add_u64 v[194:195], s[40:41], 0, v[130:131]
	s_addc_u32 s27, s41, 0
	s_add_i32 s64, s65, s44
	global_load_lds_dwordx4 v[194:195], off
	v_lshl_add_u64 v[214:215], s[26:27], 0, v[0:1]
	s_mov_b32 m0, s64
	global_load_lds_dwordx4 v[214:215], off
	v_lshl_add_u64 v[214:215], s[26:27], 0, v[130:131]
	s_add_i32 m0, s64, 0x2000
	s_nop 0
	global_load_lds_dwordx4 v[214:215], off
	s_waitcnt vmcnt(8)
	s_waitcnt lgkmcnt(0)
	s_setprio 1
	s_waitcnt lgkmcnt(0)
	v_mfma_f32_16x16x32_bf16 v[114:117], v[136:139], v[174:177], v[114:117]
	v_mfma_f32_16x16x32_bf16 v[94:97], v[144:147], v[174:177], v[94:97]
	v_mfma_f32_16x16x32_bf16 v[118:121], v[136:139], v[182:185], v[118:121]
	v_mfma_f32_16x16x32_bf16 v[90:93], v[144:147], v[182:185], v[90:93]
	s_barrier
; #define PG8_STAGE(bufoff, gbase, voff) do { _Pragma("unroll") for (int _i = 0; _i < 2; ++_i) \
;         __builtin_amdgcn_global_load_lds((const unsigned*)((const char*)(gbase) + (voff)[_i]), (PG8_LAS unsigned*)(lds + (bufoff) + ldsw + _i * 8192), 16, 0, 0); } while (0)
; #define PG8_LDA(dst, b, h) do { _Pragma("unroll") for (int m = 0; m < 4; ++m) _Pragma("unroll") for (int k = 0; k < 2; ++k) dst[m][k] = *(const PG8_LAS bf16x8*)(lds + PG8_SA(b, h) + aoff + m * 2048 + k * 1024); } while (0)
; #define PG8_LDB(dst, b, h) do { _Pragma("unroll") for (int n = 0; n < 2; ++n) _Pragma("unroll") for (int k = 0; k < 2; ++k) dst[n][k] = *(const PG8_LAS bf16x8*)(lds + PG8_SB(b, h) + boff + n * 2048 + k * 1024); } while (0)
; #define PG8_MMA(ai, bj, At, Bt) do { __builtin_amdgcn_s_setprio(1); _Pragma("unroll") for (int m = 0; m < 4; ++m) _Pragma("unroll") for (int n = 0; n < 2; ++n) _Pragma("unroll") for (int k = 0; k < 2; ++k) \
;         acc[ai][bj][m][n] = __builtin_amdgcn_mfma_f32_16x16x32_bf16(Bt[n][k], At[m][k], acc[ai][bj][m][n], 0, 0, 0); __builtin_amdgcn_s_setprio(0); } while (0)
; #define PG8_WAIT_V(n) asm volatile("s_waitcnt vmcnt(" #n ")" ::: "memory")
; #define PG8_WAIT_L(n) asm volatile("s_waitcnt lgkmcnt(" #n ")" ::: "memory")
; #define PG8_BAR __builtin_amdgcn_s_barrier()
; #define PG8_SCHED __builtin_amdgcn_sched_barrier(0)
; template <class Epi, class Sched, bool ALIGN_EPI = false, bool SP2 = false>
; __device__ __forceinline__ void gemm_phase(PG8_LAS unsigned char* lds, const Gemm g, const Sched& S, const Epi& E) {
;     ...
;             PG8_WAIT_V(8); PG8_WAIT_L(0); PG8_BAR; PG8_MMA(0, 0, At, B0); PG8_MMA(0, 1, At, B1); PG8_BAR; PG8_SCHED;
;             PG8_LDA(At, 0, 1); PG8_STAGE(PG8_SB(0, 0), b2, voffB); PG8_STAGE(PG8_SB(0, 1), b2 + hstep, voffB); PG8_STAGE(PG8_SA(0, 0), a2, voffA);
;             PG8_WAIT_V(8); PG8_WAIT_L(0); PG8_BAR; PG8_MMA(1, 0, At, B0); PG8_MMA(1, 1, At, B1); PG8_BAR; PG8_SCHED;
;             PG8_LDB(B0, 1, 0); PG8_LDB(B1, 1, 1); PG8_SCHED; PG8_LDA(At, 1, 0); PG8_STAGE(PG8_SA(0, 1), a2 + hstep, voffA);
;             PG8_WAIT_V(8); PG8_WAIT_L(0); PG8_BAR; PG8_MMA(0, 0, At, B0); PG8_MMA(0, 1, At, B1); PG8_BAR; PG8_SCHED;
	v_mfma_f32_16x16x32_bf16 v[122:125], v[136:139], v[190:193], v[122:125]
	v_mfma_f32_16x16x32_bf16 v[86:89], v[144:147], v[190:193], v[86:89]
	v_mfma_f32_16x16x32_bf16 v[126:129], v[136:139], v[206:209], v[126:129]
	v_mfma_f32_16x16x32_bf16 v[82:85], v[144:147], v[206:209], v[82:85]
	v_mfma_f32_16x16x32_bf16 v[114:117], v[140:143], v[178:181], v[114:117]
	v_mfma_f32_16x16x32_bf16 v[94:97], v[148:151], v[178:181], v[94:97]
	v_mfma_f32_16x16x32_bf16 v[118:121], v[140:143], v[186:189], v[118:121]
	v_mfma_f32_16x16x32_bf16 v[90:93], v[148:151], v[186:189], v[90:93]
	v_mfma_f32_16x16x32_bf16 v[122:125], v[140:143], v[202:205], v[122:125]
	v_mfma_f32_16x16x32_bf16 v[86:89], v[148:151], v[202:205], v[86:89]
	v_mfma_f32_16x16x32_bf16 v[126:129], v[140:143], v[210:213], v[126:129]
	v_mfma_f32_16x16x32_bf16 v[82:85], v[148:151], v[210:213], v[82:85]
	s_setprio 0
	s_setprio 1
	v_mfma_f32_16x16x32_bf16 v[62:65], v[152:155], v[174:177], v[62:65]
	v_mfma_f32_16x16x32_bf16 v[18:21], v[160:163], v[174:177], v[18:21]
	v_mfma_f32_16x16x32_bf16 v[58:61], v[152:155], v[182:185], v[58:61]
	v_mfma_f32_16x16x32_bf16 v[22:25], v[160:163], v[182:185], v[22:25]
	v_mfma_f32_16x16x32_bf16 v[54:57], v[152:155], v[190:193], v[54:57]
	v_mfma_f32_16x16x32_bf16 v[26:29], v[160:163], v[190:193], v[26:29]
	v_mfma_f32_16x16x32_bf16 v[50:53], v[152:155], v[206:209], v[50:53]
	v_mfma_f32_16x16x32_bf16 v[30:33], v[160:163], v[206:209], v[30:33]
	v_mfma_f32_16x16x32_bf16 v[62:65], v[156:159], v[178:181], v[62:65]
	v_mfma_f32_16x16x32_bf16 v[18:21], v[164:167], v[178:181], v[18:21]
	v_mfma_f32_16x16x32_bf16 v[58:61], v[156:159], v[186:189], v[58:61]
	v_mfma_f32_16x16x32_bf16 v[22:25], v[164:167], v[186:189], v[22:25]
	v_mfma_f32_16x16x32_bf16 v[54:57], v[156:159], v[202:205], v[54:57]
	v_mfma_f32_16x16x32_bf16 v[26:29], v[164:167], v[202:205], v[26:29]
	v_mfma_f32_16x16x32_bf16 v[50:53], v[156:159], v[210:213], v[50:53]
	v_mfma_f32_16x16x32_bf16 v[30:33], v[164:167], v[210:213], v[30:33]
	s_setprio 0
	s_barrier
	s_add_i32 s64, 0, 0x18000
	s_add_i32 s65, 0, 0x1c000
	v_add_u32_e32 v148, s64, v171
	v_add_u32_e32 v164, s65, v171
	ds_read_b128 v[136:139], v148
	ds_read_b128 v[140:143], v148 offset:1024
	ds_read_b128 v[144:147], v148 offset:2048
	ds_read_b128 v[148:151], v148 offset:3072
	ds_read_b128 v[152:155], v164
	ds_read_b128 v[156:159], v164 offset:1024
	ds_read_b128 v[160:163], v164 offset:2048
	ds_read_b128 v[164:167], v164 offset:3072
	s_add_u32 s26, s42, 0x80000
	s_addc_u32 s27, s43, 0
	s_mov_b32 m0, s46
	v_lshl_add_u64 v[218:219], s[26:27], 0, v[0:1]
	v_add_u32_e32 v250, s101, v173
	ds_read_b128 v[174:177], v250
	ds_read_b128 v[178:181], v250 offset:1024
	ds_read_b128 v[182:185], v250 offset:2048
	ds_read_b128 v[186:189], v250 offset:3072
	ds_read_b128 v[190:193], v250 offset:4096
	ds_read_b128 v[202:205], v250 offset:5120
	ds_read_b128 v[206:209], v250 offset:6144
	ds_read_b128 v[210:213], v250 offset:7168
	global_load_lds_dwordx4 v[218:219], off
	v_lshl_add_u64 v[218:219], s[26:27], 0, v[130:131]
	s_mov_b32 m0, s47
	s_nop 0
	global_load_lds_dwordx4 v[218:219], off
	v_lshl_add_u64 v[242:243], v[238:239], 0, s[96:97]
	v_lshl_add_u64 v[244:245], v[240:241], 0, s[96:97]
	s_add_i32 m0, s100, s23
	s_nop 0
	global_load_lds_dwordx4 v[242:243], off
	s_add_i32 m0, m0, 0x2000
	s_nop 0
	global_load_lds_dwordx4 v[244:245], off
	s_waitcnt vmcnt(10)
	s_waitcnt lgkmcnt(0)
	s_setprio 1
	s_waitcnt lgkmcnt(0)
	v_mfma_f32_16x16x32_bf16 v[98:101], v[136:139], v[174:177], v[98:101]
	v_mfma_f32_16x16x32_bf16 v[78:81], v[144:147], v[174:177], v[78:81]
	v_mfma_f32_16x16x32_bf16 v[102:105], v[136:139], v[182:185], v[102:105]
	v_mfma_f32_16x16x32_bf16 v[74:77], v[144:147], v[182:185], v[74:77]
	s_barrier
; #define PG8_STAGE(bufoff, gbase, voff) do { _Pragma("unroll") for (int _i = 0; _i < 2; ++_i) \
;         __builtin_amdgcn_global_load_lds((const unsigned*)((const char*)(gbase) + (voff)[_i]), (PG8_LAS unsigned*)(lds + (bufoff) + ldsw + _i * 8192), 16, 0, 0); } while (0)
; #define PG8_LDA(dst, b, h) do { _Pragma("unroll") for (int m = 0; m < 4; ++m) _Pragma("unroll") for (int k = 0; k < 2; ++k) dst[m][k] = *(const PG8_LAS bf16x8*)(lds + PG8_SA(b, h) + aoff + m * 2048 + k * 1024); } while (0)
; #define PG8_LDB(dst, b, h) do { _Pragma("unroll") for (int n = 0; n < 2; ++n) _Pragma("unroll") for (int k = 0; k < 2; ++k) dst[n][k] = *(const PG8_LAS bf16x8*)(lds + PG8_SB(b, h) + boff + n * 2048 + k * 1024); } while (0)
; #define PG8_MMA(ai, bj, At, Bt) do { __builtin_amdgcn_s_setprio(1); _Pragma("unroll") for (int m = 0; m < 4; ++m) _Pragma("unroll") for (int n = 0; n < 2; ++n) _Pragma("unroll") for (int k = 0; k < 2; ++k) \
;         acc[ai][bj][m][n] = __builtin_amdgcn_mfma_f32_16x16x32_bf16(Bt[n][k], At[m][k], acc[ai][bj][m][n], 0, 0, 0); __builtin_amdgcn_s_setprio(0); } while (0)
; #define PG8_WAIT_V(n) asm volatile("s_waitcnt vmcnt(" #n ")" ::: "memory")
; #define PG8_WAIT_L(n) asm volatile("s_waitcnt lgkmcnt(" #n ")" ::: "memory")
; template <class Epi, class Sched, bool ALIGN_EPI = false, bool SP2 = false>
; __device__ __forceinline__ void gemm_phase(PG8_LAS unsigned char* lds, const Gemm g, const Sched& S, const Epi& E) {
;     ...
;         for (int t = 0; t < nt; t += 2) {
;             const bool last = (t == nt - 2);
;             const char* a1 = cA + (size_t)(t + 1) * kstep;
;             const char* a2 = last ? nA : cA + (size_t)(t + 2) * kstep; const char* b2 = last ? nB : cB + (size_t)(t + 2) * kstep;
;             const char* a3 = a2 + kstep; const char* b3 = b2 + kstep;
;             if (last && has_next) S.a_ready(nxt);
;     ...
;             PG8_LDB(B0, 1, 0); PG8_LDB(B1, 1, 1); PG8_SCHED; PG8_LDA(At, 1, 0); PG8_STAGE(PG8_SA(0, 1), a2 + hstep, voffA);
;             PG8_WAIT_V(8); PG8_WAIT_L(0); PG8_BAR; PG8_MMA(0, 0, At, B0); PG8_MMA(0, 1, At, B1); PG8_BAR; PG8_SCHED;
;             PG8_LDA(At, 1, 1); PG8_STAGE(PG8_SB(1, 0), b3, voffB); PG8_STAGE(PG8_SB(1, 1), b3 + hstep, voffB); PG8_STAGE(PG8_SA(1, 0), a3, voffA);
;             PG8_WAIT_V(8); PG8_WAIT_L(0); PG8_BAR; PG8_MMA(1, 0, At, B0); PG8_MMA(1, 1, At, B1); PG8_BAR; PG8_SCHED;
	v_mfma_f32_16x16x32_bf16 v[106:109], v[136:139], v[190:193], v[106:109]
	v_mfma_f32_16x16x32_bf16 v[70:73], v[144:147], v[190:193], v[70:73]
	v_mfma_f32_16x16x32_bf16 v[110:113], v[136:139], v[206:209], v[110:113]
	v_mfma_f32_16x16x32_bf16 v[66:69], v[144:147], v[206:209], v[66:69]
	v_mfma_f32_16x16x32_bf16 v[98:101], v[140:143], v[178:181], v[98:101]
	v_mfma_f32_16x16x32_bf16 v[78:81], v[148:151], v[178:181], v[78:81]
	v_mfma_f32_16x16x32_bf16 v[102:105], v[140:143], v[186:189], v[102:105]
	v_mfma_f32_16x16x32_bf16 v[74:77], v[148:151], v[186:189], v[74:77]
	v_mfma_f32_16x16x32_bf16 v[106:109], v[140:143], v[202:205], v[106:109]
	v_mfma_f32_16x16x32_bf16 v[70:73], v[148:151], v[202:205], v[70:73]
	v_mfma_f32_16x16x32_bf16 v[110:113], v[140:143], v[210:213], v[110:113]
	v_mfma_f32_16x16x32_bf16 v[66:69], v[148:151], v[210:213], v[66:69]
	s_setprio 0
	s_setprio 1
	v_mfma_f32_16x16x32_bf16 v[46:49], v[152:155], v[174:177], v[46:49]
	v_mfma_f32_16x16x32_bf16 v[2:5], v[160:163], v[174:177], v[2:5]
	v_mfma_f32_16x16x32_bf16 v[42:45], v[152:155], v[182:185], v[42:45]
	v_mfma_f32_16x16x32_bf16 v[6:9], v[160:163], v[182:185], v[6:9]
	v_mfma_f32_16x16x32_bf16 v[38:41], v[152:155], v[190:193], v[38:41]
	v_mfma_f32_16x16x32_bf16 v[10:13], v[160:163], v[190:193], v[10:13]
	v_mfma_f32_16x16x32_bf16 v[34:37], v[152:155], v[206:209], v[34:37]
	v_mfma_f32_16x16x32_bf16 v[14:17], v[160:163], v[206:209], v[14:17]
	v_mfma_f32_16x16x32_bf16 v[46:49], v[156:159], v[178:181], v[46:49]
	v_mfma_f32_16x16x32_bf16 v[2:5], v[164:167], v[178:181], v[2:5]
	v_mfma_f32_16x16x32_bf16 v[42:45], v[156:159], v[186:189], v[42:45]
	v_mfma_f32_16x16x32_bf16 v[6:9], v[164:167], v[186:189], v[6:9]
	v_mfma_f32_16x16x32_bf16 v[38:41], v[156:159], v[202:205], v[38:41]
	v_mfma_f32_16x16x32_bf16 v[10:13], v[164:167], v[202:205], v[10:13]
	v_mfma_f32_16x16x32_bf16 v[34:37], v[156:159], v[210:213], v[34:37]
	v_mfma_f32_16x16x32_bf16 v[14:17], v[164:167], v[210:213], v[14:17]
	s_setprio 0
	s_barrier
	s_add_i32 s26, s64, s44
	v_lshl_add_u64 v[168:169], v[168:169], 0, s[96:97]
	s_mov_b32 m0, s26
	ds_read_b128 v[174:177], v173 offset:49152
	ds_read_b128 v[178:181], v173 offset:50176
	ds_read_b128 v[182:185], v173 offset:51200
	ds_read_b128 v[186:189], v173 offset:52224
	ds_read_b128 v[190:193], v173 offset:53248
	ds_read_b128 v[202:205], v173 offset:54272
	ds_read_b128 v[206:209], v173 offset:55296
	ds_read_b128 v[210:213], v173 offset:56320
	global_load_lds_dwordx4 v[168:169], off
	s_add_i32 m0, s26, 0x2000
	s_add_u32 s26, s40, 0x80080
	v_lshl_add_u64 v[168:169], v[194:195], 0, s[96:97]
	s_addc_u32 s27, s41, 0
	s_add_i32 s40, s65, s44
	global_load_lds_dwordx4 v[168:169], off
	v_lshl_add_u64 v[168:169], s[26:27], 0, v[0:1]
	s_mov_b32 m0, s40
	s_nop 0
	global_load_lds_dwordx4 v[168:169], off
	v_lshl_add_u64 v[168:169], s[26:27], 0, v[130:131]
	s_add_i32 m0, s40, 0x2000
	s_nop 0
	global_load_lds_dwordx4 v[168:169], off
	s_waitcnt vmcnt(8)
	s_waitcnt lgkmcnt(0)
	s_setprio 1
	s_waitcnt lgkmcnt(0)
	v_mfma_f32_16x16x32_bf16 v[114:117], v[136:139], v[174:177], v[114:117]
	v_mfma_f32_16x16x32_bf16 v[94:97], v[144:147], v[174:177], v[94:97]
	v_mfma_f32_16x16x32_bf16 v[118:121], v[136:139], v[182:185], v[118:121]
	v_mfma_f32_16x16x32_bf16 v[90:93], v[144:147], v[182:185], v[90:93]
	s_barrier
	v_mfma_f32_16x16x32_bf16 v[122:125], v[136:139], v[190:193], v[122:125]
	v_mfma_f32_16x16x32_bf16 v[86:89], v[144:147], v[190:193], v[86:89]
	v_mfma_f32_16x16x32_bf16 v[126:129], v[136:139], v[206:209], v[126:129]
	v_mfma_f32_16x16x32_bf16 v[82:85], v[144:147], v[206:209], v[82:85]
	v_mfma_f32_16x16x32_bf16 v[114:117], v[140:143], v[178:181], v[114:117]
	v_mfma_f32_16x16x32_bf16 v[94:97], v[148:151], v[178:181], v[94:97]
	v_mfma_f32_16x16x32_bf16 v[118:121], v[140:143], v[186:189], v[118:121]
	v_mfma_f32_16x16x32_bf16 v[90:93], v[148:151], v[186:189], v[90:93]
	v_mfma_f32_16x16x32_bf16 v[122:125], v[140:143], v[202:205], v[122:125]
	v_mfma_f32_16x16x32_bf16 v[86:89], v[148:151], v[202:205], v[86:89]
	v_mfma_f32_16x16x32_bf16 v[126:129], v[140:143], v[210:213], v[126:129]
	v_mfma_f32_16x16x32_bf16 v[82:85], v[148:151], v[210:213], v[82:85]
	s_setprio 0
	s_setprio 1
	v_mfma_f32_16x16x32_bf16 v[62:65], v[152:155], v[174:177], v[62:65]
	v_mfma_f32_16x16x32_bf16 v[18:21], v[160:163], v[174:177], v[18:21]
	v_mfma_f32_16x16x32_bf16 v[58:61], v[152:155], v[182:185], v[58:61]
	v_mfma_f32_16x16x32_bf16 v[22:25], v[160:163], v[182:185], v[22:25]
	v_mfma_f32_16x16x32_bf16 v[54:57], v[152:155], v[190:193], v[54:57]
	v_mfma_f32_16x16x32_bf16 v[26:29], v[160:163], v[190:193], v[26:29]
	v_mfma_f32_16x16x32_bf16 v[50:53], v[152:155], v[206:209], v[50:53]
	v_mfma_f32_16x16x32_bf16 v[30:33], v[160:163], v[206:209], v[30:33]
	v_mfma_f32_16x16x32_bf16 v[62:65], v[156:159], v[178:181], v[62:65]
	v_mfma_f32_16x16x32_bf16 v[18:21], v[164:167], v[178:181], v[18:21]
	v_mfma_f32_16x16x32_bf16 v[58:61], v[156:159], v[186:189], v[58:61]
	v_mfma_f32_16x16x32_bf16 v[22:25], v[164:167], v[186:189], v[22:25]
	v_mfma_f32_16x16x32_bf16 v[54:57], v[156:159], v[202:205], v[54:57]
	v_mfma_f32_16x16x32_bf16 v[26:29], v[164:167], v[202:205], v[26:29]
	v_mfma_f32_16x16x32_bf16 v[50:53], v[156:159], v[210:213], v[50:53]
	v_mfma_f32_16x16x32_bf16 v[30:33], v[164:167], v[210:213], v[30:33]
	s_setprio 0
	s_barrier
	s_add_i32 s63, s63, 2
	s_mov_b32 s101, s100
	s_mov_b32 s100, vcc_hi
	s_add_u32 s61, s61, 0x100
	s_addc_u32 s62, s62, 0
	s_cmp_gt_u32 s63, 29
	s_mov_b64 s[26:27], s[38:39]
	s_cbranch_scc0 .LBB0_1255
	s_and_b64 vcc, exec, s[8:9]
	s_cbranch_vccz .LBB0_1258
	s_barrier

;     __device__ bool next(int i, pg8::Unit& u) const { const int t = (i >> 2) * G + c; if (t >= ntile) return false; const int br = i & 3; u.pm = br * 65 + (t >> 3); u.pn = br * 8 + (t & 7); return true; }
;     __host__ __device__ bool next(int i, Unit& u) const {
;         const long L = (long)i * G + c; if (L >= nwg) return false;
;         int wgid = (int)L; { const int q = nwg / NXCD, r = nwg % NXCD, xcd = wgid % NXCD, off = wgid / NXCD; wgid = (xcd < r ? xcd * (q + 1) : r * (q + 1) + (xcd - r) * q) + off; }
;         const int nig = WGM * nN, gid = wgid / nig, fm = gid * WGM, gsz = (nM - fm) < WGM ? (nM - fm) : WGM;
;         u.pm = fm + ((wgid % nig) % gsz); u.pn = (wgid % nig) / gsz; return true;
;     }
; template <class Epi, class Sched, bool ALIGN_EPI = false, bool SP2 = false>
; __device__ __forceinline__ void gemm_phase(PG8_LAS unsigned char* lds, const Gemm g, const Sched& S, const Epi& E) {
;     ...
;     Unit cur, nxt; int ui = 0;
;     if (!S.next(0, cur)) return;
.LBB0_1395:
	s_andn2_b64 vcc, exec, s[4:5]
	s_cbranch_vccnz .LBB0_1505
	s_mov_b32 s100, 0
	s_mov_b32 s101, 0x8000
	s_lshr_b32 s31, s30, 8
	s_waitcnt lgkmcnt(0)
	v_readlane_b32 s8, v253, 51
	s_mul_i32 s12, s31, 44
	v_readlane_b32 s9, v253, 52
	s_cmp_lt_i32 s94, s12
	s_cselect_b64 s[4:5], -1, 0
	s_lshr_b32 s68, s12, 3
	v_mov_b32_e32 v0, v197
	s_and_b32 s69, s12, 4
	s_add_i32 s70, s68, 1
	v_mov_b32_e32 v3, v197
	s_cmp_ge_i32 s94, s12
	s_mul_i32 s71, s70, s69
	s_nop 0
	v_readfirstlane_b32 s0, v3
	s_cbranch_scc1 .LBB0_1410
	v_readlane_b32 s7, v253, 21
	s_sub_i32 s6, s7, s69
	s_mul_i32 s6, s6, s68
	s_add_i32 s6, s6, s71
	s_mul_i32 s1, s70, s7
	s_cmp_lt_i32 s7, s69
	s_cselect_b32 s1, s1, s6
	v_readlane_b32 s6, v252, 62
	s_add_i32 s1, s1, s6
	s_mul_hi_i32 s6, s1, 0x2e8ba2e9
	s_lshr_b32 s7, s6, 31
	s_ashr_i32 s6, s6, 6
	s_add_i32 s6, s6, s7
	s_lshl_b32 s7, s6, 3
	s_sub_i32 s10, s31, s7
	s_min_i32 s10, s10, 8
	s_abs_i32 s11, s10
	v_cvt_f32_u32_e32 v0, s11
	s_sub_i32 s15, 0, s11
	s_mulk_i32 s6, 0x160
	s_sub_i32 s1, s1, s6
	v_rcp_iflag_f32_e32 v0, v0
	s_abs_i32 s6, s1
	s_xor_b32 s14, s1, s10
	s_ashr_i32 s14, s14, 31
	v_mul_f32_e32 v0, 0x4f7ffffe, v0
	v_cvt_u32_f32_e32 v0, v0
	s_nop 0
	v_readfirstlane_b32 s16, v0
	s_mul_i32 s15, s15, s16
	s_mul_hi_u32 s15, s16, s15
	s_add_i32 s16, s16, s15
	s_mul_hi_u32 s15, s6, s16
	s_mul_i32 s16, s15, s11
	s_sub_i32 s6, s6, s16
	s_add_i32 s17, s15, 1
	s_sub_i32 s16, s6, s11
	s_cmp_ge_u32 s6, s11
	s_cselect_b32 s15, s17, s15
	s_cselect_b32 s6, s16, s6
	s_add_i32 s16, s15, 1
	s_cmp_ge_u32 s6, s11
	s_cselect_b32 s6, s16, s15
	s_xor_b32 s6, s6, s14
	s_sub_i32 s60, s6, s14
	s_mul_i32 s6, s60, s10
	s_sub_i32 s1, s1, s6
	s_add_i32 s58, s7, s1
	s_andn2_b64 vcc, exec, s[4:5]
	s_cbranch_vccz .LBB0_1411

; #define PG8_STAGE(bufoff, gbase, voff) do { _Pragma("unroll") for (int _i = 0; _i < 2; ++_i) \
;         __builtin_amdgcn_global_load_lds((const unsigned*)((const char*)(gbase) + (voff)[_i]), (PG8_LAS unsigned*)(lds + (bufoff) + ldsw + _i * 8192), 16, 0, 0); } while (0)
; #define PG8_LDA(dst, b, h) do { _Pragma("unroll") for (int m = 0; m < 4; ++m) _Pragma("unroll") for (int k = 0; k < 2; ++k) dst[m][k] = *(const PG8_LAS bf16x8*)(lds + PG8_SA(b, h) + aoff + m * 2048 + k * 1024); } while (0)
; #define PG8_LDB(dst, b, h) do { _Pragma("unroll") for (int n = 0; n < 2; ++n) _Pragma("unroll") for (int k = 0; k < 2; ++k) dst[n][k] = *(const PG8_LAS bf16x8*)(lds + PG8_SB(b, h) + boff + n * 2048 + k * 1024); } while (0)
; #define PG8_MMA(ai, bj, At, Bt) do { __builtin_amdgcn_s_setprio(1); _Pragma("unroll") for (int m = 0; m < 4; ++m) _Pragma("unroll") for (int n = 0; n < 2; ++n) _Pragma("unroll") for (int k = 0; k < 2; ++k) \
;         acc[ai][bj][m][n] = __builtin_amdgcn_mfma_f32_16x16x32_bf16(Bt[n][k], At[m][k], acc[ai][bj][m][n], 0, 0, 0); __builtin_amdgcn_s_setprio(0); } while (0)
; #define PG8_WAIT_V(n) asm volatile("s_waitcnt vmcnt(" #n ")" ::: "memory")
; #define PG8_BAR __builtin_amdgcn_s_barrier()
; template <class Epi, class Sched, bool ALIGN_EPI = false, bool SP2 = false>
; __device__ __forceinline__ void gemm_phase(PG8_LAS unsigned char* lds, const Gemm g, const Sched& S, const Epi& E) {
;     ...
;         for (int t = 0; t < nt; t += 2) {
;             const bool last = (t == nt - 2);
;             const char* a1 = cA + (size_t)(t + 1) * kstep;
;             const char* a2 = last ? nA : cA + (size_t)(t + 2) * kstep; const char* b2 = last ? nB : cB + (size_t)(t + 2) * kstep;
;             const char* a3 = a2 + kstep; const char* b3 = b2 + kstep;
;             if (last && has_next) S.a_ready(nxt);
;             if constexpr (SP2) {
;             PG8_LDB(B0, 0, 0); PG8_LDB(B1, 0, 1); PG8_SCHED; PG8_LDA(At, 0, 0); PG8_STAGE(PG8_SA(1, 1), a1 + hstep, voffA);
;             PG8_WAIT_V(8); PG8_WAIT_L(0); PG8_BAR; PG8_MMA(0, 0, At, B0); PG8_MMA(0, 1, At, B1); PG8_BAR; PG8_SCHED;
;             PG8_LDA(At, 0, 1); PG8_STAGE(PG8_SB(0, 0), b2, voffB); PG8_STAGE(PG8_SB(0, 1), b2 + hstep, voffB); PG8_STAGE(PG8_SA(0, 0), a2, voffA);
;             PG8_WAIT_V(8); PG8_WAIT_L(0); PG8_BAR; PG8_MMA(1, 0, At, B0); PG8_MMA(1, 1, At, B1); PG8_BAR; PG8_SCHED;
.LBB0_1423:
	s_sub_i32 vcc_hi, 0x29000, s100
	s_sub_i32 vcc_hi, vcc_hi, s101
	s_add_u32 s61, s64, 0xfff80080
	s_addc_u32 s62, s65, -1
	s_add_i32 s85, 0, 0x10000
	s_cmp_eq_u32 s59, 28
	s_cselect_b32 s67, s0, s62
	s_cselect_b32 s66, s1, s61
	s_cselect_b32 s63, s28, s53
	s_cselect_b32 s62, s29, s51
	s_add_i32 s61, 0, 0x14000
	v_add_u32_e32 v142, s85, v169
	v_add_u32_e32 v158, s61, v169
	ds_read_b128 v[130:133], v142
	ds_read_b128 v[134:137], v142 offset:1024
	ds_read_b128 v[138:141], v142 offset:2048
	ds_read_b128 v[142:145], v142 offset:3072
	ds_read_b128 v[146:149], v158
	ds_read_b128 v[150:153], v158 offset:1024
	ds_read_b128 v[154:157], v158 offset:2048
	ds_read_b128 v[158:161], v158 offset:3072
	v_lshl_add_u64 v[202:203], s[64:65], 0, v[172:173]
	s_add_i32 m0, s77, 0xc000
	v_add_u32_e32 v250, s100, v208
	ds_read_b128 v[176:179], v250
	ds_read_b128 v[180:183], v250 offset:1024
	ds_read_b128 v[184:187], v250 offset:2048
	ds_read_b128 v[188:191], v250 offset:3072
	ds_read_b128 v[192:195], v250 offset:4096
	ds_read_b128 v[210:213], v250 offset:5120
	ds_read_b128 v[214:217], v250 offset:6144
	ds_read_b128 v[218:221], v250 offset:7168
	global_load_lds_dwordx4 v[202:203], off
	v_lshl_add_u64 v[202:203], s[64:65], 0, v[174:175]
	s_add_i32 m0, s77, 0xe000
	s_nop 0
	global_load_lds_dwordx4 v[202:203], off
	v_lshl_add_u64 v[244:245], s[66:67], 0, v[162:163]
	v_lshl_add_u64 v[246:247], s[66:67], 0, v[164:165]
	s_add_i32 m0, vcc_hi, s77
	s_nop 0
	global_load_lds_dwordx4 v[244:245], off
	s_add_i32 m0, m0, 0x2000
	s_nop 0
	global_load_lds_dwordx4 v[246:247], off
	s_waitcnt vmcnt(10)
	s_waitcnt lgkmcnt(0)
	s_setprio 1
	s_waitcnt lgkmcnt(0)
	v_mfma_f32_16x16x32_bf16 v[122:125], v[130:133], v[176:179], v[122:125]
	v_mfma_f32_16x16x32_bf16 v[58:61], v[138:141], v[176:179], v[58:61]
	v_mfma_f32_16x16x32_bf16 v[114:117], v[130:133], v[184:187], v[114:117]
	v_mfma_f32_16x16x32_bf16 v[50:53], v[138:141], v[184:187], v[50:53]
	s_barrier
	v_mfma_f32_16x16x32_bf16 v[106:109], v[130:133], v[192:195], v[106:109]
	v_mfma_f32_16x16x32_bf16 v[42:45], v[138:141], v[192:195], v[42:45]
	v_mfma_f32_16x16x32_bf16 v[98:101], v[130:133], v[214:217], v[98:101]
	v_mfma_f32_16x16x32_bf16 v[34:37], v[138:141], v[214:217], v[34:37]
	v_mfma_f32_16x16x32_bf16 v[122:125], v[134:137], v[180:183], v[122:125]
	v_mfma_f32_16x16x32_bf16 v[58:61], v[142:145], v[180:183], v[58:61]
	v_mfma_f32_16x16x32_bf16 v[114:117], v[134:137], v[188:191], v[114:117]
	v_mfma_f32_16x16x32_bf16 v[50:53], v[142:145], v[188:191], v[50:53]
	v_mfma_f32_16x16x32_bf16 v[106:109], v[134:137], v[210:213], v[106:109]
	v_mfma_f32_16x16x32_bf16 v[42:45], v[142:145], v[210:213], v[42:45]
	v_mfma_f32_16x16x32_bf16 v[98:101], v[134:137], v[218:221], v[98:101]
	v_mfma_f32_16x16x32_bf16 v[34:37], v[142:145], v[218:221], v[34:37]
	s_setprio 0
	s_setprio 1
	v_mfma_f32_16x16x32_bf16 v[126:129], v[146:149], v[176:179], v[126:129]
	v_mfma_f32_16x16x32_bf16 v[62:65], v[154:157], v[176:179], v[62:65]
	v_mfma_f32_16x16x32_bf16 v[118:121], v[146:149], v[184:187], v[118:121]
	v_mfma_f32_16x16x32_bf16 v[54:57], v[154:157], v[184:187], v[54:57]
	v_mfma_f32_16x16x32_bf16 v[110:113], v[146:149], v[192:195], v[110:113]
	v_mfma_f32_16x16x32_bf16 v[46:49], v[154:157], v[192:195], v[46:49]
	v_mfma_f32_16x16x32_bf16 v[102:105], v[146:149], v[214:217], v[102:105]
	v_mfma_f32_16x16x32_bf16 v[38:41], v[154:157], v[214:217], v[38:41]
	v_mfma_f32_16x16x32_bf16 v[126:129], v[150:153], v[180:183], v[126:129]
	v_mfma_f32_16x16x32_bf16 v[62:65], v[158:161], v[180:183], v[62:65]
	v_mfma_f32_16x16x32_bf16 v[118:121], v[150:153], v[188:191], v[118:121]
	v_mfma_f32_16x16x32_bf16 v[54:57], v[158:161], v[188:191], v[54:57]
	v_mfma_f32_16x16x32_bf16 v[110:113], v[150:153], v[210:213], v[110:113]
	v_mfma_f32_16x16x32_bf16 v[46:49], v[158:161], v[210:213], v[46:49]
	v_mfma_f32_16x16x32_bf16 v[102:105], v[150:153], v[218:221], v[102:105]
	v_mfma_f32_16x16x32_bf16 v[38:41], v[158:161], v[218:221], v[38:41]
	s_setprio 0
	s_barrier
	s_add_i32 s85, s85, s76
	v_lshl_add_u64 v[202:203], s[62:63], 0, v[0:1]
	s_mov_b32 m0, s85
	ds_read_b128 v[176:179], v208 offset:16384
	ds_read_b128 v[180:183], v208 offset:17408
	ds_read_b128 v[184:187], v208 offset:18432
	ds_read_b128 v[188:191], v208 offset:19456
	ds_read_b128 v[192:195], v208 offset:20480
	ds_read_b128 v[210:213], v208 offset:21504
	ds_read_b128 v[214:217], v208 offset:22528
	ds_read_b128 v[218:221], v208 offset:23552
	global_load_lds_dwordx4 v[202:203], off
	s_add_i32 m0, s85, 0x2000
	s_add_u32 s86, s62, 0x80000
	v_lshl_add_u64 v[230:231], s[62:63], 0, v[166:167]
	s_addc_u32 s87, s63, 0
	s_add_i32 s61, s61, s76
	global_load_lds_dwordx4 v[230:231], off
	v_lshl_add_u64 v[238:239], s[86:87], 0, v[0:1]
	s_mov_b32 m0, s61
	global_load_lds_dwordx4 v[238:239], off
	v_lshl_add_u64 v[238:239], s[86:87], 0, v[166:167]
	s_add_i32 m0, s61, 0x2000
	s_nop 0
	global_load_lds_dwordx4 v[238:239], off
	s_waitcnt vmcnt(8)
	s_waitcnt lgkmcnt(0)
	s_setprio 1
	s_waitcnt lgkmcnt(0)
	v_mfma_f32_16x16x32_bf16 v[90:93], v[130:133], v[176:179], v[90:93]
	v_mfma_f32_16x16x32_bf16 v[26:29], v[138:141], v[176:179], v[26:29]
	v_mfma_f32_16x16x32_bf16 v[82:85], v[130:133], v[184:187], v[82:85]
	v_mfma_f32_16x16x32_bf16 v[18:21], v[138:141], v[184:187], v[18:21]
	s_barrier
; #define PG8_STAGE(bufoff, gbase, voff) do { _Pragma("unroll") for (int _i = 0; _i < 2; ++_i) \
;         __builtin_amdgcn_global_load_lds((const unsigned*)((const char*)(gbase) + (voff)[_i]), (PG8_LAS unsigned*)(lds + (bufoff) + ldsw + _i * 8192), 16, 0, 0); } while (0)
; #define PG8_LDA(dst, b, h) do { _Pragma("unroll") for (int m = 0; m < 4; ++m) _Pragma("unroll") for (int k = 0; k < 2; ++k) dst[m][k] = *(const PG8_LAS bf16x8*)(lds + PG8_SA(b, h) + aoff + m * 2048 + k * 1024); } while (0)
; #define PG8_LDB(dst, b, h) do { _Pragma("unroll") for (int n = 0; n < 2; ++n) _Pragma("unroll") for (int k = 0; k < 2; ++k) dst[n][k] = *(const PG8_LAS bf16x8*)(lds + PG8_SB(b, h) + boff + n * 2048 + k * 1024); } while (0)
; #define PG8_MMA(ai, bj, At, Bt) do { __builtin_amdgcn_s_setprio(1); _Pragma("unroll") for (int m = 0; m < 4; ++m) _Pragma("unroll") for (int n = 0; n < 2; ++n) _Pragma("unroll") for (int k = 0; k < 2; ++k) \
;         acc[ai][bj][m][n] = __builtin_amdgcn_mfma_f32_16x16x32_bf16(Bt[n][k], At[m][k], acc[ai][bj][m][n], 0, 0, 0); __builtin_amdgcn_s_setprio(0); } while (0)
; #define PG8_WAIT_V(n) asm volatile("s_waitcnt vmcnt(" #n ")" ::: "memory")
; #define PG8_WAIT_L(n) asm volatile("s_waitcnt lgkmcnt(" #n ")" ::: "memory")
; #define PG8_BAR __builtin_amdgcn_s_barrier()
; #define PG8_SCHED __builtin_amdgcn_sched_barrier(0)
; template <class Epi, class Sched, bool ALIGN_EPI = false, bool SP2 = false>
; __device__ __forceinline__ void gemm_phase(PG8_LAS unsigned char* lds, const Gemm g, const Sched& S, const Epi& E) {
;     ...
;             PG8_WAIT_V(8); PG8_WAIT_L(0); PG8_BAR; PG8_MMA(0, 0, At, B0); PG8_MMA(0, 1, At, B1); PG8_BAR; PG8_SCHED;
;             PG8_LDA(At, 0, 1); PG8_STAGE(PG8_SB(0, 0), b2, voffB); PG8_STAGE(PG8_SB(0, 1), b2 + hstep, voffB); PG8_STAGE(PG8_SA(0, 0), a2, voffA);
;             PG8_WAIT_V(8); PG8_WAIT_L(0); PG8_BAR; PG8_MMA(1, 0, At, B0); PG8_MMA(1, 1, At, B1); PG8_BAR; PG8_SCHED;
;             PG8_LDB(B0, 1, 0); PG8_LDB(B1, 1, 1); PG8_SCHED; PG8_LDA(At, 1, 0); PG8_STAGE(PG8_SA(0, 1), a2 + hstep, voffA);
;             PG8_WAIT_V(8); PG8_WAIT_L(0); PG8_BAR; PG8_MMA(0, 0, At, B0); PG8_MMA(0, 1, At, B1); PG8_BAR; PG8_SCHED;
	v_mfma_f32_16x16x32_bf16 v[74:77], v[130:133], v[192:195], v[74:77]
	v_mfma_f32_16x16x32_bf16 v[10:13], v[138:141], v[192:195], v[10:13]
	v_mfma_f32_16x16x32_bf16 v[66:69], v[130:133], v[214:217], v[66:69]
	v_mfma_f32_16x16x32_bf16 v[2:5], v[138:141], v[214:217], v[2:5]
	v_mfma_f32_16x16x32_bf16 v[90:93], v[134:137], v[180:183], v[90:93]
	v_mfma_f32_16x16x32_bf16 v[26:29], v[142:145], v[180:183], v[26:29]
	v_mfma_f32_16x16x32_bf16 v[82:85], v[134:137], v[188:191], v[82:85]
	v_mfma_f32_16x16x32_bf16 v[18:21], v[142:145], v[188:191], v[18:21]
	v_mfma_f32_16x16x32_bf16 v[74:77], v[134:137], v[210:213], v[74:77]
	v_mfma_f32_16x16x32_bf16 v[10:13], v[142:145], v[210:213], v[10:13]
	v_mfma_f32_16x16x32_bf16 v[66:69], v[134:137], v[218:221], v[66:69]
	v_mfma_f32_16x16x32_bf16 v[2:5], v[142:145], v[218:221], v[2:5]
	s_setprio 0
	s_setprio 1
	v_mfma_f32_16x16x32_bf16 v[94:97], v[146:149], v[176:179], v[94:97]
	v_mfma_f32_16x16x32_bf16 v[30:33], v[154:157], v[176:179], v[30:33]
	v_mfma_f32_16x16x32_bf16 v[86:89], v[146:149], v[184:187], v[86:89]
	v_mfma_f32_16x16x32_bf16 v[22:25], v[154:157], v[184:187], v[22:25]
	v_mfma_f32_16x16x32_bf16 v[78:81], v[146:149], v[192:195], v[78:81]
	v_mfma_f32_16x16x32_bf16 v[14:17], v[154:157], v[192:195], v[14:17]
	v_mfma_f32_16x16x32_bf16 v[70:73], v[146:149], v[214:217], v[70:73]
	v_mfma_f32_16x16x32_bf16 v[6:9], v[154:157], v[214:217], v[6:9]
	v_mfma_f32_16x16x32_bf16 v[94:97], v[150:153], v[180:183], v[94:97]
	v_mfma_f32_16x16x32_bf16 v[30:33], v[158:161], v[180:183], v[30:33]
	v_mfma_f32_16x16x32_bf16 v[86:89], v[150:153], v[188:191], v[86:89]
	v_mfma_f32_16x16x32_bf16 v[22:25], v[158:161], v[188:191], v[22:25]
	v_mfma_f32_16x16x32_bf16 v[78:81], v[150:153], v[210:213], v[78:81]
	v_mfma_f32_16x16x32_bf16 v[14:17], v[158:161], v[210:213], v[14:17]
	v_mfma_f32_16x16x32_bf16 v[70:73], v[150:153], v[218:221], v[70:73]
	v_mfma_f32_16x16x32_bf16 v[6:9], v[158:161], v[218:221], v[6:9]
	s_setprio 0
	s_barrier
	s_add_i32 s61, 0, 0x18000
	s_add_i32 s85, 0, 0x1c000
	v_add_u32_e32 v142, s61, v169
	v_add_u32_e32 v158, s85, v169
	ds_read_b128 v[130:133], v142
	ds_read_b128 v[134:137], v142 offset:1024
	ds_read_b128 v[138:141], v142 offset:2048
	ds_read_b128 v[142:145], v142 offset:3072
	ds_read_b128 v[146:149], v158
	ds_read_b128 v[150:153], v158 offset:1024
	ds_read_b128 v[154:157], v158 offset:2048
	ds_read_b128 v[158:161], v158 offset:3072
	s_add_u32 s66, s66, 0x80000
	s_addc_u32 s67, s67, 0
	s_mov_b32 m0, s79
	v_lshl_add_u64 v[242:243], s[66:67], 0, v[162:163]
	v_add_u32_e32 v250, s101, v208
	ds_read_b128 v[176:179], v250
	ds_read_b128 v[180:183], v250 offset:1024
	ds_read_b128 v[184:187], v250 offset:2048
	ds_read_b128 v[188:191], v250 offset:3072
	ds_read_b128 v[192:195], v250 offset:4096
	ds_read_b128 v[210:213], v250 offset:5120
	ds_read_b128 v[214:217], v250 offset:6144
	ds_read_b128 v[218:221], v250 offset:7168
	global_load_lds_dwordx4 v[242:243], off
	v_lshl_add_u64 v[242:243], s[66:67], 0, v[164:165]
	s_mov_b32 m0, s80
	s_nop 0
	global_load_lds_dwordx4 v[242:243], off
	v_lshl_add_u64 v[248:249], v[244:245], 0, s[96:97]
	v_lshl_add_u64 v[242:243], v[246:247], 0, s[96:97]
	s_add_i32 m0, s100, s77
	s_nop 0
	global_load_lds_dwordx4 v[248:249], off
	s_add_i32 m0, m0, 0x2000
	s_nop 0
	global_load_lds_dwordx4 v[242:243], off
	s_waitcnt vmcnt(10)
	s_waitcnt lgkmcnt(0)
	s_setprio 1
	s_waitcnt lgkmcnt(0)
	v_mfma_f32_16x16x32_bf16 v[122:125], v[130:133], v[176:179], v[122:125]
	v_mfma_f32_16x16x32_bf16 v[58:61], v[138:141], v[176:179], v[58:61]
	v_mfma_f32_16x16x32_bf16 v[114:117], v[130:133], v[184:187], v[114:117]
	v_mfma_f32_16x16x32_bf16 v[50:53], v[138:141], v[184:187], v[50:53]
	s_barrier
; #define PG8_STAGE(bufoff, gbase, voff) do { _Pragma("unroll") for (int _i = 0; _i < 2; ++_i) \
;         __builtin_amdgcn_global_load_lds((const unsigned*)((const char*)(gbase) + (voff)[_i]), (PG8_LAS unsigned*)(lds + (bufoff) + ldsw + _i * 8192), 16, 0, 0); } while (0)
; #define PG8_LDA(dst, b, h) do { _Pragma("unroll") for (int m = 0; m < 4; ++m) _Pragma("unroll") for (int k = 0; k < 2; ++k) dst[m][k] = *(const PG8_LAS bf16x8*)(lds + PG8_SA(b, h) + aoff + m * 2048 + k * 1024); } while (0)
; #define PG8_LDB(dst, b, h) do { _Pragma("unroll") for (int n = 0; n < 2; ++n) _Pragma("unroll") for (int k = 0; k < 2; ++k) dst[n][k] = *(const PG8_LAS bf16x8*)(lds + PG8_SB(b, h) + boff + n * 2048 + k * 1024); } while (0)
; #define PG8_MMA(ai, bj, At, Bt) do { __builtin_amdgcn_s_setprio(1); _Pragma("unroll") for (int m = 0; m < 4; ++m) _Pragma("unroll") for (int n = 0; n < 2; ++n) _Pragma("unroll") for (int k = 0; k < 2; ++k) \
;         acc[ai][bj][m][n] = __builtin_amdgcn_mfma_f32_16x16x32_bf16(Bt[n][k], At[m][k], acc[ai][bj][m][n], 0, 0, 0); __builtin_amdgcn_s_setprio(0); } while (0)
; #define PG8_WAIT_V(n) asm volatile("s_waitcnt vmcnt(" #n ")" ::: "memory")
; #define PG8_WAIT_L(n) asm volatile("s_waitcnt lgkmcnt(" #n ")" ::: "memory")
; template <class Epi, class Sched, bool ALIGN_EPI = false, bool SP2 = false>
; __device__ __forceinline__ void gemm_phase(PG8_LAS unsigned char* lds, const Gemm g, const Sched& S, const Epi& E) {
;     ...
;         for (int t = 0; t < nt; t += 2) {
;             const bool last = (t == nt - 2);
;             const char* a1 = cA + (size_t)(t + 1) * kstep;
;             const char* a2 = last ? nA : cA + (size_t)(t + 2) * kstep; const char* b2 = last ? nB : cB + (size_t)(t + 2) * kstep;
;             const char* a3 = a2 + kstep; const char* b3 = b2 + kstep;
;             if (last && has_next) S.a_ready(nxt);
;     ...
;             PG8_LDB(B0, 1, 0); PG8_LDB(B1, 1, 1); PG8_SCHED; PG8_LDA(At, 1, 0); PG8_STAGE(PG8_SA(0, 1), a2 + hstep, voffA);
;             PG8_WAIT_V(8); PG8_WAIT_L(0); PG8_BAR; PG8_MMA(0, 0, At, B0); PG8_MMA(0, 1, At, B1); PG8_BAR; PG8_SCHED;
;             PG8_LDA(At, 1, 1); PG8_STAGE(PG8_SB(1, 0), b3, voffB); PG8_STAGE(PG8_SB(1, 1), b3 + hstep, voffB); PG8_STAGE(PG8_SA(1, 0), a3, voffA);
;             PG8_WAIT_V(8); PG8_WAIT_L(0); PG8_BAR; PG8_MMA(1, 0, At, B0); PG8_MMA(1, 1, At, B1); PG8_BAR; PG8_SCHED;
	v_mfma_f32_16x16x32_bf16 v[106:109], v[130:133], v[192:195], v[106:109]
	v_mfma_f32_16x16x32_bf16 v[42:45], v[138:141], v[192:195], v[42:45]
	v_mfma_f32_16x16x32_bf16 v[98:101], v[130:133], v[214:217], v[98:101]
	v_mfma_f32_16x16x32_bf16 v[34:37], v[138:141], v[214:217], v[34:37]
	v_mfma_f32_16x16x32_bf16 v[122:125], v[134:137], v[180:183], v[122:125]
	v_mfma_f32_16x16x32_bf16 v[58:61], v[142:145], v[180:183], v[58:61]
	v_mfma_f32_16x16x32_bf16 v[114:117], v[134:137], v[188:191], v[114:117]
	v_mfma_f32_16x16x32_bf16 v[50:53], v[142:145], v[188:191], v[50:53]
	v_mfma_f32_16x16x32_bf16 v[106:109], v[134:137], v[210:213], v[106:109]
	v_mfma_f32_16x16x32_bf16 v[42:45], v[142:145], v[210:213], v[42:45]
	v_mfma_f32_16x16x32_bf16 v[98:101], v[134:137], v[218:221], v[98:101]
	v_mfma_f32_16x16x32_bf16 v[34:37], v[142:145], v[218:221], v[34:37]
	s_setprio 0
	s_setprio 1
	v_mfma_f32_16x16x32_bf16 v[126:129], v[146:149], v[176:179], v[126:129]
	v_mfma_f32_16x16x32_bf16 v[62:65], v[154:157], v[176:179], v[62:65]
	v_mfma_f32_16x16x32_bf16 v[118:121], v[146:149], v[184:187], v[118:121]
	v_mfma_f32_16x16x32_bf16 v[54:57], v[154:157], v[184:187], v[54:57]
	v_mfma_f32_16x16x32_bf16 v[110:113], v[146:149], v[192:195], v[110:113]
	v_mfma_f32_16x16x32_bf16 v[46:49], v[154:157], v[192:195], v[46:49]
	v_mfma_f32_16x16x32_bf16 v[102:105], v[146:149], v[214:217], v[102:105]
	v_mfma_f32_16x16x32_bf16 v[38:41], v[154:157], v[214:217], v[38:41]
	v_mfma_f32_16x16x32_bf16 v[126:129], v[150:153], v[180:183], v[126:129]
	v_mfma_f32_16x16x32_bf16 v[62:65], v[158:161], v[180:183], v[62:65]
	v_mfma_f32_16x16x32_bf16 v[118:121], v[150:153], v[188:191], v[118:121]
	v_mfma_f32_16x16x32_bf16 v[54:57], v[158:161], v[188:191], v[54:57]
	v_mfma_f32_16x16x32_bf16 v[110:113], v[150:153], v[210:213], v[110:113]
	v_mfma_f32_16x16x32_bf16 v[46:49], v[158:161], v[210:213], v[46:49]
	v_mfma_f32_16x16x32_bf16 v[102:105], v[150:153], v[218:221], v[102:105]
	v_mfma_f32_16x16x32_bf16 v[38:41], v[158:161], v[218:221], v[38:41]
	s_setprio 0
	s_barrier
	s_add_i32 s61, s61, s76
	v_lshl_add_u64 v[202:203], v[202:203], 0, s[96:97]
	s_mov_b32 m0, s61
	ds_read_b128 v[176:179], v208 offset:49152
	ds_read_b128 v[180:183], v208 offset:50176
	ds_read_b128 v[184:187], v208 offset:51200
	ds_read_b128 v[188:191], v208 offset:52224
	ds_read_b128 v[192:195], v208 offset:53248
	ds_read_b128 v[210:213], v208 offset:54272
	ds_read_b128 v[214:217], v208 offset:55296
	ds_read_b128 v[218:221], v208 offset:56320
	global_load_lds_dwordx4 v[202:203], off
	s_add_i32 m0, s61, 0x2000
	s_add_u32 s62, s62, 0x80080
	v_lshl_add_u64 v[202:203], v[230:231], 0, s[96:97]
	s_addc_u32 s63, s63, 0
	s_add_i32 s61, s85, s76
	global_load_lds_dwordx4 v[202:203], off
	v_lshl_add_u64 v[202:203], s[62:63], 0, v[0:1]
	s_mov_b32 m0, s61
	s_nop 0
	global_load_lds_dwordx4 v[202:203], off
	v_lshl_add_u64 v[202:203], s[62:63], 0, v[166:167]
	s_add_i32 m0, s61, 0x2000
	s_nop 0
	global_load_lds_dwordx4 v[202:203], off
	s_waitcnt vmcnt(8)
	s_waitcnt lgkmcnt(0)
	s_setprio 1
	s_waitcnt lgkmcnt(0)
	v_mfma_f32_16x16x32_bf16 v[90:93], v[130:133], v[176:179], v[90:93]
	v_mfma_f32_16x16x32_bf16 v[26:29], v[138:141], v[176:179], v[26:29]
	v_mfma_f32_16x16x32_bf16 v[82:85], v[130:133], v[184:187], v[82:85]
	v_mfma_f32_16x16x32_bf16 v[18:21], v[138:141], v[184:187], v[18:21]
	s_barrier
	v_mfma_f32_16x16x32_bf16 v[74:77], v[130:133], v[192:195], v[74:77]
	v_mfma_f32_16x16x32_bf16 v[10:13], v[138:141], v[192:195], v[10:13]
	v_mfma_f32_16x16x32_bf16 v[66:69], v[130:133], v[214:217], v[66:69]
	v_mfma_f32_16x16x32_bf16 v[2:5], v[138:141], v[214:217], v[2:5]
	v_mfma_f32_16x16x32_bf16 v[90:93], v[134:137], v[180:183], v[90:93]
	v_mfma_f32_16x16x32_bf16 v[26:29], v[142:145], v[180:183], v[26:29]
	v_mfma_f32_16x16x32_bf16 v[82:85], v[134:137], v[188:191], v[82:85]
	v_mfma_f32_16x16x32_bf16 v[18:21], v[142:145], v[188:191], v[18:21]
	v_mfma_f32_16x16x32_bf16 v[74:77], v[134:137], v[210:213], v[74:77]
	v_mfma_f32_16x16x32_bf16 v[10:13], v[142:145], v[210:213], v[10:13]
	v_mfma_f32_16x16x32_bf16 v[66:69], v[134:137], v[218:221], v[66:69]
	v_mfma_f32_16x16x32_bf16 v[2:5], v[142:145], v[218:221], v[2:5]
	s_setprio 0
	s_setprio 1
	v_mfma_f32_16x16x32_bf16 v[94:97], v[146:149], v[176:179], v[94:97]
	v_mfma_f32_16x16x32_bf16 v[30:33], v[154:157], v[176:179], v[30:33]
	v_mfma_f32_16x16x32_bf16 v[86:89], v[146:149], v[184:187], v[86:89]
	v_mfma_f32_16x16x32_bf16 v[22:25], v[154:157], v[184:187], v[22:25]
	v_mfma_f32_16x16x32_bf16 v[78:81], v[146:149], v[192:195], v[78:81]
	v_mfma_f32_16x16x32_bf16 v[14:17], v[154:157], v[192:195], v[14:17]
	v_mfma_f32_16x16x32_bf16 v[70:73], v[146:149], v[214:217], v[70:73]
	v_mfma_f32_16x16x32_bf16 v[6:9], v[154:157], v[214:217], v[6:9]
	v_mfma_f32_16x16x32_bf16 v[94:97], v[150:153], v[180:183], v[94:97]
	v_mfma_f32_16x16x32_bf16 v[30:33], v[158:161], v[180:183], v[30:33]
	v_mfma_f32_16x16x32_bf16 v[86:89], v[150:153], v[188:191], v[86:89]
	v_mfma_f32_16x16x32_bf16 v[22:25], v[158:161], v[188:191], v[22:25]
	v_mfma_f32_16x16x32_bf16 v[78:81], v[150:153], v[210:213], v[78:81]
	v_mfma_f32_16x16x32_bf16 v[14:17], v[158:161], v[210:213], v[14:17]
	v_mfma_f32_16x16x32_bf16 v[70:73], v[150:153], v[218:221], v[70:73]
	v_mfma_f32_16x16x32_bf16 v[6:9], v[158:161], v[218:221], v[6:9]
	s_setprio 0
	s_barrier
	s_add_i32 s59, s59, 2
	s_mov_b32 s101, s100
	s_mov_b32 s100, vcc_hi
	s_add_u32 s64, s64, 0x100
	s_addc_u32 s65, s65, 0
	s_add_u32 s51, s51, 0x100
	s_addc_u32 s53, s53, 0
	s_cmp_gt_u32 s59, 29
	s_cbranch_scc0 .LBB0_1423
	s_and_b64 vcc, exec, s[48:49]
	s_cbranch_vccz .LBB0_1426
	s_barrier

; #define PG8_BAR __builtin_amdgcn_s_barrier()
;     __host__ __device__ bool next(int i, Unit& u) const {
;         const long L = (long)i * G + c; if (L >= nwg) return false;
;         int wgid = (int)L; { const int q = nwg / NXCD, r = nwg % NXCD, xcd = wgid % NXCD, off = wgid / NXCD; wgid = (xcd < r ? xcd * (q + 1) : r * (q + 1) + (xcd - r) * q) + off; }
; template <class Epi, class Sched, bool ALIGN_EPI = false, bool SP2 = false>
; __device__ __forceinline__ void gemm_phase(PG8_LAS unsigned char* lds, const Gemm g, const Sched& S, const Epi& E) {
;     const int tid = ltid(), wid = __builtin_amdgcn_readfirstlane(tid >> 6), lane = tid & 63, wr = wid >> 2, wc = wid & 3, fr = lane & 15, fq = lane >> 4;
;     const int K = g.K, nt = K / BK;
;     unsigned voffA[2], voffB[2];
; #pragma unroll
;     for (int i = 0; i < 2; ++i) { int R, C; stage_rc(tid * 16 + i * 8192, R, C); const int Rb = Epi::PERM ? ((R & ~31) + perm32(R & 31)) : R;
;         voffA[i] = (unsigned)(R * K + C) * 2u; voffB[i] = (unsigned)(Rb * K + C) * 2u; }
;     const size_t kstep = (size_t)(BK * 2);
;     const size_t hstep = (size_t)HALF * K * 2;
;     const size_t tstep = 2 * hstep;
;     const unsigned ldsw = (unsigned)wid * 1024u;
;     const int aoff = lds_byte(wr * 64 + fr, fq * 8), boff = lds_byte(wc * 32 + fr, fq * 8);
;     ...
;     Unit cur, nxt; int ui = 0;
;     if (!S.next(0, cur)) return;
;     f32x4 acc[2][2][4][2];
; #pragma unroll
;     for (int a = 0; a < 2; ++a)
; #pragma unroll
;         for (int b = 0; b < 2; ++b)
; #pragma unroll
;             for (int m = 0; m < 4; ++m)
; #pragma unroll
;                 for (int n = 0; n < 2; ++n) { float zr_ = 0.f; asm volatile("" : "+v"(zr_)); acc[a][b][m][n] = (f32x4){zr_, zr_, zr_, zr_}; }
;     bf16x8 At[4][2], B0[2][2], B1[2][2];
;     const char* cA = (const char*)g.A + (size_t)cur.pm * tstep; const char* cB = (const char*)g.Bt + (size_t)cur.pn * tstep;
;     S.a_ready(cur);
;     if constexpr (SP2) {
;         PG8_STAGE(PG8_SB(0, 0), cB, voffB); PG8_STAGE(PG8_SB(0, 1), cB + hstep, voffB); PG8_STAGE(PG8_SA(0, 0), cA, voffA); PG8_STAGE(PG8_SA(0, 1), cA + hstep, voffA);
;         if (wr == 1) PG8_BAR;
;         PG8_WAIT_V(2); PG8_BAR;
;         PG8_STAGE(PG8_SB(1, 0), cB + kstep, voffB); PG8_STAGE(PG8_SA(1, 0), cA + kstep, voffA); PG8_STAGE(PG8_SB(1, 1), cB + hstep + kstep, voffB);
;         PG8_WAIT_V(6); PG8_BAR;
.LBB0_1580:
	s_mov_b32 s100, 0
	s_mov_b32 s101, 0x8000
	v_readlane_b32 s0, v253, 51
	v_readlane_b32 s1, v253, 52
	v_mov_b32_e32 v0, v197
	s_lshr_b32 s12, s30, 5
	v_mov_b32_e32 v147, v197
	s_waitcnt lgkmcnt(0)
	s_load_dwordx2 s[10:11], s[0:1], 0x40
	s_load_dwordx4 s[20:23], s[0:1], 0xd0
	s_load_dwordx2 s[8:9], s[0:1], 0xe0
	s_load_dwordx4 s[16:19], s[0:1], 0x108
	s_cmp_ge_i32 s94, s12
	v_readfirstlane_b32 s4, v147
	s_cbranch_scc1 .LBB0_1600
	v_lshlrev_b32_e32 v0, 4, v147
	v_add_u32_e32 v2, 0x2000, v0
	v_ashrrev_i32_e32 v3, 31, v2
	v_lshrrev_b32_e32 v3, 22, v3
	v_add_u32_e32 v3, v2, v3
	v_ashrrev_i32_e32 v140, 10, v3
	v_mul_i32_i24_e32 v3, 0x400, v140
	v_sub_u32_e32 v2, v2, v3
	v_lshrrev_b32_e32 v3, 4, v2
	v_bitop3_b32 v2, v3, v2, 32 bitop3:0x6c
	v_ashrrev_i32_e32 v3, 31, v2
	v_lshrrev_b32_e32 v3, 26, v3
	v_add_u32_e32 v3, v2, v3
	v_ashrrev_i32_e32 v141, 6, v3
	v_lshlrev_b32_e32 v5, 5, v140
	v_and_b32_e32 v3, 0xc0, v3
	v_and_b32_e32 v142, 32, v5
	v_sub_u32_e32 v2, v2, v3
	v_mov_b32_e32 v5, 1
	v_ashrrev_i16_sdwa v2, v5, sext(v2) dst_sel:DWORD dst_unused:UNUSED_PAD src0_sel:DWORD src1_sel:BYTE_0
	v_bfe_i32 v143, v2, 0, 16
	v_bfe_i32 v2, v147, 27, 1
	v_lshrrev_b32_e32 v2, 22, v2
	v_add_u32_e32 v2, v0, v2
	v_and_b32_e32 v2, 0xfffffc00, v2
	v_sub_u32_e32 v0, v0, v2
	v_lshrrev_b32_e32 v2, 4, v0
	v_bitop3_b32 v2, v2, v0, 32 bitop3:0x6c
	v_ashrrev_i32_e32 v0, 31, v0
	v_lshrrev_b32_e32 v0, 26, v0
	v_add_u32_e32 v0, v2, v0
	s_lshr_b32 s0, s30, 8
	v_ashrrev_i32_e32 v144, 6, v0
	v_ashrrev_i32_e32 v0, 31, v147
	s_waitcnt lgkmcnt(0)
	s_add_u32 s1, s18, 0xf4c6000
	v_lshrrev_b32_e32 v0, 26, v0
	s_addc_u32 s28, s19, 0
	v_add_u32_e32 v0, v147, v0
	s_add_u32 s29, s18, 0xbec6000
	v_ashrrev_i32_e32 v145, 6, v0
	s_addc_u32 s30, s19, 0
	s_ashr_i32 s5, s4, 6
	v_lshlrev_b32_e32 v4, 3, v140
	v_lshlrev_b32_e32 v0, 3, v145
	v_readlane_b32 s14, v253, 22
	s_ashr_i32 s6, s4, 8
	s_lshl_b32 s31, s5, 10
	v_and_b32_e32 v4, 0x7ffff0, v4
	v_and_b32_e32 v0, 0x7ffff0, v0
	s_add_i32 s46, s0, 1
	v_readlane_b32 s15, v253, 23
	v_add_u32_e32 v4, v141, v4
	s_movk_i32 s7, 0x1600
	v_add_u32_e32 v0, v144, v0
	s_and_b64 s[14:15], s[14:15], exec
	v_mul_lo_u32 v4, v4, s7
	v_mul_lo_u32 v0, v0, s7
	s_cselect_b32 s7, s46, s0
	v_readlane_b32 s14, v253, 21
	s_mul_i32 s7, s7, s14
	v_readlane_b32 s14, v252, 62
	s_add_i32 s7, s7, s14
	s_ashr_i32 s14, s7, 31
	s_lshr_b32 s14, s14, 26
	s_add_i32 s14, s7, s14
	s_ashr_i32 s15, s14, 6
	s_lshl_b32 s15, s15, 3
	s_sub_i32 s24, s0, s15
	v_lshlrev_b32_e32 v3, 5, v145
	s_min_i32 s24, s24, 8
	v_and_b32_e32 v149, 32, v3
	v_mul_i32_i24_e32 v3, 64, v144
	s_abs_i32 s25, s24
	v_sub_u32_e32 v2, v2, v3
	v_cvt_f32_u32_e32 v3, s25
	v_ashrrev_i16_sdwa v2, v5, sext(v2) dst_sel:DWORD dst_unused:UNUSED_PAD src0_sel:DWORD src1_sel:BYTE_0
	v_bfe_i32 v150, v2, 0, 16
	s_sub_i32 s27, 0, s25
	v_rcp_iflag_f32_e32 v2, v3
	s_andn2_b32 s14, s14, 63
	s_sub_i32 s7, s7, s14
	s_abs_i32 s26, s7
	v_mul_f32_e32 v2, 0x4f7ffffe, v2
	v_cvt_u32_f32_e32 v2, v2
	s_xor_b32 s14, s7, s24
	s_ashr_i32 s14, s14, 31
	v_or_b32_e32 v0, v0, v149
	v_readfirstlane_b32 s38, v2
	s_mul_i32 s27, s27, s38
	s_mul_hi_u32 s27, s38, s27
	s_add_i32 s38, s38, s27
	s_mul_hi_u32 s27, s26, s38
	s_mul_i32 s38, s27, s25
	s_sub_i32 s26, s26, s38
	s_add_i32 s38, s27, 1
	s_sub_i32 s39, s26, s25
	s_cmp_ge_u32 s26, s25
	s_cselect_b32 s27, s38, s27
	s_cselect_b32 s26, s39, s26
	s_add_i32 s38, s27, 1
	s_cmp_ge_u32 s26, s25
	s_cselect_b32 s25, s38, s27
	s_xor_b32 s25, s25, s14
	s_sub_i32 s60, s25, s14
	s_mul_i32 s14, s60, s24
	s_sub_i32 s7, s7, s14
	s_add_i32 s61, s15, s7
	s_mul_i32 s15, s60, 0x2c0000
	s_mul_hi_i32 s14, s60, 0x2c0000
	s_add_u32 s40, s29, s15
	s_addc_u32 s41, s30, s14
	s_add_i32 s47, s31, 0
	v_add_lshl_u32 v0, v0, v150, 1
	v_mov_b32_e32 v98, v1
	v_mov_b32_e32 v34, v1
	v_mov_b32_e32 v102, v1
	v_mov_b32_e32 v42, v1
	v_mov_b32_e32 v106, v1
	v_mov_b32_e32 v50, v1
	v_mov_b32_e32 v110, v1
	v_mov_b32_e32 v58, v1
	v_mov_b32_e32 v38, v1
	v_mov_b32_e32 v2, v1
	v_mov_b32_e32 v46, v1
	v_mov_b32_e32 v6, v1
	v_mov_b32_e32 v54, v1
	v_mov_b32_e32 v10, v1
	v_mov_b32_e32 v62, v1
	v_mov_b32_e32 v14, v1
	v_mov_b32_e32 v114, v1
	v_mov_b32_e32 v66, v1
	v_mov_b32_e32 v118, v1
	v_mov_b32_e32 v74, v1
	v_mov_b32_e32 v122, v1
	v_mov_b32_e32 v82, v1
	v_mov_b32_e32 v126, v1
	v_mov_b32_e32 v90, v1
	v_mov_b32_e32 v70, v1
	v_mov_b32_e32 v18, v1
	v_mov_b32_e32 v78, v1
	v_mov_b32_e32 v22, v1
	v_mov_b32_e32 v86, v1
	v_mov_b32_e32 v26, v1
	v_mov_b32_e32 v94, v1
	v_mov_b32_e32 v30, v1
	s_add_i32 m0, s47, 0x10000
	v_or_b32_e32 v4, v4, v142
	global_load_lds_dwordx4 v0, s[40:41]
	s_add_i32 m0, s47, 0x12000
	v_add_lshl_u32 v130, v4, v143, 1
	s_add_u32 s14, s40, 0x160000
	global_load_lds_dwordx4 v130, s[40:41]
	s_addc_u32 s15, s41, 0
	s_add_i32 m0, s47, 0x14000
	s_mul_i32 s24, s61, 0x2c0000
	global_load_lds_dwordx4 v0, s[14:15]
	s_add_i32 m0, s47, 0x16000
	s_mul_hi_i32 s7, s61, 0x2c0000
	s_add_u32 s38, s1, s24
	s_addc_u32 s39, s28, s7
	s_add_i32 s48, s47, 0x2000
	global_load_lds_dwordx4 v130, s[14:15]
	s_mov_b32 m0, s47
	s_add_u32 s14, s38, 0x160000
	global_load_lds_dwordx4 v0, s[38:39]
	s_mov_b32 m0, s48
	s_addc_u32 s15, s39, 0
	s_add_i32 s49, s47, 0x4000
	global_load_lds_dwordx4 v130, s[38:39]
	s_mov_b32 m0, s49
	s_add_i32 s50, s47, 0x6000
	global_load_lds_dwordx4 v0, s[14:15]
	s_mov_b32 m0, s50
	v_mov_b32_e32 v131, v1
	global_load_lds_dwordx4 v130, s[14:15]
	s_cmp_eq_u32 s6, 1
	v_lshl_add_u64 v[138:139], s[40:41], 0, v[0:1]
	v_lshl_add_u64 v[136:137], s[40:41], 0, v[130:131]
	v_lshl_add_u64 v[134:135], s[38:39], 0, v[0:1]
	s_cselect_b64 s[14:15], -1, 0
	s_cmp_lg_u32 s6, 1
	v_lshl_add_u64 v[132:133], s[38:39], 0, v[130:131]
	s_cbranch_scc1 .LBB0_1583
	s_barrier

; #define PG8_STAGE(bufoff, gbase, voff) do { _Pragma("unroll") for (int _i = 0; _i < 2; ++_i) \
;         __builtin_amdgcn_global_load_lds((const unsigned*)((const char*)(gbase) + (voff)[_i]), (PG8_LAS unsigned*)(lds + (bufoff) + ldsw + _i * 8192), 16, 0, 0); } while (0)
; #define PG8_LDA(dst, b, h) do { _Pragma("unroll") for (int m = 0; m < 4; ++m) _Pragma("unroll") for (int k = 0; k < 2; ++k) dst[m][k] = *(const PG8_LAS bf16x8*)(lds + PG8_SA(b, h) + aoff + m * 2048 + k * 1024); } while (0)
; #define PG8_LDB(dst, b, h) do { _Pragma("unroll") for (int n = 0; n < 2; ++n) _Pragma("unroll") for (int k = 0; k < 2; ++k) dst[n][k] = *(const PG8_LAS bf16x8*)(lds + PG8_SB(b, h) + boff + n * 2048 + k * 1024); } while (0)
; #define PG8_MMA(ai, bj, At, Bt) do { __builtin_amdgcn_s_setprio(1); _Pragma("unroll") for (int m = 0; m < 4; ++m) _Pragma("unroll") for (int n = 0; n < 2; ++n) _Pragma("unroll") for (int k = 0; k < 2; ++k) \
;         acc[ai][bj][m][n] = __builtin_amdgcn_mfma_f32_16x16x32_bf16(Bt[n][k], At[m][k], acc[ai][bj][m][n], 0, 0, 0); __builtin_amdgcn_s_setprio(0); } while (0)
; #define PG8_WAIT_V(n) asm volatile("s_waitcnt vmcnt(" #n ")" ::: "memory")
; #define PG8_BAR __builtin_amdgcn_s_barrier()
; template <class Epi, class Sched, bool ALIGN_EPI = false, bool SP2 = false>
; __device__ __forceinline__ void gemm_phase(PG8_LAS unsigned char* lds, const Gemm g, const Sched& S, const Epi& E) {
;     ...
;         for (int t = 0; t < nt; t += 2) {
;             const bool last = (t == nt - 2);
;             const char* a1 = cA + (size_t)(t + 1) * kstep;
;             const char* a2 = last ? nA : cA + (size_t)(t + 2) * kstep; const char* b2 = last ? nB : cB + (size_t)(t + 2) * kstep;
;             const char* a3 = a2 + kstep; const char* b3 = b2 + kstep;
;             if (last && has_next) S.a_ready(nxt);
;             if constexpr (SP2) {
;             PG8_LDB(B0, 0, 0); PG8_LDB(B1, 0, 1); PG8_SCHED; PG8_LDA(At, 0, 0); PG8_STAGE(PG8_SA(1, 1), a1 + hstep, voffA);
;             PG8_WAIT_V(8); PG8_WAIT_L(0); PG8_BAR; PG8_MMA(0, 0, At, B0); PG8_MMA(0, 1, At, B1); PG8_BAR; PG8_SCHED;
;             PG8_LDA(At, 0, 1); PG8_STAGE(PG8_SB(0, 0), b2, voffB); PG8_STAGE(PG8_SB(0, 1), b2 + hstep, voffB); PG8_STAGE(PG8_SA(0, 0), a2, voffA);
;             PG8_WAIT_V(8); PG8_WAIT_L(0); PG8_BAR; PG8_MMA(1, 0, At, B0); PG8_MMA(1, 1, At, B1); PG8_BAR; PG8_SCHED;
.LBB0_1593:
	s_sub_i32 vcc_hi, 0x29000, s100
	s_sub_i32 vcc_hi, vcc_hi, s101
	s_add_u32 s40, s38, 0x100
	s_addc_u32 s41, s39, 0
	s_add_i32 s65, 0, 0x10000
	s_cmpk_eq_i32 s64, 0x54
	s_cselect_b32 s45, s7, s41
	s_cselect_b32 s44, s6, s40
	v_add_u32_e32 v144, s65, v147
	s_cselect_b32 s43, s27, s63
	s_cselect_b32 s42, s26, s62
	s_add_i32 s66, 0, 0x14000
	ds_read_b128 v[136:139], v144
	ds_read_b128 v[140:143], v144 offset:1024
	ds_read_b128 v[150:153], v144 offset:2048
	ds_read_b128 v[154:157], v144 offset:3072
	v_add_u32_e32 v144, s66, v147
	ds_read_b128 v[158:161], v144
	ds_read_b128 v[162:165], v144 offset:1024
	ds_read_b128 v[166:169], v144 offset:2048
	ds_read_b128 v[170:173], v144 offset:3072
	v_lshl_add_u64 v[144:145], s[38:39], 0, v[132:133]
	s_add_i32 m0, s47, 0xc000
	v_add_u32_e32 v250, s100, v149
	ds_read_b128 v[174:177], v250
	ds_read_b128 v[178:181], v250 offset:1024
	ds_read_b128 v[182:185], v250 offset:2048
	ds_read_b128 v[186:189], v250 offset:3072
	ds_read_b128 v[190:193], v250 offset:4096
	ds_read_b128 v[202:205], v250 offset:5120
	ds_read_b128 v[206:209], v250 offset:6144
	ds_read_b128 v[210:213], v250 offset:7168
	global_load_lds_dwordx4 v[144:145], off
	v_lshl_add_u64 v[144:145], s[38:39], 0, v[134:135]
	s_add_i32 m0, s47, 0xe000
	s_nop 0
	global_load_lds_dwordx4 v[144:145], off
	v_lshl_add_u64 v[238:239], s[44:45], 0, v[0:1]
	v_lshl_add_u64 v[240:241], s[44:45], 0, v[130:131]
	s_add_i32 m0, vcc_hi, s47
	s_nop 0
	global_load_lds_dwordx4 v[238:239], off
	s_add_i32 m0, m0, 0x2000
	s_nop 0
	global_load_lds_dwordx4 v[240:241], off
	s_waitcnt vmcnt(10)
	s_waitcnt lgkmcnt(0)
	s_setprio 1
	s_waitcnt lgkmcnt(0)
	v_mfma_f32_16x16x32_bf16 v[98:101], v[136:139], v[174:177], v[98:101]
	v_mfma_f32_16x16x32_bf16 v[34:37], v[150:153], v[174:177], v[34:37]
	v_mfma_f32_16x16x32_bf16 v[102:105], v[136:139], v[182:185], v[102:105]
	v_mfma_f32_16x16x32_bf16 v[42:45], v[150:153], v[182:185], v[42:45]
	s_barrier
	v_mfma_f32_16x16x32_bf16 v[106:109], v[136:139], v[190:193], v[106:109]
	v_mfma_f32_16x16x32_bf16 v[50:53], v[150:153], v[190:193], v[50:53]
	v_mfma_f32_16x16x32_bf16 v[110:113], v[136:139], v[206:209], v[110:113]
	v_mfma_f32_16x16x32_bf16 v[58:61], v[150:153], v[206:209], v[58:61]
	v_mfma_f32_16x16x32_bf16 v[98:101], v[140:143], v[178:181], v[98:101]
	v_mfma_f32_16x16x32_bf16 v[34:37], v[154:157], v[178:181], v[34:37]
	v_mfma_f32_16x16x32_bf16 v[102:105], v[140:143], v[186:189], v[102:105]
	v_mfma_f32_16x16x32_bf16 v[42:45], v[154:157], v[186:189], v[42:45]
	v_mfma_f32_16x16x32_bf16 v[106:109], v[140:143], v[202:205], v[106:109]
	v_mfma_f32_16x16x32_bf16 v[50:53], v[154:157], v[202:205], v[50:53]
	v_mfma_f32_16x16x32_bf16 v[110:113], v[140:143], v[210:213], v[110:113]
	v_mfma_f32_16x16x32_bf16 v[58:61], v[154:157], v[210:213], v[58:61]
	s_setprio 0
	s_setprio 1
	v_mfma_f32_16x16x32_bf16 v[38:41], v[158:161], v[174:177], v[38:41]
	v_mfma_f32_16x16x32_bf16 v[2:5], v[166:169], v[174:177], v[2:5]
	v_mfma_f32_16x16x32_bf16 v[46:49], v[158:161], v[182:185], v[46:49]
	v_mfma_f32_16x16x32_bf16 v[6:9], v[166:169], v[182:185], v[6:9]
	v_mfma_f32_16x16x32_bf16 v[54:57], v[158:161], v[190:193], v[54:57]
	v_mfma_f32_16x16x32_bf16 v[10:13], v[166:169], v[190:193], v[10:13]
	v_mfma_f32_16x16x32_bf16 v[62:65], v[158:161], v[206:209], v[62:65]
	v_mfma_f32_16x16x32_bf16 v[14:17], v[166:169], v[206:209], v[14:17]
	v_mfma_f32_16x16x32_bf16 v[38:41], v[162:165], v[178:181], v[38:41]
	v_mfma_f32_16x16x32_bf16 v[2:5], v[170:173], v[178:181], v[2:5]
	v_mfma_f32_16x16x32_bf16 v[46:49], v[162:165], v[186:189], v[46:49]
	v_mfma_f32_16x16x32_bf16 v[6:9], v[170:173], v[186:189], v[6:9]
	v_mfma_f32_16x16x32_bf16 v[54:57], v[162:165], v[202:205], v[54:57]
	v_mfma_f32_16x16x32_bf16 v[10:13], v[170:173], v[202:205], v[10:13]
	v_mfma_f32_16x16x32_bf16 v[62:65], v[162:165], v[210:213], v[62:65]
	v_mfma_f32_16x16x32_bf16 v[14:17], v[170:173], v[210:213], v[14:17]
	s_setprio 0
	s_barrier
	s_add_i32 s38, s65, s31
	v_lshl_add_u64 v[144:145], s[42:43], 0, v[0:1]
	s_mov_b32 m0, s38
	ds_read_b128 v[174:177], v149 offset:16384
	ds_read_b128 v[178:181], v149 offset:17408
	ds_read_b128 v[182:185], v149 offset:18432
	ds_read_b128 v[186:189], v149 offset:19456
	ds_read_b128 v[190:193], v149 offset:20480
	ds_read_b128 v[202:205], v149 offset:21504
	ds_read_b128 v[206:209], v149 offset:22528
	ds_read_b128 v[210:213], v149 offset:23552
	global_load_lds_dwordx4 v[144:145], off
	s_add_i32 m0, s38, 0x2000
	s_add_u32 s38, s42, 0x160000
	v_lshl_add_u64 v[194:195], s[42:43], 0, v[130:131]
	s_addc_u32 s39, s43, 0
	s_add_i32 s65, s66, s31
	global_load_lds_dwordx4 v[194:195], off
	v_lshl_add_u64 v[214:215], s[38:39], 0, v[0:1]
	s_mov_b32 m0, s65
	global_load_lds_dwordx4 v[214:215], off
	v_lshl_add_u64 v[214:215], s[38:39], 0, v[130:131]
	s_add_i32 m0, s65, 0x2000
	s_nop 0
	global_load_lds_dwordx4 v[214:215], off
	s_waitcnt vmcnt(8)
	s_waitcnt lgkmcnt(0)
	s_setprio 1
	s_waitcnt lgkmcnt(0)
	v_mfma_f32_16x16x32_bf16 v[114:117], v[136:139], v[174:177], v[114:117]
	v_mfma_f32_16x16x32_bf16 v[66:69], v[150:153], v[174:177], v[66:69]
	v_mfma_f32_16x16x32_bf16 v[118:121], v[136:139], v[182:185], v[118:121]
	v_mfma_f32_16x16x32_bf16 v[74:77], v[150:153], v[182:185], v[74:77]
	s_barrier
; #define PG8_STAGE(bufoff, gbase, voff) do { _Pragma("unroll") for (int _i = 0; _i < 2; ++_i) \
;         __builtin_amdgcn_global_load_lds((const unsigned*)((const char*)(gbase) + (voff)[_i]), (PG8_LAS unsigned*)(lds + (bufoff) + ldsw + _i * 8192), 16, 0, 0); } while (0)
; #define PG8_LDA(dst, b, h) do { _Pragma("unroll") for (int m = 0; m < 4; ++m) _Pragma("unroll") for (int k = 0; k < 2; ++k) dst[m][k] = *(const PG8_LAS bf16x8*)(lds + PG8_SA(b, h) + aoff + m * 2048 + k * 1024); } while (0)
; #define PG8_LDB(dst, b, h) do { _Pragma("unroll") for (int n = 0; n < 2; ++n) _Pragma("unroll") for (int k = 0; k < 2; ++k) dst[n][k] = *(const PG8_LAS bf16x8*)(lds + PG8_SB(b, h) + boff + n * 2048 + k * 1024); } while (0)
; #define PG8_MMA(ai, bj, At, Bt) do { __builtin_amdgcn_s_setprio(1); _Pragma("unroll") for (int m = 0; m < 4; ++m) _Pragma("unroll") for (int n = 0; n < 2; ++n) _Pragma("unroll") for (int k = 0; k < 2; ++k) \
;         acc[ai][bj][m][n] = __builtin_amdgcn_mfma_f32_16x16x32_bf16(Bt[n][k], At[m][k], acc[ai][bj][m][n], 0, 0, 0); __builtin_amdgcn_s_setprio(0); } while (0)
; #define PG8_WAIT_V(n) asm volatile("s_waitcnt vmcnt(" #n ")" ::: "memory")
; #define PG8_WAIT_L(n) asm volatile("s_waitcnt lgkmcnt(" #n ")" ::: "memory")
; #define PG8_BAR __builtin_amdgcn_s_barrier()
; #define PG8_SCHED __builtin_amdgcn_sched_barrier(0)
; template <class Epi, class Sched, bool ALIGN_EPI = false, bool SP2 = false>
; __device__ __forceinline__ void gemm_phase(PG8_LAS unsigned char* lds, const Gemm g, const Sched& S, const Epi& E) {
;     ...
;             PG8_WAIT_V(8); PG8_WAIT_L(0); PG8_BAR; PG8_MMA(0, 0, At, B0); PG8_MMA(0, 1, At, B1); PG8_BAR; PG8_SCHED;
;             PG8_LDA(At, 0, 1); PG8_STAGE(PG8_SB(0, 0), b2, voffB); PG8_STAGE(PG8_SB(0, 1), b2 + hstep, voffB); PG8_STAGE(PG8_SA(0, 0), a2, voffA);
;             PG8_WAIT_V(8); PG8_WAIT_L(0); PG8_BAR; PG8_MMA(1, 0, At, B0); PG8_MMA(1, 1, At, B1); PG8_BAR; PG8_SCHED;
;             PG8_LDB(B0, 1, 0); PG8_LDB(B1, 1, 1); PG8_SCHED; PG8_LDA(At, 1, 0); PG8_STAGE(PG8_SA(0, 1), a2 + hstep, voffA);
;             PG8_WAIT_V(8); PG8_WAIT_L(0); PG8_BAR; PG8_MMA(0, 0, At, B0); PG8_MMA(0, 1, At, B1); PG8_BAR; PG8_SCHED;
	v_mfma_f32_16x16x32_bf16 v[122:125], v[136:139], v[190:193], v[122:125]
	v_mfma_f32_16x16x32_bf16 v[82:85], v[150:153], v[190:193], v[82:85]
	v_mfma_f32_16x16x32_bf16 v[126:129], v[136:139], v[206:209], v[126:129]
	v_mfma_f32_16x16x32_bf16 v[90:93], v[150:153], v[206:209], v[90:93]
	v_mfma_f32_16x16x32_bf16 v[114:117], v[140:143], v[178:181], v[114:117]
	v_mfma_f32_16x16x32_bf16 v[66:69], v[154:157], v[178:181], v[66:69]
	v_mfma_f32_16x16x32_bf16 v[118:121], v[140:143], v[186:189], v[118:121]
	v_mfma_f32_16x16x32_bf16 v[74:77], v[154:157], v[186:189], v[74:77]
	v_mfma_f32_16x16x32_bf16 v[122:125], v[140:143], v[202:205], v[122:125]
	v_mfma_f32_16x16x32_bf16 v[82:85], v[154:157], v[202:205], v[82:85]
	v_mfma_f32_16x16x32_bf16 v[126:129], v[140:143], v[210:213], v[126:129]
	v_mfma_f32_16x16x32_bf16 v[90:93], v[154:157], v[210:213], v[90:93]
	s_setprio 0
	s_setprio 1
	v_mfma_f32_16x16x32_bf16 v[70:73], v[158:161], v[174:177], v[70:73]
	v_mfma_f32_16x16x32_bf16 v[18:21], v[166:169], v[174:177], v[18:21]
	v_mfma_f32_16x16x32_bf16 v[78:81], v[158:161], v[182:185], v[78:81]
	v_mfma_f32_16x16x32_bf16 v[22:25], v[166:169], v[182:185], v[22:25]
	v_mfma_f32_16x16x32_bf16 v[86:89], v[158:161], v[190:193], v[86:89]
	v_mfma_f32_16x16x32_bf16 v[26:29], v[166:169], v[190:193], v[26:29]
	v_mfma_f32_16x16x32_bf16 v[94:97], v[158:161], v[206:209], v[94:97]
	v_mfma_f32_16x16x32_bf16 v[30:33], v[166:169], v[206:209], v[30:33]
	v_mfma_f32_16x16x32_bf16 v[70:73], v[162:165], v[178:181], v[70:73]
	v_mfma_f32_16x16x32_bf16 v[18:21], v[170:173], v[178:181], v[18:21]
	v_mfma_f32_16x16x32_bf16 v[78:81], v[162:165], v[186:189], v[78:81]
	v_mfma_f32_16x16x32_bf16 v[22:25], v[170:173], v[186:189], v[22:25]
	v_mfma_f32_16x16x32_bf16 v[86:89], v[162:165], v[202:205], v[86:89]
	v_mfma_f32_16x16x32_bf16 v[26:29], v[170:173], v[202:205], v[26:29]
	v_mfma_f32_16x16x32_bf16 v[94:97], v[162:165], v[210:213], v[94:97]
	v_mfma_f32_16x16x32_bf16 v[30:33], v[170:173], v[210:213], v[30:33]
	s_setprio 0
	s_barrier
	s_add_i32 s65, 0, 0x18000
	s_add_i32 s66, 0, 0x1c000
	v_add_u32_e32 v154, s65, v147
	v_add_u32_e32 v170, s66, v147
	ds_read_b128 v[136:139], v154
	ds_read_b128 v[140:143], v154 offset:1024
	ds_read_b128 v[150:153], v154 offset:2048
	ds_read_b128 v[154:157], v154 offset:3072
	ds_read_b128 v[158:161], v170
	ds_read_b128 v[162:165], v170 offset:1024
	ds_read_b128 v[166:169], v170 offset:2048
	ds_read_b128 v[170:173], v170 offset:3072
	s_add_u32 s38, s44, 0x160000
	s_addc_u32 s39, s45, 0
	s_mov_b32 m0, s49
	v_lshl_add_u64 v[218:219], s[38:39], 0, v[0:1]
	v_add_u32_e32 v250, s101, v149
	ds_read_b128 v[174:177], v250
	ds_read_b128 v[178:181], v250 offset:1024
	ds_read_b128 v[182:185], v250 offset:2048
	ds_read_b128 v[186:189], v250 offset:3072
	ds_read_b128 v[190:193], v250 offset:4096
	ds_read_b128 v[202:205], v250 offset:5120
	ds_read_b128 v[206:209], v250 offset:6144
	ds_read_b128 v[210:213], v250 offset:7168
	global_load_lds_dwordx4 v[218:219], off
	v_lshl_add_u64 v[218:219], s[38:39], 0, v[130:131]
	s_mov_b32 m0, s50
	s_nop 0
	global_load_lds_dwordx4 v[218:219], off
	v_lshl_add_u64 v[242:243], v[238:239], 0, s[96:97]
	v_lshl_add_u64 v[244:245], v[240:241], 0, s[96:97]
	s_add_i32 m0, s100, s47
	s_nop 0
	global_load_lds_dwordx4 v[242:243], off
	s_add_i32 m0, m0, 0x2000
	s_nop 0
	global_load_lds_dwordx4 v[244:245], off
	s_waitcnt vmcnt(10)
	s_waitcnt lgkmcnt(0)
	s_setprio 1
	s_waitcnt lgkmcnt(0)
	v_mfma_f32_16x16x32_bf16 v[98:101], v[136:139], v[174:177], v[98:101]
	v_mfma_f32_16x16x32_bf16 v[34:37], v[150:153], v[174:177], v[34:37]
	v_mfma_f32_16x16x32_bf16 v[102:105], v[136:139], v[182:185], v[102:105]
	v_mfma_f32_16x16x32_bf16 v[42:45], v[150:153], v[182:185], v[42:45]
	s_barrier
; #define PG8_STAGE(bufoff, gbase, voff) do { _Pragma("unroll") for (int _i = 0; _i < 2; ++_i) \
;         __builtin_amdgcn_global_load_lds((const unsigned*)((const char*)(gbase) + (voff)[_i]), (PG8_LAS unsigned*)(lds + (bufoff) + ldsw + _i * 8192), 16, 0, 0); } while (0)
; #define PG8_LDA(dst, b, h) do { _Pragma("unroll") for (int m = 0; m < 4; ++m) _Pragma("unroll") for (int k = 0; k < 2; ++k) dst[m][k] = *(const PG8_LAS bf16x8*)(lds + PG8_SA(b, h) + aoff + m * 2048 + k * 1024); } while (0)
; #define PG8_LDB(dst, b, h) do { _Pragma("unroll") for (int n = 0; n < 2; ++n) _Pragma("unroll") for (int k = 0; k < 2; ++k) dst[n][k] = *(const PG8_LAS bf16x8*)(lds + PG8_SB(b, h) + boff + n * 2048 + k * 1024); } while (0)
; #define PG8_MMA(ai, bj, At, Bt) do { __builtin_amdgcn_s_setprio(1); _Pragma("unroll") for (int m = 0; m < 4; ++m) _Pragma("unroll") for (int n = 0; n < 2; ++n) _Pragma("unroll") for (int k = 0; k < 2; ++k) \
;         acc[ai][bj][m][n] = __builtin_amdgcn_mfma_f32_16x16x32_bf16(Bt[n][k], At[m][k], acc[ai][bj][m][n], 0, 0, 0); __builtin_amdgcn_s_setprio(0); } while (0)
; #define PG8_WAIT_V(n) asm volatile("s_waitcnt vmcnt(" #n ")" ::: "memory")
; #define PG8_WAIT_L(n) asm volatile("s_waitcnt lgkmcnt(" #n ")" ::: "memory")
; template <class Epi, class Sched, bool ALIGN_EPI = false, bool SP2 = false>
; __device__ __forceinline__ void gemm_phase(PG8_LAS unsigned char* lds, const Gemm g, const Sched& S, const Epi& E) {
;     ...
;         for (int t = 0; t < nt; t += 2) {
;             const bool last = (t == nt - 2);
;             const char* a1 = cA + (size_t)(t + 1) * kstep;
;             const char* a2 = last ? nA : cA + (size_t)(t + 2) * kstep; const char* b2 = last ? nB : cB + (size_t)(t + 2) * kstep;
;             const char* a3 = a2 + kstep; const char* b3 = b2 + kstep;
;             if (last && has_next) S.a_ready(nxt);
;     ...
;             PG8_LDB(B0, 1, 0); PG8_LDB(B1, 1, 1); PG8_SCHED; PG8_LDA(At, 1, 0); PG8_STAGE(PG8_SA(0, 1), a2 + hstep, voffA);
;             PG8_WAIT_V(8); PG8_WAIT_L(0); PG8_BAR; PG8_MMA(0, 0, At, B0); PG8_MMA(0, 1, At, B1); PG8_BAR; PG8_SCHED;
;             PG8_LDA(At, 1, 1); PG8_STAGE(PG8_SB(1, 0), b3, voffB); PG8_STAGE(PG8_SB(1, 1), b3 + hstep, voffB); PG8_STAGE(PG8_SA(1, 0), a3, voffA);
;             PG8_WAIT_V(8); PG8_WAIT_L(0); PG8_BAR; PG8_MMA(1, 0, At, B0); PG8_MMA(1, 1, At, B1); PG8_BAR; PG8_SCHED;
	v_mfma_f32_16x16x32_bf16 v[106:109], v[136:139], v[190:193], v[106:109]
	v_mfma_f32_16x16x32_bf16 v[50:53], v[150:153], v[190:193], v[50:53]
	v_mfma_f32_16x16x32_bf16 v[110:113], v[136:139], v[206:209], v[110:113]
	v_mfma_f32_16x16x32_bf16 v[58:61], v[150:153], v[206:209], v[58:61]
	v_mfma_f32_16x16x32_bf16 v[98:101], v[140:143], v[178:181], v[98:101]
	v_mfma_f32_16x16x32_bf16 v[34:37], v[154:157], v[178:181], v[34:37]
	v_mfma_f32_16x16x32_bf16 v[102:105], v[140:143], v[186:189], v[102:105]
	v_mfma_f32_16x16x32_bf16 v[42:45], v[154:157], v[186:189], v[42:45]
	v_mfma_f32_16x16x32_bf16 v[106:109], v[140:143], v[202:205], v[106:109]
	v_mfma_f32_16x16x32_bf16 v[50:53], v[154:157], v[202:205], v[50:53]
	v_mfma_f32_16x16x32_bf16 v[110:113], v[140:143], v[210:213], v[110:113]
	v_mfma_f32_16x16x32_bf16 v[58:61], v[154:157], v[210:213], v[58:61]
	s_setprio 0
	s_setprio 1
	v_mfma_f32_16x16x32_bf16 v[38:41], v[158:161], v[174:177], v[38:41]
	v_mfma_f32_16x16x32_bf16 v[2:5], v[166:169], v[174:177], v[2:5]
	v_mfma_f32_16x16x32_bf16 v[46:49], v[158:161], v[182:185], v[46:49]
	v_mfma_f32_16x16x32_bf16 v[6:9], v[166:169], v[182:185], v[6:9]
	v_mfma_f32_16x16x32_bf16 v[54:57], v[158:161], v[190:193], v[54:57]
	v_mfma_f32_16x16x32_bf16 v[10:13], v[166:169], v[190:193], v[10:13]
	v_mfma_f32_16x16x32_bf16 v[62:65], v[158:161], v[206:209], v[62:65]
	v_mfma_f32_16x16x32_bf16 v[14:17], v[166:169], v[206:209], v[14:17]
	v_mfma_f32_16x16x32_bf16 v[38:41], v[162:165], v[178:181], v[38:41]
	v_mfma_f32_16x16x32_bf16 v[2:5], v[170:173], v[178:181], v[2:5]
	v_mfma_f32_16x16x32_bf16 v[46:49], v[162:165], v[186:189], v[46:49]
	v_mfma_f32_16x16x32_bf16 v[6:9], v[170:173], v[186:189], v[6:9]
	v_mfma_f32_16x16x32_bf16 v[54:57], v[162:165], v[202:205], v[54:57]
	v_mfma_f32_16x16x32_bf16 v[10:13], v[170:173], v[202:205], v[10:13]
	v_mfma_f32_16x16x32_bf16 v[62:65], v[162:165], v[210:213], v[62:65]
	v_mfma_f32_16x16x32_bf16 v[14:17], v[170:173], v[210:213], v[14:17]
	s_setprio 0
	s_barrier
	s_add_i32 s38, s65, s31
	v_lshl_add_u64 v[144:145], v[144:145], 0, s[96:97]
	s_mov_b32 m0, s38
	ds_read_b128 v[174:177], v149 offset:49152
	ds_read_b128 v[178:181], v149 offset:50176
	ds_read_b128 v[182:185], v149 offset:51200
	ds_read_b128 v[186:189], v149 offset:52224
	ds_read_b128 v[190:193], v149 offset:53248
	ds_read_b128 v[202:205], v149 offset:54272
	ds_read_b128 v[206:209], v149 offset:55296
	ds_read_b128 v[210:213], v149 offset:56320
	global_load_lds_dwordx4 v[144:145], off
	s_add_i32 m0, s38, 0x2000
	s_add_u32 s38, s42, 0x160080
	v_lshl_add_u64 v[144:145], v[194:195], 0, s[96:97]
	s_addc_u32 s39, s43, 0
	s_add_i32 s42, s66, s31
	global_load_lds_dwordx4 v[144:145], off
	v_lshl_add_u64 v[144:145], s[38:39], 0, v[0:1]
	s_mov_b32 m0, s42
	s_nop 0
	global_load_lds_dwordx4 v[144:145], off
	v_lshl_add_u64 v[144:145], s[38:39], 0, v[130:131]
	s_add_i32 m0, s42, 0x2000
	s_nop 0
	global_load_lds_dwordx4 v[144:145], off
	s_waitcnt vmcnt(8)
	s_waitcnt lgkmcnt(0)
	s_setprio 1
	s_waitcnt lgkmcnt(0)
	v_mfma_f32_16x16x32_bf16 v[114:117], v[136:139], v[174:177], v[114:117]
	v_mfma_f32_16x16x32_bf16 v[66:69], v[150:153], v[174:177], v[66:69]
	v_mfma_f32_16x16x32_bf16 v[118:121], v[136:139], v[182:185], v[118:121]
	v_mfma_f32_16x16x32_bf16 v[74:77], v[150:153], v[182:185], v[74:77]
	s_barrier
	v_mfma_f32_16x16x32_bf16 v[122:125], v[136:139], v[190:193], v[122:125]
	v_mfma_f32_16x16x32_bf16 v[82:85], v[150:153], v[190:193], v[82:85]
	v_mfma_f32_16x16x32_bf16 v[126:129], v[136:139], v[206:209], v[126:129]
	v_mfma_f32_16x16x32_bf16 v[90:93], v[150:153], v[206:209], v[90:93]
	v_mfma_f32_16x16x32_bf16 v[114:117], v[140:143], v[178:181], v[114:117]
	v_mfma_f32_16x16x32_bf16 v[66:69], v[154:157], v[178:181], v[66:69]
	v_mfma_f32_16x16x32_bf16 v[118:121], v[140:143], v[186:189], v[118:121]
	v_mfma_f32_16x16x32_bf16 v[74:77], v[154:157], v[186:189], v[74:77]
	v_mfma_f32_16x16x32_bf16 v[122:125], v[140:143], v[202:205], v[122:125]
	v_mfma_f32_16x16x32_bf16 v[82:85], v[154:157], v[202:205], v[82:85]
	v_mfma_f32_16x16x32_bf16 v[126:129], v[140:143], v[210:213], v[126:129]
	v_mfma_f32_16x16x32_bf16 v[90:93], v[154:157], v[210:213], v[90:93]
	s_setprio 0
	s_setprio 1
	v_mfma_f32_16x16x32_bf16 v[70:73], v[158:161], v[174:177], v[70:73]
	v_mfma_f32_16x16x32_bf16 v[18:21], v[166:169], v[174:177], v[18:21]
	v_mfma_f32_16x16x32_bf16 v[78:81], v[158:161], v[182:185], v[78:81]
	v_mfma_f32_16x16x32_bf16 v[22:25], v[166:169], v[182:185], v[22:25]
	v_mfma_f32_16x16x32_bf16 v[86:89], v[158:161], v[190:193], v[86:89]
	v_mfma_f32_16x16x32_bf16 v[26:29], v[166:169], v[190:193], v[26:29]
	v_mfma_f32_16x16x32_bf16 v[94:97], v[158:161], v[206:209], v[94:97]
	v_mfma_f32_16x16x32_bf16 v[30:33], v[166:169], v[206:209], v[30:33]
	v_mfma_f32_16x16x32_bf16 v[70:73], v[162:165], v[178:181], v[70:73]
	v_mfma_f32_16x16x32_bf16 v[18:21], v[170:173], v[178:181], v[18:21]
	v_mfma_f32_16x16x32_bf16 v[78:81], v[162:165], v[186:189], v[78:81]
	v_mfma_f32_16x16x32_bf16 v[22:25], v[170:173], v[186:189], v[22:25]
	v_mfma_f32_16x16x32_bf16 v[86:89], v[162:165], v[202:205], v[86:89]
	v_mfma_f32_16x16x32_bf16 v[26:29], v[170:173], v[202:205], v[26:29]
	v_mfma_f32_16x16x32_bf16 v[94:97], v[162:165], v[210:213], v[94:97]
	v_mfma_f32_16x16x32_bf16 v[30:33], v[170:173], v[210:213], v[30:33]
	s_setprio 0
	s_barrier
	s_add_i32 s64, s64, 2
	s_mov_b32 s101, s100
	s_mov_b32 s100, vcc_hi
	s_add_u32 s62, s62, 0x100
	s_addc_u32 s63, s63, 0
	s_cmpk_gt_u32 s64, 0x55
	s_mov_b64 s[38:39], s[40:41]
	s_cbranch_scc0 .LBB0_1593
	s_and_b64 vcc, exec, s[24:25]
	s_cbranch_vccz .LBB0_1596
	s_barrier

; __global__ void __launch_bounds__(NTH, 2) mega(Params p_arg) {
;     extern __shared__ __attribute__((aligned(16))) char smem[];
;     cg::grid_group grid = cg::this_grid();
;     const int bid = blockIdx.x, G = gridDim.x;
;     volatile __attribute__((address_space(3))) unsigned* xst = (volatile __attribute__((address_space(3))) unsigned*)(smem + LDS_BYTES - 64);
	.amdhsa_kernel _Z4mega6Params
		.amdhsa_group_segment_fixed_size 16384
		.amdhsa_private_segment_fixed_size 0
		.amdhsa_kernarg_size 544
		.amdhsa_user_sgpr_count 2
		.amdhsa_user_sgpr_dispatch_ptr 0
		.amdhsa_user_sgpr_queue_ptr 0
		.amdhsa_user_sgpr_kernarg_segment_ptr 1
		.amdhsa_user_sgpr_dispatch_id 0
		.amdhsa_user_sgpr_kernarg_preload_length 0
		.amdhsa_user_sgpr_kernarg_preload_offset 0
		.amdhsa_user_sgpr_private_segment_size 0
		.amdhsa_uses_dynamic_stack 0
		.amdhsa_enable_private_segment 0
		.amdhsa_system_sgpr_workgroup_id_x 1
		.amdhsa_system_sgpr_workgroup_id_y 0
		.amdhsa_system_sgpr_workgroup_id_z 0
		.amdhsa_system_sgpr_workgroup_info 0
		.amdhsa_system_vgpr_workitem_id 2
		.amdhsa_next_free_vgpr 256
		.amdhsa_next_free_sgpr 102
		.amdhsa_accum_offset 256
		.amdhsa_reserve_vcc 1
		.amdhsa_float_round_mode_32 0
		.amdhsa_float_round_mode_16_64 0
		.amdhsa_float_denorm_mode_32 3
		.amdhsa_float_denorm_mode_16_64 3
		.amdhsa_dx10_clamp 1
		.amdhsa_ieee_mode 1
		.amdhsa_fp16_overflow 0
		.amdhsa_tg_split 0
		.amdhsa_exception_fp_ieee_invalid_op 0
		.amdhsa_exception_fp_denorm_src 0
		.amdhsa_exception_fp_ieee_div_zero 0
		.amdhsa_exception_fp_ieee_overflow 0
		.amdhsa_exception_fp_ieee_underflow 0
		.amdhsa_exception_fp_ieee_inexact 0
		.amdhsa_exception_int_div_zero 0
	.end_amdhsa_kernel

; __global__ void __launch_bounds__(NTH, 2) mega(Params p_arg) {
;     extern __shared__ __attribute__((aligned(16))) char smem[];
;     cg::grid_group grid = cg::this_grid();
;     const int bid = blockIdx.x, G = gridDim.x;
;     volatile __attribute__((address_space(3))) unsigned* xst = (volatile __attribute__((address_space(3))) unsigned*)(smem + LDS_BYTES - 64);
amdhsa.kernels:
  - .agpr_count:     0
    .args:
      - .offset:         0
        .size:           288
        .value_kind:     by_value
      - .offset:         288
        .size:           4
        .value_kind:     hidden_block_count_x
      - .offset:         292
        .size:           4
        .value_kind:     hidden_block_count_y
      - .offset:         296
        .size:           4
        .value_kind:     hidden_block_count_z
      - .offset:         300
        .size:           2
        .value_kind:     hidden_group_size_x
      - .offset:         302
        .size:           2
        .value_kind:     hidden_group_size_y
      - .offset:         304
        .size:           2
        .value_kind:     hidden_group_size_z
      - .offset:         306
        .size:           2
        .value_kind:     hidden_remainder_x
      - .offset:         308
        .size:           2
        .value_kind:     hidden_remainder_y
      - .offset:         310
        .size:           2
        .value_kind:     hidden_remainder_z
      - .offset:         328
        .size:           8
        .value_kind:     hidden_global_offset_x
      - .offset:         336
        .size:           8
        .value_kind:     hidden_global_offset_y
      - .offset:         344
        .size:           8
        .value_kind:     hidden_global_offset_z
      - .offset:         352
        .size:           2
        .value_kind:     hidden_grid_dims
      - .offset:         376
        .size:           8
        .value_kind:     hidden_multigrid_sync_arg
      - .offset:         408
        .size:           4
        .value_kind:     hidden_dynamic_lds_size
    .group_segment_fixed_size: 16384
    .kernarg_segment_align: 8
    .kernarg_segment_size: 544
    .language:       OpenCL C
    .language_version:
      - 2
      - 0
    .max_flat_workgroup_size: 512
    .name:           _Z4mega6Params
    .private_segment_fixed_size: 0
    .sgpr_count:     108
    .sgpr_spill_count: 244
    .symbol:         _Z4mega6Params.kd
    .uniform_work_group_size: 1
    .uses_dynamic_stack: false
    .vgpr_count:     256
    .vgpr_spill_count: 0
    .wavefront_size: 64
